# v47 + swapped s_setprio in K-loops: loading wave at prio 1, MFMA wave at prio 0
# speedup vs baseline: 1.0055x; 1.0051x over previous
.LBB0_261:
	s_add_u32 s0, s76, 0xfff80080
	s_addc_u32 s1, s77, -1
	s_and_b64 s[84:85], s[84:85], exec
	s_cselect_b32 vcc_hi, s22, s1
	s_cselect_b32 vcc_lo, s23, s0
	s_cselect_b32 s85, s49, s58
	s_cselect_b32 s84, s57, s51
	s_add_i32 s0, 0, 0x10000
	s_add_i32 s1, 0, 0x14000
	v_add_u32_e32 v158, s0, v176
	v_add_u32_e32 v174, s1, v176
	ds_read_b128 v[146:149], v158
	ds_read_b128 v[150:153], v158 offset:1024
	ds_read_b128 v[154:157], v158 offset:2048
	ds_read_b128 v[158:161], v158 offset:3072
	ds_read_b128 v[162:165], v174
	ds_read_b128 v[166:169], v174 offset:1024
	ds_read_b128 v[170:173], v174 offset:2048
	ds_read_b128 v[178:181], v174 offset:3072
	s_add_i32 m0, s21, 0xc000
	ds_read_b128 v[182:185], v177
	ds_read_b128 v[186:189], v177 offset:1024
	ds_read_b128 v[190:193], v177 offset:2048
	ds_read_b128 v[204:207], v177 offset:3072
	ds_read_b128 v[208:211], v177 offset:4096
	ds_read_b128 v[212:215], v177 offset:5120
	ds_read_b128 v[216:219], v177 offset:6144
	ds_read_b128 v[220:223], v177 offset:7168
	global_load_lds_dwordx4 v138, s[76:77]
	s_add_i32 m0, s21, 0xe000
	s_nop 0
	global_load_lds_dwordx4 v140, s[76:77]
	s_waitcnt vmcnt(8)
	s_waitcnt lgkmcnt(0)
	s_barrier
	s_setprio 0
	s_waitcnt lgkmcnt(0)
	v_mfma_f32_16x16x32_bf16 v[126:129], v[146:149], v[182:185], v[126:129]
	v_mfma_f32_16x16x32_bf16 v[126:129], v[150:153], v[186:189], v[126:129]
	v_mfma_f32_16x16x32_bf16 v[122:125], v[158:161], v[186:189], v[122:125]
	v_mfma_f32_16x16x32_bf16 v[122:125], v[154:157], v[182:185], v[122:125]
	v_mfma_f32_16x16x32_bf16 v[118:121], v[162:165], v[182:185], v[118:121]
	v_mfma_f32_16x16x32_bf16 v[118:121], v[166:169], v[186:189], v[118:121]
	v_mfma_f32_16x16x32_bf16 v[114:117], v[178:181], v[186:189], v[114:117]
	v_mfma_f32_16x16x32_bf16 v[114:117], v[170:173], v[182:185], v[114:117]
	v_mfma_f32_16x16x32_bf16 v[98:101], v[170:173], v[190:193], v[98:101]
	v_mfma_f32_16x16x32_bf16 v[98:101], v[178:181], v[204:207], v[98:101]
	v_mfma_f32_16x16x32_bf16 v[102:105], v[166:169], v[204:207], v[102:105]
	v_mfma_f32_16x16x32_bf16 v[102:105], v[162:165], v[190:193], v[102:105]
	v_mfma_f32_16x16x32_bf16 v[106:109], v[154:157], v[190:193], v[106:109]
	v_mfma_f32_16x16x32_bf16 v[106:109], v[158:161], v[204:207], v[106:109]
	v_mfma_f32_16x16x32_bf16 v[110:113], v[150:153], v[204:207], v[110:113]
	v_mfma_f32_16x16x32_bf16 v[110:113], v[146:149], v[190:193], v[110:113]
	v_mfma_f32_16x16x32_bf16 v[94:97], v[146:149], v[208:211], v[94:97]
	v_mfma_f32_16x16x32_bf16 v[94:97], v[150:153], v[212:215], v[94:97]
	v_mfma_f32_16x16x32_bf16 v[90:93], v[158:161], v[212:215], v[90:93]
	v_mfma_f32_16x16x32_bf16 v[90:93], v[154:157], v[208:211], v[90:93]
	v_mfma_f32_16x16x32_bf16 v[86:89], v[162:165], v[208:211], v[86:89]
	v_mfma_f32_16x16x32_bf16 v[86:89], v[166:169], v[212:215], v[86:89]
	v_mfma_f32_16x16x32_bf16 v[82:85], v[178:181], v[212:215], v[82:85]
	v_mfma_f32_16x16x32_bf16 v[82:85], v[170:173], v[208:211], v[82:85]
	v_mfma_f32_16x16x32_bf16 v[66:69], v[170:173], v[216:219], v[66:69]
	v_mfma_f32_16x16x32_bf16 v[66:69], v[178:181], v[220:223], v[66:69]
	v_mfma_f32_16x16x32_bf16 v[70:73], v[166:169], v[220:223], v[70:73]
	v_mfma_f32_16x16x32_bf16 v[70:73], v[162:165], v[216:219], v[70:73]
	v_mfma_f32_16x16x32_bf16 v[74:77], v[154:157], v[216:219], v[74:77]
	v_mfma_f32_16x16x32_bf16 v[74:77], v[158:161], v[220:223], v[74:77]
	v_mfma_f32_16x16x32_bf16 v[78:81], v[150:153], v[220:223], v[78:81]
	v_mfma_f32_16x16x32_bf16 v[78:81], v[146:149], v[216:219], v[78:81]
	s_setprio 1
	s_barrier
	s_add_i32 s0, s0, s20
	s_mov_b32 m0, s0
	ds_read_b128 v[182:185], v177 offset:16384
	ds_read_b128 v[186:189], v177 offset:17408
	ds_read_b128 v[190:193], v177 offset:18432
	ds_read_b128 v[204:207], v177 offset:19456
	ds_read_b128 v[208:211], v177 offset:20480
	ds_read_b128 v[212:215], v177 offset:21504
	ds_read_b128 v[216:219], v177 offset:22528
	ds_read_b128 v[220:223], v177 offset:23552
	global_load_lds_dwordx4 v132, s[84:85]
	s_add_i32 m0, s0, 0x2000
	s_add_u32 s94, s84, 0x80000
	s_addc_u32 s95, s85, 0
	s_add_i32 s0, s1, s20
	global_load_lds_dwordx4 v130, s[84:85]
	s_mov_b32 m0, s0
	s_nop 0
	global_load_lds_dwordx4 v132, s[94:95]
	s_add_i32 m0, s0, 0x2000
	s_nop 0
	global_load_lds_dwordx4 v130, s[94:95]
	s_mov_b32 m0, s21
	s_nop 0
	global_load_lds_dwordx4 v132, vcc
	s_mov_b32 m0, s26
	s_nop 0
	global_load_lds_dwordx4 v130, vcc
	s_waitcnt vmcnt(8)
	s_waitcnt lgkmcnt(0)
	s_barrier
	s_setprio 0
	s_waitcnt lgkmcnt(0)
	v_mfma_f32_16x16x32_bf16 v[62:65], v[146:149], v[182:185], v[62:65]
	v_mfma_f32_16x16x32_bf16 v[62:65], v[150:153], v[186:189], v[62:65]
	v_mfma_f32_16x16x32_bf16 v[58:61], v[158:161], v[186:189], v[58:61]
	v_mfma_f32_16x16x32_bf16 v[58:61], v[154:157], v[182:185], v[58:61]
	v_mfma_f32_16x16x32_bf16 v[54:57], v[162:165], v[182:185], v[54:57]
	v_mfma_f32_16x16x32_bf16 v[54:57], v[166:169], v[186:189], v[54:57]
	v_mfma_f32_16x16x32_bf16 v[50:53], v[178:181], v[186:189], v[50:53]
	v_mfma_f32_16x16x32_bf16 v[50:53], v[170:173], v[182:185], v[50:53]
	v_mfma_f32_16x16x32_bf16 v[34:37], v[170:173], v[190:193], v[34:37]
	v_mfma_f32_16x16x32_bf16 v[34:37], v[178:181], v[204:207], v[34:37]
	v_mfma_f32_16x16x32_bf16 v[38:41], v[166:169], v[204:207], v[38:41]
	v_mfma_f32_16x16x32_bf16 v[38:41], v[162:165], v[190:193], v[38:41]
	v_mfma_f32_16x16x32_bf16 v[42:45], v[154:157], v[190:193], v[42:45]
	v_mfma_f32_16x16x32_bf16 v[42:45], v[158:161], v[204:207], v[42:45]
	v_mfma_f32_16x16x32_bf16 v[46:49], v[150:153], v[204:207], v[46:49]
	v_mfma_f32_16x16x32_bf16 v[46:49], v[146:149], v[190:193], v[46:49]
	v_mfma_f32_16x16x32_bf16 v[30:33], v[146:149], v[208:211], v[30:33]
	v_mfma_f32_16x16x32_bf16 v[30:33], v[150:153], v[212:215], v[30:33]
	v_mfma_f32_16x16x32_bf16 v[26:29], v[158:161], v[212:215], v[26:29]
	v_mfma_f32_16x16x32_bf16 v[26:29], v[154:157], v[208:211], v[26:29]
	v_mfma_f32_16x16x32_bf16 v[22:25], v[162:165], v[208:211], v[22:25]
	v_mfma_f32_16x16x32_bf16 v[22:25], v[166:169], v[212:215], v[22:25]
	v_mfma_f32_16x16x32_bf16 v[18:21], v[178:181], v[212:215], v[18:21]
	v_mfma_f32_16x16x32_bf16 v[18:21], v[170:173], v[208:211], v[18:21]
	v_mfma_f32_16x16x32_bf16 v[2:5], v[170:173], v[216:219], v[2:5]
	v_mfma_f32_16x16x32_bf16 v[2:5], v[178:181], v[220:223], v[2:5]
	v_mfma_f32_16x16x32_bf16 v[6:9], v[166:169], v[220:223], v[6:9]
	v_mfma_f32_16x16x32_bf16 v[6:9], v[162:165], v[216:219], v[6:9]
	v_mfma_f32_16x16x32_bf16 v[10:13], v[154:157], v[216:219], v[10:13]
	v_mfma_f32_16x16x32_bf16 v[10:13], v[158:161], v[220:223], v[10:13]
	v_mfma_f32_16x16x32_bf16 v[14:17], v[150:153], v[220:223], v[14:17]
	v_mfma_f32_16x16x32_bf16 v[14:17], v[146:149], v[216:219], v[14:17]
	s_setprio 1
	s_barrier
	s_add_i32 s0, 0, 0x18000
	s_add_i32 s1, 0, 0x1c000
	v_add_u32_e32 v158, s0, v176
	v_add_u32_e32 v178, s1, v176
	ds_read_b128 v[146:149], v158
	ds_read_b128 v[150:153], v158 offset:1024
	ds_read_b128 v[154:157], v158 offset:2048
	ds_read_b128 v[158:161], v158 offset:3072
	ds_read_b128 v[162:165], v178
	ds_read_b128 v[166:169], v178 offset:1024
	ds_read_b128 v[170:173], v178 offset:2048
	ds_read_b128 v[178:181], v178 offset:3072
	s_add_u32 s94, vcc_lo, 0x80000
	s_addc_u32 s95, vcc_hi, 0
	s_mov_b32 m0, s27
	ds_read_b128 v[182:185], v177 offset:32768
	ds_read_b128 v[186:189], v177 offset:33792
	ds_read_b128 v[190:193], v177 offset:34816
	ds_read_b128 v[204:207], v177 offset:35840
	ds_read_b128 v[208:211], v177 offset:36864
	ds_read_b128 v[212:215], v177 offset:37888
	ds_read_b128 v[216:219], v177 offset:38912
	ds_read_b128 v[220:223], v177 offset:39936
	global_load_lds_dwordx4 v132, s[94:95]
	s_mov_b32 m0, s29
	s_nop 0
	global_load_lds_dwordx4 v130, s[94:95]
	s_waitcnt vmcnt(8)
	s_waitcnt lgkmcnt(0)
	s_barrier
	s_setprio 0
	s_waitcnt lgkmcnt(0)
	v_mfma_f32_16x16x32_bf16 v[126:129], v[146:149], v[182:185], v[126:129]
	v_mfma_f32_16x16x32_bf16 v[126:129], v[150:153], v[186:189], v[126:129]
	v_mfma_f32_16x16x32_bf16 v[122:125], v[158:161], v[186:189], v[122:125]
	v_mfma_f32_16x16x32_bf16 v[122:125], v[154:157], v[182:185], v[122:125]
	v_mfma_f32_16x16x32_bf16 v[118:121], v[162:165], v[182:185], v[118:121]
	v_mfma_f32_16x16x32_bf16 v[118:121], v[166:169], v[186:189], v[118:121]
	v_mfma_f32_16x16x32_bf16 v[114:117], v[178:181], v[186:189], v[114:117]
	v_mfma_f32_16x16x32_bf16 v[114:117], v[170:173], v[182:185], v[114:117]
	v_mfma_f32_16x16x32_bf16 v[98:101], v[170:173], v[190:193], v[98:101]
	v_mfma_f32_16x16x32_bf16 v[98:101], v[178:181], v[204:207], v[98:101]
	v_mfma_f32_16x16x32_bf16 v[102:105], v[166:169], v[204:207], v[102:105]
	v_mfma_f32_16x16x32_bf16 v[102:105], v[162:165], v[190:193], v[102:105]
	v_mfma_f32_16x16x32_bf16 v[106:109], v[154:157], v[190:193], v[106:109]
	v_mfma_f32_16x16x32_bf16 v[106:109], v[158:161], v[204:207], v[106:109]
	v_mfma_f32_16x16x32_bf16 v[110:113], v[150:153], v[204:207], v[110:113]
	v_mfma_f32_16x16x32_bf16 v[110:113], v[146:149], v[190:193], v[110:113]
	v_mfma_f32_16x16x32_bf16 v[94:97], v[146:149], v[208:211], v[94:97]
	v_mfma_f32_16x16x32_bf16 v[94:97], v[150:153], v[212:215], v[94:97]
	v_mfma_f32_16x16x32_bf16 v[90:93], v[158:161], v[212:215], v[90:93]
	v_mfma_f32_16x16x32_bf16 v[90:93], v[154:157], v[208:211], v[90:93]
	v_mfma_f32_16x16x32_bf16 v[86:89], v[162:165], v[208:211], v[86:89]
	v_mfma_f32_16x16x32_bf16 v[86:89], v[166:169], v[212:215], v[86:89]
	v_mfma_f32_16x16x32_bf16 v[82:85], v[178:181], v[212:215], v[82:85]
	v_mfma_f32_16x16x32_bf16 v[82:85], v[170:173], v[208:211], v[82:85]
	v_mfma_f32_16x16x32_bf16 v[66:69], v[170:173], v[216:219], v[66:69]
	v_mfma_f32_16x16x32_bf16 v[66:69], v[178:181], v[220:223], v[66:69]
	v_mfma_f32_16x16x32_bf16 v[70:73], v[166:169], v[220:223], v[70:73]
	v_mfma_f32_16x16x32_bf16 v[70:73], v[162:165], v[216:219], v[70:73]
	v_mfma_f32_16x16x32_bf16 v[74:77], v[154:157], v[216:219], v[74:77]
	v_mfma_f32_16x16x32_bf16 v[74:77], v[158:161], v[220:223], v[74:77]
	v_mfma_f32_16x16x32_bf16 v[78:81], v[150:153], v[220:223], v[78:81]
	v_mfma_f32_16x16x32_bf16 v[78:81], v[146:149], v[216:219], v[78:81]
	s_setprio 1
	s_barrier
	s_add_u32 s98, s84, 0x80
	s_addc_u32 s99, s85, 0
	s_add_u32 s100, vcc_lo, 0x80
	s_addc_u32 s101, vcc_hi, 0
	s_add_i32 s0, s0, s20
	s_mov_b32 m0, s0
	ds_read_b128 v[182:185], v177 offset:49152
	ds_read_b128 v[186:189], v177 offset:50176
	ds_read_b128 v[190:193], v177 offset:51200
	ds_read_b128 v[204:207], v177 offset:52224
	ds_read_b128 v[208:211], v177 offset:53248
	ds_read_b128 v[212:215], v177 offset:54272
	ds_read_b128 v[216:219], v177 offset:55296
	ds_read_b128 v[220:223], v177 offset:56320
	global_load_lds_dwordx4 v132, s[98:99]
	s_add_i32 m0, s0, 0x2000
	s_add_u32 s84, s84, 0x80080
	s_addc_u32 s85, s85, 0
	s_add_i32 s0, s1, s20
	global_load_lds_dwordx4 v130, s[98:99]
	s_mov_b32 m0, s0
	s_nop 0
	global_load_lds_dwordx4 v132, s[84:85]
	s_add_i32 m0, s0, 0x2000
	s_nop 0
	global_load_lds_dwordx4 v130, s[84:85]
	s_mov_b32 m0, s40
	s_nop 0
	global_load_lds_dwordx4 v132, s[100:101]
	s_mov_b32 m0, s41
	s_nop 0
	global_load_lds_dwordx4 v130, s[100:101]
	s_waitcnt vmcnt(8)
	s_waitcnt lgkmcnt(0)
	s_barrier
	s_setprio 0
	s_waitcnt lgkmcnt(0)
	v_mfma_f32_16x16x32_bf16 v[62:65], v[146:149], v[182:185], v[62:65]
	v_mfma_f32_16x16x32_bf16 v[62:65], v[150:153], v[186:189], v[62:65]
	v_mfma_f32_16x16x32_bf16 v[58:61], v[158:161], v[186:189], v[58:61]
	v_mfma_f32_16x16x32_bf16 v[58:61], v[154:157], v[182:185], v[58:61]
	v_mfma_f32_16x16x32_bf16 v[54:57], v[162:165], v[182:185], v[54:57]
	v_mfma_f32_16x16x32_bf16 v[54:57], v[166:169], v[186:189], v[54:57]
	v_mfma_f32_16x16x32_bf16 v[50:53], v[178:181], v[186:189], v[50:53]
	v_mfma_f32_16x16x32_bf16 v[50:53], v[170:173], v[182:185], v[50:53]
	v_mfma_f32_16x16x32_bf16 v[34:37], v[170:173], v[190:193], v[34:37]
	v_mfma_f32_16x16x32_bf16 v[34:37], v[178:181], v[204:207], v[34:37]
	v_mfma_f32_16x16x32_bf16 v[38:41], v[166:169], v[204:207], v[38:41]
	v_mfma_f32_16x16x32_bf16 v[38:41], v[162:165], v[190:193], v[38:41]
	v_mfma_f32_16x16x32_bf16 v[42:45], v[154:157], v[190:193], v[42:45]
	v_mfma_f32_16x16x32_bf16 v[42:45], v[158:161], v[204:207], v[42:45]
	v_mfma_f32_16x16x32_bf16 v[46:49], v[150:153], v[204:207], v[46:49]
	v_mfma_f32_16x16x32_bf16 v[46:49], v[146:149], v[190:193], v[46:49]
	v_mfma_f32_16x16x32_bf16 v[30:33], v[146:149], v[208:211], v[30:33]
	v_mfma_f32_16x16x32_bf16 v[30:33], v[150:153], v[212:215], v[30:33]
	v_mfma_f32_16x16x32_bf16 v[26:29], v[158:161], v[212:215], v[26:29]
	v_mfma_f32_16x16x32_bf16 v[26:29], v[154:157], v[208:211], v[26:29]
	v_mfma_f32_16x16x32_bf16 v[22:25], v[162:165], v[208:211], v[22:25]
	v_mfma_f32_16x16x32_bf16 v[22:25], v[166:169], v[212:215], v[22:25]
	v_mfma_f32_16x16x32_bf16 v[18:21], v[178:181], v[212:215], v[18:21]
	v_mfma_f32_16x16x32_bf16 v[18:21], v[170:173], v[208:211], v[18:21]
	v_mfma_f32_16x16x32_bf16 v[2:5], v[170:173], v[216:219], v[2:5]
	v_mfma_f32_16x16x32_bf16 v[2:5], v[178:181], v[220:223], v[2:5]
	v_mfma_f32_16x16x32_bf16 v[6:9], v[166:169], v[220:223], v[6:9]
	v_mfma_f32_16x16x32_bf16 v[6:9], v[162:165], v[216:219], v[6:9]
	v_mfma_f32_16x16x32_bf16 v[10:13], v[154:157], v[216:219], v[10:13]
	v_mfma_f32_16x16x32_bf16 v[10:13], v[158:161], v[220:223], v[10:13]
	v_mfma_f32_16x16x32_bf16 v[14:17], v[150:153], v[220:223], v[14:17]
	v_mfma_f32_16x16x32_bf16 v[14:17], v[146:149], v[216:219], v[14:17]
	s_setprio 1
	s_barrier
	s_add_i32 s65, s65, 2
	s_add_u32 s76, s76, 0x100
	s_addc_u32 s77, s77, 0
	s_add_u32 s51, s51, 0x100
	s_addc_u32 s58, s58, 0
	s_cmp_gt_u32 s65, 29
	s_cbranch_scc1 .LBB0_264

.Lpeel_disp_ine:
	s_cmp_lg_u32 s65, -2
	s_cbranch_scc1 .LBB0_261
	s_add_u32 s0, s76, 0xfff80080
	s_addc_u32 s1, s77, -1
	s_and_b64 s[84:85], s[84:85], exec
	s_cselect_b32 vcc_hi, s22, s1
	s_cselect_b32 vcc_lo, s23, s0
	s_cselect_b32 s85, s49, s58
	s_cselect_b32 s84, s57, s51
	s_add_i32 s0, 0, 0x10000
	s_add_i32 s1, 0, 0x14000
	v_add_u32_e32 v158, s0, v176
	v_add_u32_e32 v174, s1, v176
	ds_read_b128 v[146:149], v158
	ds_read_b128 v[150:153], v158 offset:1024
	ds_read_b128 v[154:157], v158 offset:2048
	ds_read_b128 v[158:161], v158 offset:3072
	ds_read_b128 v[162:165], v174
	ds_read_b128 v[166:169], v174 offset:1024
	ds_read_b128 v[170:173], v174 offset:2048
	ds_read_b128 v[178:181], v174 offset:3072
	s_add_i32 m0, s21, 0xc000
	ds_read_b128 v[182:185], v177
	ds_read_b128 v[186:189], v177 offset:1024
	ds_read_b128 v[190:193], v177 offset:2048
	ds_read_b128 v[204:207], v177 offset:3072
	ds_read_b128 v[208:211], v177 offset:4096
	ds_read_b128 v[212:215], v177 offset:5120
	ds_read_b128 v[216:219], v177 offset:6144
	ds_read_b128 v[220:223], v177 offset:7168
	global_load_lds_dwordx4 v138, s[76:77]
	s_add_i32 m0, s21, 0xe000
	s_nop 0
	global_load_lds_dwordx4 v140, s[76:77]
	s_waitcnt vmcnt(8)
	s_waitcnt lgkmcnt(0)
	s_barrier
	s_setprio 0
	s_waitcnt lgkmcnt(0)
	v_mfma_f32_16x16x32_bf16 v[126:129], v[146:149], v[182:185], 0
	v_mfma_f32_16x16x32_bf16 v[126:129], v[150:153], v[186:189], v[126:129]
	v_mfma_f32_16x16x32_bf16 v[122:125], v[158:161], v[186:189], 0
	v_mfma_f32_16x16x32_bf16 v[122:125], v[154:157], v[182:185], v[122:125]
	v_mfma_f32_16x16x32_bf16 v[118:121], v[162:165], v[182:185], 0
	v_mfma_f32_16x16x32_bf16 v[118:121], v[166:169], v[186:189], v[118:121]
	v_mfma_f32_16x16x32_bf16 v[114:117], v[178:181], v[186:189], 0
	v_mfma_f32_16x16x32_bf16 v[114:117], v[170:173], v[182:185], v[114:117]
	v_mfma_f32_16x16x32_bf16 v[98:101], v[170:173], v[190:193], 0
	v_mfma_f32_16x16x32_bf16 v[98:101], v[178:181], v[204:207], v[98:101]
	v_mfma_f32_16x16x32_bf16 v[102:105], v[166:169], v[204:207], 0
	v_mfma_f32_16x16x32_bf16 v[102:105], v[162:165], v[190:193], v[102:105]
	v_mfma_f32_16x16x32_bf16 v[106:109], v[154:157], v[190:193], 0
	v_mfma_f32_16x16x32_bf16 v[106:109], v[158:161], v[204:207], v[106:109]
	v_mfma_f32_16x16x32_bf16 v[110:113], v[150:153], v[204:207], 0
	v_mfma_f32_16x16x32_bf16 v[110:113], v[146:149], v[190:193], v[110:113]
	v_mfma_f32_16x16x32_bf16 v[94:97], v[146:149], v[208:211], 0
	v_mfma_f32_16x16x32_bf16 v[94:97], v[150:153], v[212:215], v[94:97]
	v_mfma_f32_16x16x32_bf16 v[90:93], v[158:161], v[212:215], 0
	v_mfma_f32_16x16x32_bf16 v[90:93], v[154:157], v[208:211], v[90:93]
	v_mfma_f32_16x16x32_bf16 v[86:89], v[162:165], v[208:211], 0
	v_mfma_f32_16x16x32_bf16 v[86:89], v[166:169], v[212:215], v[86:89]
	v_mfma_f32_16x16x32_bf16 v[82:85], v[178:181], v[212:215], 0
	v_mfma_f32_16x16x32_bf16 v[82:85], v[170:173], v[208:211], v[82:85]
	v_mfma_f32_16x16x32_bf16 v[66:69], v[170:173], v[216:219], 0
	v_mfma_f32_16x16x32_bf16 v[66:69], v[178:181], v[220:223], v[66:69]
	v_mfma_f32_16x16x32_bf16 v[70:73], v[166:169], v[220:223], 0
	v_mfma_f32_16x16x32_bf16 v[70:73], v[162:165], v[216:219], v[70:73]
	v_mfma_f32_16x16x32_bf16 v[74:77], v[154:157], v[216:219], 0
	v_mfma_f32_16x16x32_bf16 v[74:77], v[158:161], v[220:223], v[74:77]
	v_mfma_f32_16x16x32_bf16 v[78:81], v[150:153], v[220:223], 0
	v_mfma_f32_16x16x32_bf16 v[78:81], v[146:149], v[216:219], v[78:81]
	s_setprio 1
	s_barrier
	s_add_i32 s0, s0, s20
	s_mov_b32 m0, s0
	ds_read_b128 v[182:185], v177 offset:16384
	ds_read_b128 v[186:189], v177 offset:17408
	ds_read_b128 v[190:193], v177 offset:18432
	ds_read_b128 v[204:207], v177 offset:19456
	ds_read_b128 v[208:211], v177 offset:20480
	ds_read_b128 v[212:215], v177 offset:21504
	ds_read_b128 v[216:219], v177 offset:22528
	ds_read_b128 v[220:223], v177 offset:23552
	global_load_lds_dwordx4 v132, s[84:85]
	s_add_i32 m0, s0, 0x2000
	s_add_u32 s94, s84, 0x80000
	s_addc_u32 s95, s85, 0
	s_add_i32 s0, s1, s20
	global_load_lds_dwordx4 v130, s[84:85]
	s_mov_b32 m0, s0
	s_nop 0
	global_load_lds_dwordx4 v132, s[94:95]
	s_add_i32 m0, s0, 0x2000
	s_nop 0
	global_load_lds_dwordx4 v130, s[94:95]
	s_mov_b32 m0, s21
	s_nop 0
	global_load_lds_dwordx4 v132, vcc
	s_mov_b32 m0, s26
	s_nop 0
	global_load_lds_dwordx4 v130, vcc
	s_waitcnt vmcnt(8)
	s_waitcnt lgkmcnt(0)
	s_barrier
	s_setprio 0
	s_waitcnt lgkmcnt(0)
	v_mfma_f32_16x16x32_bf16 v[62:65], v[146:149], v[182:185], 0
	v_mfma_f32_16x16x32_bf16 v[62:65], v[150:153], v[186:189], v[62:65]
	v_mfma_f32_16x16x32_bf16 v[58:61], v[158:161], v[186:189], 0
	v_mfma_f32_16x16x32_bf16 v[58:61], v[154:157], v[182:185], v[58:61]
	v_mfma_f32_16x16x32_bf16 v[54:57], v[162:165], v[182:185], 0
	v_mfma_f32_16x16x32_bf16 v[54:57], v[166:169], v[186:189], v[54:57]
	v_mfma_f32_16x16x32_bf16 v[50:53], v[178:181], v[186:189], 0
	v_mfma_f32_16x16x32_bf16 v[50:53], v[170:173], v[182:185], v[50:53]
	v_mfma_f32_16x16x32_bf16 v[34:37], v[170:173], v[190:193], 0
	v_mfma_f32_16x16x32_bf16 v[34:37], v[178:181], v[204:207], v[34:37]
	v_mfma_f32_16x16x32_bf16 v[38:41], v[166:169], v[204:207], 0
	v_mfma_f32_16x16x32_bf16 v[38:41], v[162:165], v[190:193], v[38:41]
	v_mfma_f32_16x16x32_bf16 v[42:45], v[154:157], v[190:193], 0
	v_mfma_f32_16x16x32_bf16 v[42:45], v[158:161], v[204:207], v[42:45]
	v_mfma_f32_16x16x32_bf16 v[46:49], v[150:153], v[204:207], 0
	v_mfma_f32_16x16x32_bf16 v[46:49], v[146:149], v[190:193], v[46:49]
	v_mfma_f32_16x16x32_bf16 v[30:33], v[146:149], v[208:211], 0
	v_mfma_f32_16x16x32_bf16 v[30:33], v[150:153], v[212:215], v[30:33]
	v_mfma_f32_16x16x32_bf16 v[26:29], v[158:161], v[212:215], 0
	v_mfma_f32_16x16x32_bf16 v[26:29], v[154:157], v[208:211], v[26:29]
	v_mfma_f32_16x16x32_bf16 v[22:25], v[162:165], v[208:211], 0
	v_mfma_f32_16x16x32_bf16 v[22:25], v[166:169], v[212:215], v[22:25]
	v_mfma_f32_16x16x32_bf16 v[18:21], v[178:181], v[212:215], 0
	v_mfma_f32_16x16x32_bf16 v[18:21], v[170:173], v[208:211], v[18:21]
	v_mfma_f32_16x16x32_bf16 v[2:5], v[170:173], v[216:219], 0
	v_mfma_f32_16x16x32_bf16 v[2:5], v[178:181], v[220:223], v[2:5]
	v_mfma_f32_16x16x32_bf16 v[6:9], v[166:169], v[220:223], 0
	v_mfma_f32_16x16x32_bf16 v[6:9], v[162:165], v[216:219], v[6:9]
	v_mfma_f32_16x16x32_bf16 v[10:13], v[154:157], v[216:219], 0
	v_mfma_f32_16x16x32_bf16 v[10:13], v[158:161], v[220:223], v[10:13]
	v_mfma_f32_16x16x32_bf16 v[14:17], v[150:153], v[220:223], 0
	v_mfma_f32_16x16x32_bf16 v[14:17], v[146:149], v[216:219], v[14:17]
	s_setprio 1
	s_barrier
	s_add_i32 s0, 0, 0x18000
	s_add_i32 s1, 0, 0x1c000
	v_add_u32_e32 v158, s0, v176
	v_add_u32_e32 v178, s1, v176
	ds_read_b128 v[146:149], v158
	ds_read_b128 v[150:153], v158 offset:1024
	ds_read_b128 v[154:157], v158 offset:2048
	ds_read_b128 v[158:161], v158 offset:3072
	ds_read_b128 v[162:165], v178
	ds_read_b128 v[166:169], v178 offset:1024
	ds_read_b128 v[170:173], v178 offset:2048
	ds_read_b128 v[178:181], v178 offset:3072
	s_add_u32 s94, vcc_lo, 0x80000
	s_addc_u32 s95, vcc_hi, 0
	s_mov_b32 m0, s27
	ds_read_b128 v[182:185], v177 offset:32768
	ds_read_b128 v[186:189], v177 offset:33792
	ds_read_b128 v[190:193], v177 offset:34816
	ds_read_b128 v[204:207], v177 offset:35840
	ds_read_b128 v[208:211], v177 offset:36864
	ds_read_b128 v[212:215], v177 offset:37888
	ds_read_b128 v[216:219], v177 offset:38912
	ds_read_b128 v[220:223], v177 offset:39936
	global_load_lds_dwordx4 v132, s[94:95]
	s_mov_b32 m0, s29
	s_nop 0
	global_load_lds_dwordx4 v130, s[94:95]
	s_waitcnt vmcnt(8)
	s_waitcnt lgkmcnt(0)
	s_barrier
	s_setprio 0
	s_waitcnt lgkmcnt(0)
	v_mfma_f32_16x16x32_bf16 v[126:129], v[146:149], v[182:185], v[126:129]
	v_mfma_f32_16x16x32_bf16 v[126:129], v[150:153], v[186:189], v[126:129]
	v_mfma_f32_16x16x32_bf16 v[122:125], v[158:161], v[186:189], v[122:125]
	v_mfma_f32_16x16x32_bf16 v[122:125], v[154:157], v[182:185], v[122:125]
	v_mfma_f32_16x16x32_bf16 v[118:121], v[162:165], v[182:185], v[118:121]
	v_mfma_f32_16x16x32_bf16 v[118:121], v[166:169], v[186:189], v[118:121]
	v_mfma_f32_16x16x32_bf16 v[114:117], v[178:181], v[186:189], v[114:117]
	v_mfma_f32_16x16x32_bf16 v[114:117], v[170:173], v[182:185], v[114:117]
	v_mfma_f32_16x16x32_bf16 v[98:101], v[170:173], v[190:193], v[98:101]
	v_mfma_f32_16x16x32_bf16 v[98:101], v[178:181], v[204:207], v[98:101]
	v_mfma_f32_16x16x32_bf16 v[102:105], v[166:169], v[204:207], v[102:105]
	v_mfma_f32_16x16x32_bf16 v[102:105], v[162:165], v[190:193], v[102:105]
	v_mfma_f32_16x16x32_bf16 v[106:109], v[154:157], v[190:193], v[106:109]
	v_mfma_f32_16x16x32_bf16 v[106:109], v[158:161], v[204:207], v[106:109]
	v_mfma_f32_16x16x32_bf16 v[110:113], v[150:153], v[204:207], v[110:113]
	v_mfma_f32_16x16x32_bf16 v[110:113], v[146:149], v[190:193], v[110:113]
	v_mfma_f32_16x16x32_bf16 v[94:97], v[146:149], v[208:211], v[94:97]
	v_mfma_f32_16x16x32_bf16 v[94:97], v[150:153], v[212:215], v[94:97]
	v_mfma_f32_16x16x32_bf16 v[90:93], v[158:161], v[212:215], v[90:93]
	v_mfma_f32_16x16x32_bf16 v[90:93], v[154:157], v[208:211], v[90:93]
	v_mfma_f32_16x16x32_bf16 v[86:89], v[162:165], v[208:211], v[86:89]
	v_mfma_f32_16x16x32_bf16 v[86:89], v[166:169], v[212:215], v[86:89]
	v_mfma_f32_16x16x32_bf16 v[82:85], v[178:181], v[212:215], v[82:85]
	v_mfma_f32_16x16x32_bf16 v[82:85], v[170:173], v[208:211], v[82:85]
	v_mfma_f32_16x16x32_bf16 v[66:69], v[170:173], v[216:219], v[66:69]
	v_mfma_f32_16x16x32_bf16 v[66:69], v[178:181], v[220:223], v[66:69]
	v_mfma_f32_16x16x32_bf16 v[70:73], v[166:169], v[220:223], v[70:73]
	v_mfma_f32_16x16x32_bf16 v[70:73], v[162:165], v[216:219], v[70:73]
	v_mfma_f32_16x16x32_bf16 v[74:77], v[154:157], v[216:219], v[74:77]
	v_mfma_f32_16x16x32_bf16 v[74:77], v[158:161], v[220:223], v[74:77]
	v_mfma_f32_16x16x32_bf16 v[78:81], v[150:153], v[220:223], v[78:81]
	v_mfma_f32_16x16x32_bf16 v[78:81], v[146:149], v[216:219], v[78:81]
	s_setprio 1
	s_barrier
	s_add_u32 s98, s84, 0x80
	s_addc_u32 s99, s85, 0
	s_add_u32 s100, vcc_lo, 0x80
	s_addc_u32 s101, vcc_hi, 0
	s_add_i32 s0, s0, s20
	s_mov_b32 m0, s0
	ds_read_b128 v[182:185], v177 offset:49152
	ds_read_b128 v[186:189], v177 offset:50176
	ds_read_b128 v[190:193], v177 offset:51200
	ds_read_b128 v[204:207], v177 offset:52224
	ds_read_b128 v[208:211], v177 offset:53248
	ds_read_b128 v[212:215], v177 offset:54272
	ds_read_b128 v[216:219], v177 offset:55296
	ds_read_b128 v[220:223], v177 offset:56320
	global_load_lds_dwordx4 v132, s[98:99]
	s_add_i32 m0, s0, 0x2000
	s_add_u32 s84, s84, 0x80080
	s_addc_u32 s85, s85, 0
	s_add_i32 s0, s1, s20
	global_load_lds_dwordx4 v130, s[98:99]
	s_mov_b32 m0, s0
	s_nop 0
	global_load_lds_dwordx4 v132, s[84:85]
	s_add_i32 m0, s0, 0x2000
	s_nop 0
	global_load_lds_dwordx4 v130, s[84:85]
	s_mov_b32 m0, s40
	s_nop 0
	global_load_lds_dwordx4 v132, s[100:101]
	s_mov_b32 m0, s41
	s_nop 0
	global_load_lds_dwordx4 v130, s[100:101]
	s_waitcnt vmcnt(8)
	s_waitcnt lgkmcnt(0)
	s_barrier
	s_setprio 0
	s_waitcnt lgkmcnt(0)
	v_mfma_f32_16x16x32_bf16 v[62:65], v[146:149], v[182:185], v[62:65]
	v_mfma_f32_16x16x32_bf16 v[62:65], v[150:153], v[186:189], v[62:65]
	v_mfma_f32_16x16x32_bf16 v[58:61], v[158:161], v[186:189], v[58:61]
	v_mfma_f32_16x16x32_bf16 v[58:61], v[154:157], v[182:185], v[58:61]
	v_mfma_f32_16x16x32_bf16 v[54:57], v[162:165], v[182:185], v[54:57]
	v_mfma_f32_16x16x32_bf16 v[54:57], v[166:169], v[186:189], v[54:57]
	v_mfma_f32_16x16x32_bf16 v[50:53], v[178:181], v[186:189], v[50:53]
	v_mfma_f32_16x16x32_bf16 v[50:53], v[170:173], v[182:185], v[50:53]
	v_mfma_f32_16x16x32_bf16 v[34:37], v[170:173], v[190:193], v[34:37]
	v_mfma_f32_16x16x32_bf16 v[34:37], v[178:181], v[204:207], v[34:37]
	v_mfma_f32_16x16x32_bf16 v[38:41], v[166:169], v[204:207], v[38:41]
	v_mfma_f32_16x16x32_bf16 v[38:41], v[162:165], v[190:193], v[38:41]
	v_mfma_f32_16x16x32_bf16 v[42:45], v[154:157], v[190:193], v[42:45]
	v_mfma_f32_16x16x32_bf16 v[42:45], v[158:161], v[204:207], v[42:45]
	v_mfma_f32_16x16x32_bf16 v[46:49], v[150:153], v[204:207], v[46:49]
	v_mfma_f32_16x16x32_bf16 v[46:49], v[146:149], v[190:193], v[46:49]
	v_mfma_f32_16x16x32_bf16 v[30:33], v[146:149], v[208:211], v[30:33]
	v_mfma_f32_16x16x32_bf16 v[30:33], v[150:153], v[212:215], v[30:33]
	v_mfma_f32_16x16x32_bf16 v[26:29], v[158:161], v[212:215], v[26:29]
	v_mfma_f32_16x16x32_bf16 v[26:29], v[154:157], v[208:211], v[26:29]
	v_mfma_f32_16x16x32_bf16 v[22:25], v[162:165], v[208:211], v[22:25]
	v_mfma_f32_16x16x32_bf16 v[22:25], v[166:169], v[212:215], v[22:25]
	v_mfma_f32_16x16x32_bf16 v[18:21], v[178:181], v[212:215], v[18:21]
	v_mfma_f32_16x16x32_bf16 v[18:21], v[170:173], v[208:211], v[18:21]
	v_mfma_f32_16x16x32_bf16 v[2:5], v[170:173], v[216:219], v[2:5]
	v_mfma_f32_16x16x32_bf16 v[2:5], v[178:181], v[220:223], v[2:5]
	v_mfma_f32_16x16x32_bf16 v[6:9], v[166:169], v[220:223], v[6:9]
	v_mfma_f32_16x16x32_bf16 v[6:9], v[162:165], v[216:219], v[6:9]
	v_mfma_f32_16x16x32_bf16 v[10:13], v[154:157], v[216:219], v[10:13]
	v_mfma_f32_16x16x32_bf16 v[10:13], v[158:161], v[220:223], v[10:13]
	v_mfma_f32_16x16x32_bf16 v[14:17], v[150:153], v[220:223], v[14:17]
	v_mfma_f32_16x16x32_bf16 v[14:17], v[146:149], v[216:219], v[14:17]
	s_setprio 1
	s_barrier
	s_add_i32 s65, s65, 2
	s_add_u32 s76, s76, 0x100
	s_addc_u32 s77, s77, 0
	s_add_u32 s51, s51, 0x100
	s_addc_u32 s58, s58, 0
	s_cmp_gt_u32 s65, 29
	s_cbranch_scc1 .LBB0_264
	s_branch .LBB0_262

.LBB0_285:
	s_add_u32 s0, s76, 0xfff80080
	s_addc_u32 s1, s77, -1
	s_and_b64 s[70:71], s[70:71], exec
	s_cselect_b32 vcc_hi, s21, s1
	s_cselect_b32 vcc_lo, s22, s0
	s_cselect_b32 s71, s23, s41
	s_cselect_b32 s70, s39, s7
	s_add_i32 s0, 0, 0x10000
	s_add_i32 s1, 0, 0x14000
	v_add_u32_e32 v146, s0, v1
	v_add_u32_e32 v174, s1, v1
	ds_read_b128 v[134:137], v146
	ds_read_b128 v[138:141], v146 offset:1024
	ds_read_b128 v[142:145], v146 offset:2048
	ds_read_b128 v[146:149], v146 offset:3072
	ds_read_b128 v[150:153], v174
	ds_read_b128 v[154:157], v174 offset:1024
	ds_read_b128 v[158:161], v174 offset:2048
	ds_read_b128 v[174:177], v174 offset:3072
	s_add_i32 m0, s67, 0xc000
	ds_read_b128 v[178:181], v222
	ds_read_b128 v[182:185], v222 offset:1024
	ds_read_b128 v[186:189], v222 offset:2048
	ds_read_b128 v[190:193], v222 offset:3072
	ds_read_b128 v[204:207], v222 offset:4096
	ds_read_b128 v[208:211], v222 offset:5120
	ds_read_b128 v[212:215], v222 offset:6144
	ds_read_b128 v[216:219], v222 offset:7168
	global_load_lds_dwordx4 v170, s[76:77]
	s_add_i32 m0, s67, 0xe000
	s_nop 0
	global_load_lds_dwordx4 v172, s[76:77]
	s_waitcnt vmcnt(8)
	s_waitcnt lgkmcnt(0)
	s_barrier
	s_setprio 0
	s_waitcnt lgkmcnt(0)
	v_mfma_f32_16x16x32_bf16 v[126:129], v[134:137], v[178:181], v[126:129]
	v_mfma_f32_16x16x32_bf16 v[126:129], v[138:141], v[182:185], v[126:129]
	v_mfma_f32_16x16x32_bf16 v[122:125], v[146:149], v[182:185], v[122:125]
	v_mfma_f32_16x16x32_bf16 v[122:125], v[142:145], v[178:181], v[122:125]
	v_mfma_f32_16x16x32_bf16 v[118:121], v[150:153], v[178:181], v[118:121]
	v_mfma_f32_16x16x32_bf16 v[118:121], v[154:157], v[182:185], v[118:121]
	v_mfma_f32_16x16x32_bf16 v[114:117], v[174:177], v[182:185], v[114:117]
	v_mfma_f32_16x16x32_bf16 v[114:117], v[158:161], v[178:181], v[114:117]
	v_mfma_f32_16x16x32_bf16 v[98:101], v[158:161], v[186:189], v[98:101]
	v_mfma_f32_16x16x32_bf16 v[98:101], v[174:177], v[190:193], v[98:101]
	v_mfma_f32_16x16x32_bf16 v[102:105], v[154:157], v[190:193], v[102:105]
	v_mfma_f32_16x16x32_bf16 v[102:105], v[150:153], v[186:189], v[102:105]
	v_mfma_f32_16x16x32_bf16 v[106:109], v[142:145], v[186:189], v[106:109]
	v_mfma_f32_16x16x32_bf16 v[106:109], v[146:149], v[190:193], v[106:109]
	v_mfma_f32_16x16x32_bf16 v[110:113], v[138:141], v[190:193], v[110:113]
	v_mfma_f32_16x16x32_bf16 v[110:113], v[134:137], v[186:189], v[110:113]
	v_mfma_f32_16x16x32_bf16 v[94:97], v[134:137], v[204:207], v[94:97]
	v_mfma_f32_16x16x32_bf16 v[94:97], v[138:141], v[208:211], v[94:97]
	v_mfma_f32_16x16x32_bf16 v[90:93], v[146:149], v[208:211], v[90:93]
	v_mfma_f32_16x16x32_bf16 v[90:93], v[142:145], v[204:207], v[90:93]
	v_mfma_f32_16x16x32_bf16 v[86:89], v[150:153], v[204:207], v[86:89]
	v_mfma_f32_16x16x32_bf16 v[86:89], v[154:157], v[208:211], v[86:89]
	v_mfma_f32_16x16x32_bf16 v[82:85], v[174:177], v[208:211], v[82:85]
	v_mfma_f32_16x16x32_bf16 v[82:85], v[158:161], v[204:207], v[82:85]
	v_mfma_f32_16x16x32_bf16 v[66:69], v[158:161], v[212:215], v[66:69]
	v_mfma_f32_16x16x32_bf16 v[66:69], v[174:177], v[216:219], v[66:69]
	v_mfma_f32_16x16x32_bf16 v[70:73], v[154:157], v[216:219], v[70:73]
	v_mfma_f32_16x16x32_bf16 v[70:73], v[150:153], v[212:215], v[70:73]
	v_mfma_f32_16x16x32_bf16 v[74:77], v[142:145], v[212:215], v[74:77]
	v_mfma_f32_16x16x32_bf16 v[74:77], v[146:149], v[216:219], v[74:77]
	v_mfma_f32_16x16x32_bf16 v[78:81], v[138:141], v[216:219], v[78:81]
	v_mfma_f32_16x16x32_bf16 v[78:81], v[134:137], v[212:215], v[78:81]
	s_setprio 1
	s_barrier
	s_add_i32 s0, s0, s54
	s_mov_b32 m0, s0
	ds_read_b128 v[178:181], v222 offset:16384
	ds_read_b128 v[182:185], v222 offset:17408
	ds_read_b128 v[186:189], v222 offset:18432
	ds_read_b128 v[190:193], v222 offset:19456
	ds_read_b128 v[204:207], v222 offset:20480
	ds_read_b128 v[208:211], v222 offset:21504
	ds_read_b128 v[212:215], v222 offset:22528
	ds_read_b128 v[216:219], v222 offset:23552
	global_load_lds_dwordx4 v164, s[70:71]
	s_add_i32 m0, s0, 0x2000
	s_add_u32 s44, s70, 0x80000
	s_addc_u32 s45, s71, 0
	s_add_i32 s0, s1, s54
	global_load_lds_dwordx4 v162, s[70:71]
	s_mov_b32 m0, s0
	s_nop 0
	global_load_lds_dwordx4 v164, s[44:45]
	s_add_i32 m0, s0, 0x2000
	s_nop 0
	global_load_lds_dwordx4 v162, s[44:45]
	s_mov_b32 m0, s67
	s_nop 0
	global_load_lds_dwordx4 v164, vcc
	s_mov_b32 m0, s68
	s_nop 0
	global_load_lds_dwordx4 v162, vcc
	s_waitcnt vmcnt(8)
	s_waitcnt lgkmcnt(0)
	s_barrier
	s_setprio 0
	s_waitcnt lgkmcnt(0)
	v_mfma_f32_16x16x32_bf16 v[62:65], v[134:137], v[178:181], v[62:65]
	v_mfma_f32_16x16x32_bf16 v[62:65], v[138:141], v[182:185], v[62:65]
	v_mfma_f32_16x16x32_bf16 v[58:61], v[146:149], v[182:185], v[58:61]
	v_mfma_f32_16x16x32_bf16 v[58:61], v[142:145], v[178:181], v[58:61]
	v_mfma_f32_16x16x32_bf16 v[54:57], v[150:153], v[178:181], v[54:57]
	v_mfma_f32_16x16x32_bf16 v[54:57], v[154:157], v[182:185], v[54:57]
	v_mfma_f32_16x16x32_bf16 v[50:53], v[174:177], v[182:185], v[50:53]
	v_mfma_f32_16x16x32_bf16 v[50:53], v[158:161], v[178:181], v[50:53]
	v_mfma_f32_16x16x32_bf16 v[34:37], v[158:161], v[186:189], v[34:37]
	v_mfma_f32_16x16x32_bf16 v[34:37], v[174:177], v[190:193], v[34:37]
	v_mfma_f32_16x16x32_bf16 v[38:41], v[154:157], v[190:193], v[38:41]
	v_mfma_f32_16x16x32_bf16 v[38:41], v[150:153], v[186:189], v[38:41]
	v_mfma_f32_16x16x32_bf16 v[42:45], v[142:145], v[186:189], v[42:45]
	v_mfma_f32_16x16x32_bf16 v[42:45], v[146:149], v[190:193], v[42:45]
	v_mfma_f32_16x16x32_bf16 v[46:49], v[138:141], v[190:193], v[46:49]
	v_mfma_f32_16x16x32_bf16 v[46:49], v[134:137], v[186:189], v[46:49]
	v_mfma_f32_16x16x32_bf16 v[30:33], v[134:137], v[204:207], v[30:33]
	v_mfma_f32_16x16x32_bf16 v[30:33], v[138:141], v[208:211], v[30:33]
	v_mfma_f32_16x16x32_bf16 v[26:29], v[146:149], v[208:211], v[26:29]
	v_mfma_f32_16x16x32_bf16 v[26:29], v[142:145], v[204:207], v[26:29]
	v_mfma_f32_16x16x32_bf16 v[22:25], v[150:153], v[204:207], v[22:25]
	v_mfma_f32_16x16x32_bf16 v[22:25], v[154:157], v[208:211], v[22:25]
	v_mfma_f32_16x16x32_bf16 v[18:21], v[174:177], v[208:211], v[18:21]
	v_mfma_f32_16x16x32_bf16 v[18:21], v[158:161], v[204:207], v[18:21]
	v_mfma_f32_16x16x32_bf16 v[2:5], v[158:161], v[212:215], v[2:5]
	v_mfma_f32_16x16x32_bf16 v[2:5], v[174:177], v[216:219], v[2:5]
	v_mfma_f32_16x16x32_bf16 v[6:9], v[154:157], v[216:219], v[6:9]
	v_mfma_f32_16x16x32_bf16 v[6:9], v[150:153], v[212:215], v[6:9]
	v_mfma_f32_16x16x32_bf16 v[10:13], v[142:145], v[212:215], v[10:13]
	v_mfma_f32_16x16x32_bf16 v[10:13], v[146:149], v[216:219], v[10:13]
	v_mfma_f32_16x16x32_bf16 v[14:17], v[138:141], v[216:219], v[14:17]
	v_mfma_f32_16x16x32_bf16 v[14:17], v[134:137], v[212:215], v[14:17]
	s_setprio 1
	s_barrier
	s_add_i32 s0, 0, 0x18000
	s_add_i32 s1, 0, 0x1c000
	v_add_u32_e32 v146, s0, v1
	v_add_u32_e32 v174, s1, v1
	ds_read_b128 v[134:137], v146
	ds_read_b128 v[138:141], v146 offset:1024
	ds_read_b128 v[142:145], v146 offset:2048
	ds_read_b128 v[146:149], v146 offset:3072
	ds_read_b128 v[150:153], v174
	ds_read_b128 v[154:157], v174 offset:1024
	ds_read_b128 v[158:161], v174 offset:2048
	ds_read_b128 v[174:177], v174 offset:3072
	s_add_u32 s44, vcc_lo, 0x80000
	s_addc_u32 s45, vcc_hi, 0
	s_mov_b32 m0, s8
	ds_read_b128 v[178:181], v222 offset:32768
	ds_read_b128 v[182:185], v222 offset:33792
	ds_read_b128 v[186:189], v222 offset:34816
	ds_read_b128 v[190:193], v222 offset:35840
	ds_read_b128 v[204:207], v222 offset:36864
	ds_read_b128 v[208:211], v222 offset:37888
	ds_read_b128 v[212:215], v222 offset:38912
	ds_read_b128 v[216:219], v222 offset:39936
	global_load_lds_dwordx4 v164, s[44:45]
	s_mov_b32 m0, s9
	s_nop 0
	global_load_lds_dwordx4 v162, s[44:45]
	s_waitcnt vmcnt(8)
	s_waitcnt lgkmcnt(0)
	s_barrier
	s_setprio 0
	s_waitcnt lgkmcnt(0)
	v_mfma_f32_16x16x32_bf16 v[126:129], v[134:137], v[178:181], v[126:129]
	v_mfma_f32_16x16x32_bf16 v[126:129], v[138:141], v[182:185], v[126:129]
	v_mfma_f32_16x16x32_bf16 v[122:125], v[146:149], v[182:185], v[122:125]
	v_mfma_f32_16x16x32_bf16 v[122:125], v[142:145], v[178:181], v[122:125]
	v_mfma_f32_16x16x32_bf16 v[118:121], v[150:153], v[178:181], v[118:121]
	v_mfma_f32_16x16x32_bf16 v[118:121], v[154:157], v[182:185], v[118:121]
	v_mfma_f32_16x16x32_bf16 v[114:117], v[174:177], v[182:185], v[114:117]
	v_mfma_f32_16x16x32_bf16 v[114:117], v[158:161], v[178:181], v[114:117]
	v_mfma_f32_16x16x32_bf16 v[98:101], v[158:161], v[186:189], v[98:101]
	v_mfma_f32_16x16x32_bf16 v[98:101], v[174:177], v[190:193], v[98:101]
	v_mfma_f32_16x16x32_bf16 v[102:105], v[154:157], v[190:193], v[102:105]
	v_mfma_f32_16x16x32_bf16 v[102:105], v[150:153], v[186:189], v[102:105]
	v_mfma_f32_16x16x32_bf16 v[106:109], v[142:145], v[186:189], v[106:109]
	v_mfma_f32_16x16x32_bf16 v[106:109], v[146:149], v[190:193], v[106:109]
	v_mfma_f32_16x16x32_bf16 v[110:113], v[138:141], v[190:193], v[110:113]
	v_mfma_f32_16x16x32_bf16 v[110:113], v[134:137], v[186:189], v[110:113]
	v_mfma_f32_16x16x32_bf16 v[94:97], v[134:137], v[204:207], v[94:97]
	v_mfma_f32_16x16x32_bf16 v[94:97], v[138:141], v[208:211], v[94:97]
	v_mfma_f32_16x16x32_bf16 v[90:93], v[146:149], v[208:211], v[90:93]
	v_mfma_f32_16x16x32_bf16 v[90:93], v[142:145], v[204:207], v[90:93]
	v_mfma_f32_16x16x32_bf16 v[86:89], v[150:153], v[204:207], v[86:89]
	v_mfma_f32_16x16x32_bf16 v[86:89], v[154:157], v[208:211], v[86:89]
	v_mfma_f32_16x16x32_bf16 v[82:85], v[174:177], v[208:211], v[82:85]
	v_mfma_f32_16x16x32_bf16 v[82:85], v[158:161], v[204:207], v[82:85]
	v_mfma_f32_16x16x32_bf16 v[66:69], v[158:161], v[212:215], v[66:69]
	v_mfma_f32_16x16x32_bf16 v[66:69], v[174:177], v[216:219], v[66:69]
	v_mfma_f32_16x16x32_bf16 v[70:73], v[154:157], v[216:219], v[70:73]
	v_mfma_f32_16x16x32_bf16 v[70:73], v[150:153], v[212:215], v[70:73]
	v_mfma_f32_16x16x32_bf16 v[74:77], v[142:145], v[212:215], v[74:77]
	v_mfma_f32_16x16x32_bf16 v[74:77], v[146:149], v[216:219], v[74:77]
	v_mfma_f32_16x16x32_bf16 v[78:81], v[138:141], v[216:219], v[78:81]
	v_mfma_f32_16x16x32_bf16 v[78:81], v[134:137], v[212:215], v[78:81]
	s_setprio 1
	s_barrier
	s_add_u32 s98, s70, 0x80
	s_addc_u32 s99, s71, 0
	s_add_u32 s100, vcc_lo, 0x80
	s_addc_u32 s101, vcc_hi, 0
	s_add_i32 s0, s0, s54
	s_mov_b32 m0, s0
	ds_read_b128 v[178:181], v222 offset:49152
	ds_read_b128 v[182:185], v222 offset:50176
	ds_read_b128 v[186:189], v222 offset:51200
	ds_read_b128 v[190:193], v222 offset:52224
	ds_read_b128 v[204:207], v222 offset:53248
	ds_read_b128 v[208:211], v222 offset:54272
	ds_read_b128 v[212:215], v222 offset:55296
	ds_read_b128 v[216:219], v222 offset:56320
	global_load_lds_dwordx4 v164, s[98:99]
	s_add_i32 m0, s0, 0x2000
	s_add_u32 s44, s70, 0x80080
	s_addc_u32 s45, s71, 0
	s_add_i32 s0, s1, s54
	global_load_lds_dwordx4 v162, s[98:99]
	s_mov_b32 m0, s0
	s_nop 0
	global_load_lds_dwordx4 v164, s[44:45]
	s_add_i32 m0, s0, 0x2000
	s_nop 0
	global_load_lds_dwordx4 v162, s[44:45]
	s_mov_b32 m0, s27
	s_nop 0
	global_load_lds_dwordx4 v164, s[100:101]
	s_mov_b32 m0, s26
	s_nop 0
	global_load_lds_dwordx4 v162, s[100:101]
	s_waitcnt vmcnt(8)
	s_waitcnt lgkmcnt(0)
	s_barrier
	s_setprio 0
	s_waitcnt lgkmcnt(0)
	v_mfma_f32_16x16x32_bf16 v[62:65], v[134:137], v[178:181], v[62:65]
	v_mfma_f32_16x16x32_bf16 v[62:65], v[138:141], v[182:185], v[62:65]
	v_mfma_f32_16x16x32_bf16 v[58:61], v[146:149], v[182:185], v[58:61]
	v_mfma_f32_16x16x32_bf16 v[58:61], v[142:145], v[178:181], v[58:61]
	v_mfma_f32_16x16x32_bf16 v[54:57], v[150:153], v[178:181], v[54:57]
	v_mfma_f32_16x16x32_bf16 v[54:57], v[154:157], v[182:185], v[54:57]
	v_mfma_f32_16x16x32_bf16 v[50:53], v[174:177], v[182:185], v[50:53]
	v_mfma_f32_16x16x32_bf16 v[50:53], v[158:161], v[178:181], v[50:53]
	v_mfma_f32_16x16x32_bf16 v[34:37], v[158:161], v[186:189], v[34:37]
	v_mfma_f32_16x16x32_bf16 v[34:37], v[174:177], v[190:193], v[34:37]
	v_mfma_f32_16x16x32_bf16 v[38:41], v[154:157], v[190:193], v[38:41]
	v_mfma_f32_16x16x32_bf16 v[38:41], v[150:153], v[186:189], v[38:41]
	v_mfma_f32_16x16x32_bf16 v[42:45], v[142:145], v[186:189], v[42:45]
	v_mfma_f32_16x16x32_bf16 v[42:45], v[146:149], v[190:193], v[42:45]
	v_mfma_f32_16x16x32_bf16 v[46:49], v[138:141], v[190:193], v[46:49]
	v_mfma_f32_16x16x32_bf16 v[46:49], v[134:137], v[186:189], v[46:49]
	v_mfma_f32_16x16x32_bf16 v[30:33], v[134:137], v[204:207], v[30:33]
	v_mfma_f32_16x16x32_bf16 v[30:33], v[138:141], v[208:211], v[30:33]
	v_mfma_f32_16x16x32_bf16 v[26:29], v[146:149], v[208:211], v[26:29]
	v_mfma_f32_16x16x32_bf16 v[26:29], v[142:145], v[204:207], v[26:29]
	v_mfma_f32_16x16x32_bf16 v[22:25], v[150:153], v[204:207], v[22:25]
	v_mfma_f32_16x16x32_bf16 v[22:25], v[154:157], v[208:211], v[22:25]
	v_mfma_f32_16x16x32_bf16 v[18:21], v[174:177], v[208:211], v[18:21]
	v_mfma_f32_16x16x32_bf16 v[18:21], v[158:161], v[204:207], v[18:21]
	v_mfma_f32_16x16x32_bf16 v[2:5], v[158:161], v[212:215], v[2:5]
	v_mfma_f32_16x16x32_bf16 v[2:5], v[174:177], v[216:219], v[2:5]
	v_mfma_f32_16x16x32_bf16 v[6:9], v[154:157], v[216:219], v[6:9]
	v_mfma_f32_16x16x32_bf16 v[6:9], v[150:153], v[212:215], v[6:9]
	v_mfma_f32_16x16x32_bf16 v[10:13], v[142:145], v[212:215], v[10:13]
	v_mfma_f32_16x16x32_bf16 v[10:13], v[146:149], v[216:219], v[10:13]
	v_mfma_f32_16x16x32_bf16 v[14:17], v[138:141], v[216:219], v[14:17]
	v_mfma_f32_16x16x32_bf16 v[14:17], v[134:137], v[212:215], v[14:17]
	s_setprio 1
	s_barrier
	s_add_i32 s43, s43, 2
	s_add_u32 s76, s76, 0x100
	s_addc_u32 s77, s77, 0
	s_add_u32 s7, s7, 0x100
	s_addc_u32 s41, s41, 0
	s_cmp_gt_u32 s43, 29
	s_cbranch_scc1 .LBB0_288

.Lpeel_disp_ino:
	s_cmp_lg_u32 s43, -2
	s_cbranch_scc1 .LBB0_285
	s_add_u32 s0, s76, 0xfff80080
	s_addc_u32 s1, s77, -1
	s_and_b64 s[70:71], s[70:71], exec
	s_cselect_b32 vcc_hi, s21, s1
	s_cselect_b32 vcc_lo, s22, s0
	s_cselect_b32 s71, s23, s41
	s_cselect_b32 s70, s39, s7
	s_add_i32 s0, 0, 0x10000
	s_add_i32 s1, 0, 0x14000
	v_add_u32_e32 v146, s0, v1
	v_add_u32_e32 v174, s1, v1
	ds_read_b128 v[134:137], v146
	ds_read_b128 v[138:141], v146 offset:1024
	ds_read_b128 v[142:145], v146 offset:2048
	ds_read_b128 v[146:149], v146 offset:3072
	ds_read_b128 v[150:153], v174
	ds_read_b128 v[154:157], v174 offset:1024
	ds_read_b128 v[158:161], v174 offset:2048
	ds_read_b128 v[174:177], v174 offset:3072
	s_add_i32 m0, s67, 0xc000
	ds_read_b128 v[178:181], v222
	ds_read_b128 v[182:185], v222 offset:1024
	ds_read_b128 v[186:189], v222 offset:2048
	ds_read_b128 v[190:193], v222 offset:3072
	ds_read_b128 v[204:207], v222 offset:4096
	ds_read_b128 v[208:211], v222 offset:5120
	ds_read_b128 v[212:215], v222 offset:6144
	ds_read_b128 v[216:219], v222 offset:7168
	global_load_lds_dwordx4 v170, s[76:77]
	s_add_i32 m0, s67, 0xe000
	s_nop 0
	global_load_lds_dwordx4 v172, s[76:77]
	s_waitcnt vmcnt(8)
	s_waitcnt lgkmcnt(0)
	s_barrier
	s_setprio 0
	s_waitcnt lgkmcnt(0)
	v_mfma_f32_16x16x32_bf16 v[126:129], v[134:137], v[178:181], 0
	v_mfma_f32_16x16x32_bf16 v[126:129], v[138:141], v[182:185], v[126:129]
	v_mfma_f32_16x16x32_bf16 v[122:125], v[146:149], v[182:185], 0
	v_mfma_f32_16x16x32_bf16 v[122:125], v[142:145], v[178:181], v[122:125]
	v_mfma_f32_16x16x32_bf16 v[118:121], v[150:153], v[178:181], 0
	v_mfma_f32_16x16x32_bf16 v[118:121], v[154:157], v[182:185], v[118:121]
	v_mfma_f32_16x16x32_bf16 v[114:117], v[174:177], v[182:185], 0
	v_mfma_f32_16x16x32_bf16 v[114:117], v[158:161], v[178:181], v[114:117]
	v_mfma_f32_16x16x32_bf16 v[98:101], v[158:161], v[186:189], 0
	v_mfma_f32_16x16x32_bf16 v[98:101], v[174:177], v[190:193], v[98:101]
	v_mfma_f32_16x16x32_bf16 v[102:105], v[154:157], v[190:193], 0
	v_mfma_f32_16x16x32_bf16 v[102:105], v[150:153], v[186:189], v[102:105]
	v_mfma_f32_16x16x32_bf16 v[106:109], v[142:145], v[186:189], 0
	v_mfma_f32_16x16x32_bf16 v[106:109], v[146:149], v[190:193], v[106:109]
	v_mfma_f32_16x16x32_bf16 v[110:113], v[138:141], v[190:193], 0
	v_mfma_f32_16x16x32_bf16 v[110:113], v[134:137], v[186:189], v[110:113]
	v_mfma_f32_16x16x32_bf16 v[94:97], v[134:137], v[204:207], 0
	v_mfma_f32_16x16x32_bf16 v[94:97], v[138:141], v[208:211], v[94:97]
	v_mfma_f32_16x16x32_bf16 v[90:93], v[146:149], v[208:211], 0
	v_mfma_f32_16x16x32_bf16 v[90:93], v[142:145], v[204:207], v[90:93]
	v_mfma_f32_16x16x32_bf16 v[86:89], v[150:153], v[204:207], 0
	v_mfma_f32_16x16x32_bf16 v[86:89], v[154:157], v[208:211], v[86:89]
	v_mfma_f32_16x16x32_bf16 v[82:85], v[174:177], v[208:211], 0
	v_mfma_f32_16x16x32_bf16 v[82:85], v[158:161], v[204:207], v[82:85]
	v_mfma_f32_16x16x32_bf16 v[66:69], v[158:161], v[212:215], 0
	v_mfma_f32_16x16x32_bf16 v[66:69], v[174:177], v[216:219], v[66:69]
	v_mfma_f32_16x16x32_bf16 v[70:73], v[154:157], v[216:219], 0
	v_mfma_f32_16x16x32_bf16 v[70:73], v[150:153], v[212:215], v[70:73]
	v_mfma_f32_16x16x32_bf16 v[74:77], v[142:145], v[212:215], 0
	v_mfma_f32_16x16x32_bf16 v[74:77], v[146:149], v[216:219], v[74:77]
	v_mfma_f32_16x16x32_bf16 v[78:81], v[138:141], v[216:219], 0
	v_mfma_f32_16x16x32_bf16 v[78:81], v[134:137], v[212:215], v[78:81]
	s_setprio 1
	s_barrier
	s_add_i32 s0, s0, s54
	s_mov_b32 m0, s0
	ds_read_b128 v[178:181], v222 offset:16384
	ds_read_b128 v[182:185], v222 offset:17408
	ds_read_b128 v[186:189], v222 offset:18432
	ds_read_b128 v[190:193], v222 offset:19456
	ds_read_b128 v[204:207], v222 offset:20480
	ds_read_b128 v[208:211], v222 offset:21504
	ds_read_b128 v[212:215], v222 offset:22528
	ds_read_b128 v[216:219], v222 offset:23552
	global_load_lds_dwordx4 v164, s[70:71]
	s_add_i32 m0, s0, 0x2000
	s_add_u32 s44, s70, 0x80000
	s_addc_u32 s45, s71, 0
	s_add_i32 s0, s1, s54
	global_load_lds_dwordx4 v162, s[70:71]
	s_mov_b32 m0, s0
	s_nop 0
	global_load_lds_dwordx4 v164, s[44:45]
	s_add_i32 m0, s0, 0x2000
	s_nop 0
	global_load_lds_dwordx4 v162, s[44:45]
	s_mov_b32 m0, s67
	s_nop 0
	global_load_lds_dwordx4 v164, vcc
	s_mov_b32 m0, s68
	s_nop 0
	global_load_lds_dwordx4 v162, vcc
	s_waitcnt vmcnt(8)
	s_waitcnt lgkmcnt(0)
	s_barrier
	s_setprio 0
	s_waitcnt lgkmcnt(0)
	v_mfma_f32_16x16x32_bf16 v[62:65], v[134:137], v[178:181], 0
	v_mfma_f32_16x16x32_bf16 v[62:65], v[138:141], v[182:185], v[62:65]
	v_mfma_f32_16x16x32_bf16 v[58:61], v[146:149], v[182:185], 0
	v_mfma_f32_16x16x32_bf16 v[58:61], v[142:145], v[178:181], v[58:61]
	v_mfma_f32_16x16x32_bf16 v[54:57], v[150:153], v[178:181], 0
	v_mfma_f32_16x16x32_bf16 v[54:57], v[154:157], v[182:185], v[54:57]
	v_mfma_f32_16x16x32_bf16 v[50:53], v[174:177], v[182:185], 0
	v_mfma_f32_16x16x32_bf16 v[50:53], v[158:161], v[178:181], v[50:53]
	v_mfma_f32_16x16x32_bf16 v[34:37], v[158:161], v[186:189], 0
	v_mfma_f32_16x16x32_bf16 v[34:37], v[174:177], v[190:193], v[34:37]
	v_mfma_f32_16x16x32_bf16 v[38:41], v[154:157], v[190:193], 0
	v_mfma_f32_16x16x32_bf16 v[38:41], v[150:153], v[186:189], v[38:41]
	v_mfma_f32_16x16x32_bf16 v[42:45], v[142:145], v[186:189], 0
	v_mfma_f32_16x16x32_bf16 v[42:45], v[146:149], v[190:193], v[42:45]
	v_mfma_f32_16x16x32_bf16 v[46:49], v[138:141], v[190:193], 0
	v_mfma_f32_16x16x32_bf16 v[46:49], v[134:137], v[186:189], v[46:49]
	v_mfma_f32_16x16x32_bf16 v[30:33], v[134:137], v[204:207], 0
	v_mfma_f32_16x16x32_bf16 v[30:33], v[138:141], v[208:211], v[30:33]
	v_mfma_f32_16x16x32_bf16 v[26:29], v[146:149], v[208:211], 0
	v_mfma_f32_16x16x32_bf16 v[26:29], v[142:145], v[204:207], v[26:29]
	v_mfma_f32_16x16x32_bf16 v[22:25], v[150:153], v[204:207], 0
	v_mfma_f32_16x16x32_bf16 v[22:25], v[154:157], v[208:211], v[22:25]
	v_mfma_f32_16x16x32_bf16 v[18:21], v[174:177], v[208:211], 0
	v_mfma_f32_16x16x32_bf16 v[18:21], v[158:161], v[204:207], v[18:21]
	v_mfma_f32_16x16x32_bf16 v[2:5], v[158:161], v[212:215], 0
	v_mfma_f32_16x16x32_bf16 v[2:5], v[174:177], v[216:219], v[2:5]
	v_mfma_f32_16x16x32_bf16 v[6:9], v[154:157], v[216:219], 0
	v_mfma_f32_16x16x32_bf16 v[6:9], v[150:153], v[212:215], v[6:9]
	v_mfma_f32_16x16x32_bf16 v[10:13], v[142:145], v[212:215], 0
	v_mfma_f32_16x16x32_bf16 v[10:13], v[146:149], v[216:219], v[10:13]
	v_mfma_f32_16x16x32_bf16 v[14:17], v[138:141], v[216:219], 0
	v_mfma_f32_16x16x32_bf16 v[14:17], v[134:137], v[212:215], v[14:17]
	s_setprio 1
	s_barrier
	s_add_i32 s0, 0, 0x18000
	s_add_i32 s1, 0, 0x1c000
	v_add_u32_e32 v146, s0, v1
	v_add_u32_e32 v174, s1, v1
	ds_read_b128 v[134:137], v146
	ds_read_b128 v[138:141], v146 offset:1024
	ds_read_b128 v[142:145], v146 offset:2048
	ds_read_b128 v[146:149], v146 offset:3072
	ds_read_b128 v[150:153], v174
	ds_read_b128 v[154:157], v174 offset:1024
	ds_read_b128 v[158:161], v174 offset:2048
	ds_read_b128 v[174:177], v174 offset:3072
	s_add_u32 s44, vcc_lo, 0x80000
	s_addc_u32 s45, vcc_hi, 0
	s_mov_b32 m0, s8
	ds_read_b128 v[178:181], v222 offset:32768
	ds_read_b128 v[182:185], v222 offset:33792
	ds_read_b128 v[186:189], v222 offset:34816
	ds_read_b128 v[190:193], v222 offset:35840
	ds_read_b128 v[204:207], v222 offset:36864
	ds_read_b128 v[208:211], v222 offset:37888
	ds_read_b128 v[212:215], v222 offset:38912
	ds_read_b128 v[216:219], v222 offset:39936
	global_load_lds_dwordx4 v164, s[44:45]
	s_mov_b32 m0, s9
	s_nop 0
	global_load_lds_dwordx4 v162, s[44:45]
	s_waitcnt vmcnt(8)
	s_waitcnt lgkmcnt(0)
	s_barrier
	s_setprio 0
	s_waitcnt lgkmcnt(0)
	v_mfma_f32_16x16x32_bf16 v[126:129], v[134:137], v[178:181], v[126:129]
	v_mfma_f32_16x16x32_bf16 v[126:129], v[138:141], v[182:185], v[126:129]
	v_mfma_f32_16x16x32_bf16 v[122:125], v[146:149], v[182:185], v[122:125]
	v_mfma_f32_16x16x32_bf16 v[122:125], v[142:145], v[178:181], v[122:125]
	v_mfma_f32_16x16x32_bf16 v[118:121], v[150:153], v[178:181], v[118:121]
	v_mfma_f32_16x16x32_bf16 v[118:121], v[154:157], v[182:185], v[118:121]
	v_mfma_f32_16x16x32_bf16 v[114:117], v[174:177], v[182:185], v[114:117]
	v_mfma_f32_16x16x32_bf16 v[114:117], v[158:161], v[178:181], v[114:117]
	v_mfma_f32_16x16x32_bf16 v[98:101], v[158:161], v[186:189], v[98:101]
	v_mfma_f32_16x16x32_bf16 v[98:101], v[174:177], v[190:193], v[98:101]
	v_mfma_f32_16x16x32_bf16 v[102:105], v[154:157], v[190:193], v[102:105]
	v_mfma_f32_16x16x32_bf16 v[102:105], v[150:153], v[186:189], v[102:105]
	v_mfma_f32_16x16x32_bf16 v[106:109], v[142:145], v[186:189], v[106:109]
	v_mfma_f32_16x16x32_bf16 v[106:109], v[146:149], v[190:193], v[106:109]
	v_mfma_f32_16x16x32_bf16 v[110:113], v[138:141], v[190:193], v[110:113]
	v_mfma_f32_16x16x32_bf16 v[110:113], v[134:137], v[186:189], v[110:113]
	v_mfma_f32_16x16x32_bf16 v[94:97], v[134:137], v[204:207], v[94:97]
	v_mfma_f32_16x16x32_bf16 v[94:97], v[138:141], v[208:211], v[94:97]
	v_mfma_f32_16x16x32_bf16 v[90:93], v[146:149], v[208:211], v[90:93]
	v_mfma_f32_16x16x32_bf16 v[90:93], v[142:145], v[204:207], v[90:93]
	v_mfma_f32_16x16x32_bf16 v[86:89], v[150:153], v[204:207], v[86:89]
	v_mfma_f32_16x16x32_bf16 v[86:89], v[154:157], v[208:211], v[86:89]
	v_mfma_f32_16x16x32_bf16 v[82:85], v[174:177], v[208:211], v[82:85]
	v_mfma_f32_16x16x32_bf16 v[82:85], v[158:161], v[204:207], v[82:85]
	v_mfma_f32_16x16x32_bf16 v[66:69], v[158:161], v[212:215], v[66:69]
	v_mfma_f32_16x16x32_bf16 v[66:69], v[174:177], v[216:219], v[66:69]
	v_mfma_f32_16x16x32_bf16 v[70:73], v[154:157], v[216:219], v[70:73]
	v_mfma_f32_16x16x32_bf16 v[70:73], v[150:153], v[212:215], v[70:73]
	v_mfma_f32_16x16x32_bf16 v[74:77], v[142:145], v[212:215], v[74:77]
	v_mfma_f32_16x16x32_bf16 v[74:77], v[146:149], v[216:219], v[74:77]
	v_mfma_f32_16x16x32_bf16 v[78:81], v[138:141], v[216:219], v[78:81]
	v_mfma_f32_16x16x32_bf16 v[78:81], v[134:137], v[212:215], v[78:81]
	s_setprio 1
	s_barrier
	s_add_u32 s98, s70, 0x80
	s_addc_u32 s99, s71, 0
	s_add_u32 s100, vcc_lo, 0x80
	s_addc_u32 s101, vcc_hi, 0
	s_add_i32 s0, s0, s54
	s_mov_b32 m0, s0
	ds_read_b128 v[178:181], v222 offset:49152
	ds_read_b128 v[182:185], v222 offset:50176
	ds_read_b128 v[186:189], v222 offset:51200
	ds_read_b128 v[190:193], v222 offset:52224
	ds_read_b128 v[204:207], v222 offset:53248
	ds_read_b128 v[208:211], v222 offset:54272
	ds_read_b128 v[212:215], v222 offset:55296
	ds_read_b128 v[216:219], v222 offset:56320
	global_load_lds_dwordx4 v164, s[98:99]
	s_add_i32 m0, s0, 0x2000
	s_add_u32 s44, s70, 0x80080
	s_addc_u32 s45, s71, 0
	s_add_i32 s0, s1, s54
	global_load_lds_dwordx4 v162, s[98:99]
	s_mov_b32 m0, s0
	s_nop 0
	global_load_lds_dwordx4 v164, s[44:45]
	s_add_i32 m0, s0, 0x2000
	s_nop 0
	global_load_lds_dwordx4 v162, s[44:45]
	s_mov_b32 m0, s27
	s_nop 0
	global_load_lds_dwordx4 v164, s[100:101]
	s_mov_b32 m0, s26
	s_nop 0
	global_load_lds_dwordx4 v162, s[100:101]
	s_waitcnt vmcnt(8)
	s_waitcnt lgkmcnt(0)
	s_barrier
	s_setprio 0
	s_waitcnt lgkmcnt(0)
	v_mfma_f32_16x16x32_bf16 v[62:65], v[134:137], v[178:181], v[62:65]
	v_mfma_f32_16x16x32_bf16 v[62:65], v[138:141], v[182:185], v[62:65]
	v_mfma_f32_16x16x32_bf16 v[58:61], v[146:149], v[182:185], v[58:61]
	v_mfma_f32_16x16x32_bf16 v[58:61], v[142:145], v[178:181], v[58:61]
	v_mfma_f32_16x16x32_bf16 v[54:57], v[150:153], v[178:181], v[54:57]
	v_mfma_f32_16x16x32_bf16 v[54:57], v[154:157], v[182:185], v[54:57]
	v_mfma_f32_16x16x32_bf16 v[50:53], v[174:177], v[182:185], v[50:53]
	v_mfma_f32_16x16x32_bf16 v[50:53], v[158:161], v[178:181], v[50:53]
	v_mfma_f32_16x16x32_bf16 v[34:37], v[158:161], v[186:189], v[34:37]
	v_mfma_f32_16x16x32_bf16 v[34:37], v[174:177], v[190:193], v[34:37]
	v_mfma_f32_16x16x32_bf16 v[38:41], v[154:157], v[190:193], v[38:41]
	v_mfma_f32_16x16x32_bf16 v[38:41], v[150:153], v[186:189], v[38:41]
	v_mfma_f32_16x16x32_bf16 v[42:45], v[142:145], v[186:189], v[42:45]
	v_mfma_f32_16x16x32_bf16 v[42:45], v[146:149], v[190:193], v[42:45]
	v_mfma_f32_16x16x32_bf16 v[46:49], v[138:141], v[190:193], v[46:49]
	v_mfma_f32_16x16x32_bf16 v[46:49], v[134:137], v[186:189], v[46:49]
	v_mfma_f32_16x16x32_bf16 v[30:33], v[134:137], v[204:207], v[30:33]
	v_mfma_f32_16x16x32_bf16 v[30:33], v[138:141], v[208:211], v[30:33]
	v_mfma_f32_16x16x32_bf16 v[26:29], v[146:149], v[208:211], v[26:29]
	v_mfma_f32_16x16x32_bf16 v[26:29], v[142:145], v[204:207], v[26:29]
	v_mfma_f32_16x16x32_bf16 v[22:25], v[150:153], v[204:207], v[22:25]
	v_mfma_f32_16x16x32_bf16 v[22:25], v[154:157], v[208:211], v[22:25]
	v_mfma_f32_16x16x32_bf16 v[18:21], v[174:177], v[208:211], v[18:21]
	v_mfma_f32_16x16x32_bf16 v[18:21], v[158:161], v[204:207], v[18:21]
	v_mfma_f32_16x16x32_bf16 v[2:5], v[158:161], v[212:215], v[2:5]
	v_mfma_f32_16x16x32_bf16 v[2:5], v[174:177], v[216:219], v[2:5]
	v_mfma_f32_16x16x32_bf16 v[6:9], v[154:157], v[216:219], v[6:9]
	v_mfma_f32_16x16x32_bf16 v[6:9], v[150:153], v[212:215], v[6:9]
	v_mfma_f32_16x16x32_bf16 v[10:13], v[142:145], v[212:215], v[10:13]
	v_mfma_f32_16x16x32_bf16 v[10:13], v[146:149], v[216:219], v[10:13]
	v_mfma_f32_16x16x32_bf16 v[14:17], v[138:141], v[216:219], v[14:17]
	v_mfma_f32_16x16x32_bf16 v[14:17], v[134:137], v[212:215], v[14:17]
	s_setprio 1
	s_barrier
	s_add_i32 s43, s43, 2
	s_add_u32 s76, s76, 0x100
	s_addc_u32 s77, s77, 0
	s_add_u32 s7, s7, 0x100
	s_addc_u32 s41, s41, 0
	s_cmp_gt_u32 s43, 29
	s_cbranch_scc1 .LBB0_288
	s_branch .LBB0_286

.LBB0_509:
	s_add_u32 s90, s76, 0x100
	s_addc_u32 s91, s77, 0
	s_and_b64 s[0:1], s[70:71], exec
	s_cselect_b32 vcc_hi, s22, s91
	s_cselect_b32 vcc_lo, s23, s90
	s_cselect_b32 s71, s41, s53
	s_cselect_b32 s70, s44, s51
	s_add_i32 s0, 0, 0x10000
	s_add_i32 s18, 0, 0x14000
	v_add_u32_e32 v114, s0, v1
	v_add_u32_e32 v154, s18, v1
	ds_read_b128 v[78:81], v114
	ds_read_b128 v[90:93], v114 offset:1024
	ds_read_b128 v[102:105], v114 offset:2048
	ds_read_b128 v[114:117], v114 offset:3072
	ds_read_b128 v[126:129], v154
	ds_read_b128 v[134:137], v154 offset:1024
	ds_read_b128 v[142:145], v154 offset:2048
	ds_read_b128 v[154:157], v154 offset:3072
	s_add_i32 m0, s29, 0xc000
	ds_read_b128 v[158:161], v237
	ds_read_b128 v[162:165], v237 offset:1024
	ds_read_b128 v[166:169], v237 offset:2048
	ds_read_b128 v[178:181], v237 offset:3072
	ds_read_b128 v[182:185], v237 offset:4096
	ds_read_b128 v[186:189], v237 offset:5120
	ds_read_b128 v[190:193], v237 offset:6144
	ds_read_b128 v[214:217], v237 offset:7168
	global_load_lds_dwordx4 v210, s[76:77]
	s_add_i32 m0, s29, 0xe000
	s_nop 0
	global_load_lds_dwordx4 v212, s[76:77]
	s_waitcnt vmcnt(8)
	s_waitcnt lgkmcnt(0)
	s_barrier
	s_setprio 0
	s_waitcnt lgkmcnt(0)
	v_mfma_f32_16x16x32_bf16 v[174:177], v[78:81], v[158:161], v[174:177]
	v_mfma_f32_16x16x32_bf16 v[174:177], v[90:93], v[162:165], v[174:177]
	v_mfma_f32_16x16x32_bf16 v[170:173], v[114:117], v[162:165], v[170:173]
	v_mfma_f32_16x16x32_bf16 v[170:173], v[102:105], v[158:161], v[170:173]
	v_mfma_f32_16x16x32_bf16 v[150:153], v[126:129], v[158:161], v[150:153]
	v_mfma_f32_16x16x32_bf16 v[150:153], v[134:137], v[162:165], v[150:153]
	v_mfma_f32_16x16x32_bf16 v[146:149], v[154:157], v[162:165], v[146:149]
	v_mfma_f32_16x16x32_bf16 v[146:149], v[142:145], v[158:161], v[146:149]
	v_mfma_f32_16x16x32_bf16 v[118:121], v[142:145], v[166:169], v[118:121]
	v_mfma_f32_16x16x32_bf16 v[118:121], v[154:157], v[178:181], v[118:121]
	v_mfma_f32_16x16x32_bf16 v[122:125], v[134:137], v[178:181], v[122:125]
	v_mfma_f32_16x16x32_bf16 v[122:125], v[126:129], v[166:169], v[122:125]
	v_mfma_f32_16x16x32_bf16 v[130:133], v[102:105], v[166:169], v[130:133]
	v_mfma_f32_16x16x32_bf16 v[130:133], v[114:117], v[178:181], v[130:133]
	v_mfma_f32_16x16x32_bf16 v[138:141], v[90:93], v[178:181], v[138:141]
	v_mfma_f32_16x16x32_bf16 v[138:141], v[78:81], v[166:169], v[138:141]
	v_mfma_f32_16x16x32_bf16 v[110:113], v[78:81], v[182:185], v[110:113]
	v_mfma_f32_16x16x32_bf16 v[110:113], v[90:93], v[186:189], v[110:113]
	v_mfma_f32_16x16x32_bf16 v[106:109], v[114:117], v[186:189], v[106:109]
	v_mfma_f32_16x16x32_bf16 v[106:109], v[102:105], v[182:185], v[106:109]
	v_mfma_f32_16x16x32_bf16 v[98:101], v[126:129], v[182:185], v[98:101]
	v_mfma_f32_16x16x32_bf16 v[98:101], v[134:137], v[186:189], v[98:101]
	v_mfma_f32_16x16x32_bf16 v[94:97], v[154:157], v[186:189], v[94:97]
	v_mfma_f32_16x16x32_bf16 v[94:97], v[142:145], v[182:185], v[94:97]
	v_mfma_f32_16x16x32_bf16 v[66:69], v[142:145], v[190:193], v[66:69]
	v_mfma_f32_16x16x32_bf16 v[66:69], v[154:157], v[214:217], v[66:69]
	v_mfma_f32_16x16x32_bf16 v[74:77], v[134:137], v[214:217], v[74:77]
	v_mfma_f32_16x16x32_bf16 v[74:77], v[126:129], v[190:193], v[74:77]
	v_mfma_f32_16x16x32_bf16 v[82:85], v[102:105], v[190:193], v[82:85]
	v_mfma_f32_16x16x32_bf16 v[82:85], v[114:117], v[214:217], v[82:85]
	v_mfma_f32_16x16x32_bf16 v[86:89], v[90:93], v[214:217], v[86:89]
	v_mfma_f32_16x16x32_bf16 v[86:89], v[78:81], v[190:193], v[86:89]
	s_setprio 1
	s_barrier
	s_add_i32 s0, s0, s28
	s_mov_b32 m0, s0
	ds_read_b128 v[158:161], v237 offset:16384
	ds_read_b128 v[162:165], v237 offset:17408
	ds_read_b128 v[166:169], v237 offset:18432
	ds_read_b128 v[178:181], v237 offset:19456
	ds_read_b128 v[182:185], v237 offset:20480
	ds_read_b128 v[186:189], v237 offset:21504
	ds_read_b128 v[190:193], v237 offset:22528
	ds_read_b128 v[214:217], v237 offset:23552
	global_load_lds_dwordx4 v194, s[70:71]
	s_add_i32 m0, s0, 0x2000
	s_add_u32 s0, s70, 0x80000
	s_addc_u32 s1, s71, 0
	s_add_i32 s18, s18, s28
	global_load_lds_dwordx4 v204, s[70:71]
	s_mov_b32 m0, s18
	s_nop 0
	global_load_lds_dwordx4 v194, s[0:1]
	s_add_i32 m0, s18, 0x2000
	s_nop 0
	global_load_lds_dwordx4 v204, s[0:1]
	s_mov_b32 m0, s29
	s_nop 0
	global_load_lds_dwordx4 v194, vcc
	s_mov_b32 m0, s31
	s_nop 0
	global_load_lds_dwordx4 v204, vcc
	s_waitcnt vmcnt(8)
	s_waitcnt lgkmcnt(0)
	s_barrier
	s_setprio 0
	s_waitcnt lgkmcnt(0)
	v_mfma_f32_16x16x32_bf16 v[62:65], v[78:81], v[158:161], v[62:65]
	v_mfma_f32_16x16x32_bf16 v[62:65], v[90:93], v[162:165], v[62:65]
	v_mfma_f32_16x16x32_bf16 v[58:61], v[114:117], v[162:165], v[58:61]
	v_mfma_f32_16x16x32_bf16 v[58:61], v[102:105], v[158:161], v[58:61]
	v_mfma_f32_16x16x32_bf16 v[54:57], v[126:129], v[158:161], v[54:57]
	v_mfma_f32_16x16x32_bf16 v[54:57], v[134:137], v[162:165], v[54:57]
	v_mfma_f32_16x16x32_bf16 v[50:53], v[154:157], v[162:165], v[50:53]
	v_mfma_f32_16x16x32_bf16 v[50:53], v[142:145], v[158:161], v[50:53]
	v_mfma_f32_16x16x32_bf16 v[34:37], v[142:145], v[166:169], v[34:37]
	v_mfma_f32_16x16x32_bf16 v[34:37], v[154:157], v[178:181], v[34:37]
	v_mfma_f32_16x16x32_bf16 v[38:41], v[134:137], v[178:181], v[38:41]
	v_mfma_f32_16x16x32_bf16 v[38:41], v[126:129], v[166:169], v[38:41]
	v_mfma_f32_16x16x32_bf16 v[42:45], v[102:105], v[166:169], v[42:45]
	v_mfma_f32_16x16x32_bf16 v[42:45], v[114:117], v[178:181], v[42:45]
	v_mfma_f32_16x16x32_bf16 v[46:49], v[90:93], v[178:181], v[46:49]
	v_mfma_f32_16x16x32_bf16 v[46:49], v[78:81], v[166:169], v[46:49]
	v_mfma_f32_16x16x32_bf16 v[30:33], v[78:81], v[182:185], v[30:33]
	v_mfma_f32_16x16x32_bf16 v[30:33], v[90:93], v[186:189], v[30:33]
	v_mfma_f32_16x16x32_bf16 v[26:29], v[114:117], v[186:189], v[26:29]
	v_mfma_f32_16x16x32_bf16 v[26:29], v[102:105], v[182:185], v[26:29]
	v_mfma_f32_16x16x32_bf16 v[22:25], v[126:129], v[182:185], v[22:25]
	v_mfma_f32_16x16x32_bf16 v[22:25], v[134:137], v[186:189], v[22:25]
	v_mfma_f32_16x16x32_bf16 v[18:21], v[154:157], v[186:189], v[18:21]
	v_mfma_f32_16x16x32_bf16 v[18:21], v[142:145], v[182:185], v[18:21]
	v_mfma_f32_16x16x32_bf16 v[2:5], v[142:145], v[190:193], v[2:5]
	v_mfma_f32_16x16x32_bf16 v[2:5], v[154:157], v[214:217], v[2:5]
	v_mfma_f32_16x16x32_bf16 v[6:9], v[134:137], v[214:217], v[6:9]
	v_mfma_f32_16x16x32_bf16 v[6:9], v[126:129], v[190:193], v[6:9]
	v_mfma_f32_16x16x32_bf16 v[10:13], v[102:105], v[190:193], v[10:13]
	v_mfma_f32_16x16x32_bf16 v[10:13], v[114:117], v[214:217], v[10:13]
	v_mfma_f32_16x16x32_bf16 v[14:17], v[90:93], v[214:217], v[14:17]
	v_mfma_f32_16x16x32_bf16 v[14:17], v[78:81], v[190:193], v[14:17]
	s_setprio 1
	s_barrier
	s_add_i32 s18, 0, 0x18000
	s_add_i32 s19, 0, 0x1c000
	v_add_u32_e32 v114, s18, v1
	v_add_u32_e32 v154, s19, v1
	ds_read_b128 v[78:81], v114
	ds_read_b128 v[90:93], v114 offset:1024
	ds_read_b128 v[102:105], v114 offset:2048
	ds_read_b128 v[114:117], v114 offset:3072
	ds_read_b128 v[126:129], v154
	ds_read_b128 v[134:137], v154 offset:1024
	ds_read_b128 v[142:145], v154 offset:2048
	ds_read_b128 v[154:157], v154 offset:3072
	s_add_u32 s0, vcc_lo, 0x80000
	s_addc_u32 s1, vcc_hi, 0
	s_mov_b32 m0, s33
	ds_read_b128 v[158:161], v237 offset:32768
	ds_read_b128 v[162:165], v237 offset:33792
	ds_read_b128 v[166:169], v237 offset:34816
	ds_read_b128 v[178:181], v237 offset:35840
	ds_read_b128 v[182:185], v237 offset:36864
	ds_read_b128 v[186:189], v237 offset:37888
	ds_read_b128 v[190:193], v237 offset:38912
	ds_read_b128 v[214:217], v237 offset:39936
	global_load_lds_dwordx4 v194, s[0:1]
	s_mov_b32 m0, s43
	s_nop 0
	global_load_lds_dwordx4 v204, s[0:1]
	s_waitcnt vmcnt(8)
	s_waitcnt lgkmcnt(0)
	s_barrier
	s_setprio 0
	s_waitcnt lgkmcnt(0)
	v_mfma_f32_16x16x32_bf16 v[174:177], v[78:81], v[158:161], v[174:177]
	v_mfma_f32_16x16x32_bf16 v[174:177], v[90:93], v[162:165], v[174:177]
	v_mfma_f32_16x16x32_bf16 v[170:173], v[114:117], v[162:165], v[170:173]
	v_mfma_f32_16x16x32_bf16 v[170:173], v[102:105], v[158:161], v[170:173]
	v_mfma_f32_16x16x32_bf16 v[150:153], v[126:129], v[158:161], v[150:153]
	v_mfma_f32_16x16x32_bf16 v[150:153], v[134:137], v[162:165], v[150:153]
	v_mfma_f32_16x16x32_bf16 v[146:149], v[154:157], v[162:165], v[146:149]
	v_mfma_f32_16x16x32_bf16 v[146:149], v[142:145], v[158:161], v[146:149]
	v_mfma_f32_16x16x32_bf16 v[118:121], v[142:145], v[166:169], v[118:121]
	v_mfma_f32_16x16x32_bf16 v[118:121], v[154:157], v[178:181], v[118:121]
	v_mfma_f32_16x16x32_bf16 v[122:125], v[134:137], v[178:181], v[122:125]
	v_mfma_f32_16x16x32_bf16 v[122:125], v[126:129], v[166:169], v[122:125]
	v_mfma_f32_16x16x32_bf16 v[130:133], v[102:105], v[166:169], v[130:133]
	v_mfma_f32_16x16x32_bf16 v[130:133], v[114:117], v[178:181], v[130:133]
	v_mfma_f32_16x16x32_bf16 v[138:141], v[90:93], v[178:181], v[138:141]
	v_mfma_f32_16x16x32_bf16 v[138:141], v[78:81], v[166:169], v[138:141]
	v_mfma_f32_16x16x32_bf16 v[110:113], v[78:81], v[182:185], v[110:113]
	v_mfma_f32_16x16x32_bf16 v[110:113], v[90:93], v[186:189], v[110:113]
	v_mfma_f32_16x16x32_bf16 v[106:109], v[114:117], v[186:189], v[106:109]
	v_mfma_f32_16x16x32_bf16 v[106:109], v[102:105], v[182:185], v[106:109]
	v_mfma_f32_16x16x32_bf16 v[98:101], v[126:129], v[182:185], v[98:101]
	v_mfma_f32_16x16x32_bf16 v[98:101], v[134:137], v[186:189], v[98:101]
	v_mfma_f32_16x16x32_bf16 v[94:97], v[154:157], v[186:189], v[94:97]
	v_mfma_f32_16x16x32_bf16 v[94:97], v[142:145], v[182:185], v[94:97]
	v_mfma_f32_16x16x32_bf16 v[66:69], v[142:145], v[190:193], v[66:69]
	v_mfma_f32_16x16x32_bf16 v[66:69], v[154:157], v[214:217], v[66:69]
	v_mfma_f32_16x16x32_bf16 v[74:77], v[134:137], v[214:217], v[74:77]
	v_mfma_f32_16x16x32_bf16 v[74:77], v[126:129], v[190:193], v[74:77]
	v_mfma_f32_16x16x32_bf16 v[82:85], v[102:105], v[190:193], v[82:85]
	v_mfma_f32_16x16x32_bf16 v[82:85], v[114:117], v[214:217], v[82:85]
	v_mfma_f32_16x16x32_bf16 v[86:89], v[90:93], v[214:217], v[86:89]
	v_mfma_f32_16x16x32_bf16 v[86:89], v[78:81], v[190:193], v[86:89]
	s_setprio 1
	s_barrier
	s_add_u32 s98, s70, 0x80
	s_addc_u32 s99, s71, 0
	s_add_u32 s100, vcc_lo, 0x80
	s_addc_u32 s101, vcc_hi, 0
	s_add_i32 s0, s18, s28
	s_mov_b32 m0, s0
	ds_read_b128 v[158:161], v237 offset:49152
	ds_read_b128 v[162:165], v237 offset:50176
	ds_read_b128 v[166:169], v237 offset:51200
	ds_read_b128 v[178:181], v237 offset:52224
	ds_read_b128 v[182:185], v237 offset:53248
	ds_read_b128 v[186:189], v237 offset:54272
	ds_read_b128 v[190:193], v237 offset:55296
	ds_read_b128 v[214:217], v237 offset:56320
	global_load_lds_dwordx4 v194, s[98:99]
	s_add_i32 m0, s0, 0x2000
	s_add_u32 s0, s70, 0x80080
	s_addc_u32 s1, s71, 0
	s_add_i32 s18, s19, s28
	global_load_lds_dwordx4 v204, s[98:99]
	s_mov_b32 m0, s18
	s_nop 0
	global_load_lds_dwordx4 v194, s[0:1]
	s_add_i32 m0, s18, 0x2000
	s_nop 0
	global_load_lds_dwordx4 v204, s[0:1]
	s_mov_b32 m0, s68
	s_nop 0
	global_load_lds_dwordx4 v194, s[100:101]
	s_mov_b32 m0, s79
	s_nop 0
	global_load_lds_dwordx4 v204, s[100:101]
	s_waitcnt vmcnt(8)
	s_waitcnt lgkmcnt(0)
	s_barrier
	s_setprio 0
	s_waitcnt lgkmcnt(0)
	v_mfma_f32_16x16x32_bf16 v[62:65], v[78:81], v[158:161], v[62:65]
	v_mfma_f32_16x16x32_bf16 v[62:65], v[90:93], v[162:165], v[62:65]
	v_mfma_f32_16x16x32_bf16 v[58:61], v[114:117], v[162:165], v[58:61]
	v_mfma_f32_16x16x32_bf16 v[58:61], v[102:105], v[158:161], v[58:61]
	v_mfma_f32_16x16x32_bf16 v[54:57], v[126:129], v[158:161], v[54:57]
	v_mfma_f32_16x16x32_bf16 v[54:57], v[134:137], v[162:165], v[54:57]
	v_mfma_f32_16x16x32_bf16 v[50:53], v[154:157], v[162:165], v[50:53]
	v_mfma_f32_16x16x32_bf16 v[50:53], v[142:145], v[158:161], v[50:53]
	v_mfma_f32_16x16x32_bf16 v[34:37], v[142:145], v[166:169], v[34:37]
	v_mfma_f32_16x16x32_bf16 v[34:37], v[154:157], v[178:181], v[34:37]
	v_mfma_f32_16x16x32_bf16 v[38:41], v[134:137], v[178:181], v[38:41]
	v_mfma_f32_16x16x32_bf16 v[38:41], v[126:129], v[166:169], v[38:41]
	v_mfma_f32_16x16x32_bf16 v[42:45], v[102:105], v[166:169], v[42:45]
	v_mfma_f32_16x16x32_bf16 v[42:45], v[114:117], v[178:181], v[42:45]
	v_mfma_f32_16x16x32_bf16 v[46:49], v[90:93], v[178:181], v[46:49]
	v_mfma_f32_16x16x32_bf16 v[46:49], v[78:81], v[166:169], v[46:49]
	v_mfma_f32_16x16x32_bf16 v[30:33], v[78:81], v[182:185], v[30:33]
	v_mfma_f32_16x16x32_bf16 v[30:33], v[90:93], v[186:189], v[30:33]
	v_mfma_f32_16x16x32_bf16 v[26:29], v[114:117], v[186:189], v[26:29]
	v_mfma_f32_16x16x32_bf16 v[26:29], v[102:105], v[182:185], v[26:29]
	v_mfma_f32_16x16x32_bf16 v[22:25], v[126:129], v[182:185], v[22:25]
	v_mfma_f32_16x16x32_bf16 v[22:25], v[134:137], v[186:189], v[22:25]
	v_mfma_f32_16x16x32_bf16 v[18:21], v[154:157], v[186:189], v[18:21]
	v_mfma_f32_16x16x32_bf16 v[18:21], v[142:145], v[182:185], v[18:21]
	v_mfma_f32_16x16x32_bf16 v[2:5], v[142:145], v[190:193], v[2:5]
	v_mfma_f32_16x16x32_bf16 v[2:5], v[154:157], v[214:217], v[2:5]
	v_mfma_f32_16x16x32_bf16 v[6:9], v[134:137], v[214:217], v[6:9]
	v_mfma_f32_16x16x32_bf16 v[6:9], v[126:129], v[190:193], v[6:9]
	v_mfma_f32_16x16x32_bf16 v[10:13], v[102:105], v[190:193], v[10:13]
	v_mfma_f32_16x16x32_bf16 v[10:13], v[114:117], v[214:217], v[10:13]
	v_mfma_f32_16x16x32_bf16 v[14:17], v[90:93], v[214:217], v[14:17]
	v_mfma_f32_16x16x32_bf16 v[14:17], v[78:81], v[190:193], v[14:17]
	s_setprio 1
	s_barrier
	s_add_i32 s57, s57, 2
	s_add_u32 s51, s51, 0x100
	s_addc_u32 s53, s53, 0
	s_cmp_gt_u32 s57, 29
	s_mov_b64 s[76:77], s[90:91]
	s_cbranch_scc1 .LBB0_512

.Lpeel_disp_out:
	s_cmp_lg_u32 s57, -2
	s_cbranch_scc1 .LBB0_509
	s_add_u32 s90, s76, 0x100
	s_addc_u32 s91, s77, 0
	s_and_b64 s[0:1], s[70:71], exec
	s_cselect_b32 vcc_hi, s22, s91
	s_cselect_b32 vcc_lo, s23, s90
	s_cselect_b32 s71, s41, s53
	s_cselect_b32 s70, s44, s51
	s_add_i32 s0, 0, 0x10000
	s_add_i32 s18, 0, 0x14000
	v_add_u32_e32 v114, s0, v1
	v_add_u32_e32 v154, s18, v1
	ds_read_b128 v[78:81], v114
	ds_read_b128 v[90:93], v114 offset:1024
	ds_read_b128 v[102:105], v114 offset:2048
	ds_read_b128 v[114:117], v114 offset:3072
	ds_read_b128 v[126:129], v154
	ds_read_b128 v[134:137], v154 offset:1024
	ds_read_b128 v[142:145], v154 offset:2048
	ds_read_b128 v[154:157], v154 offset:3072
	s_add_i32 m0, s29, 0xc000
	ds_read_b128 v[158:161], v237
	ds_read_b128 v[162:165], v237 offset:1024
	ds_read_b128 v[166:169], v237 offset:2048
	ds_read_b128 v[178:181], v237 offset:3072
	ds_read_b128 v[182:185], v237 offset:4096
	ds_read_b128 v[186:189], v237 offset:5120
	ds_read_b128 v[190:193], v237 offset:6144
	ds_read_b128 v[214:217], v237 offset:7168
	global_load_lds_dwordx4 v210, s[76:77]
	s_add_i32 m0, s29, 0xe000
	s_nop 0
	global_load_lds_dwordx4 v212, s[76:77]
	s_waitcnt vmcnt(8)
	s_waitcnt lgkmcnt(0)
	s_barrier
	s_setprio 0
	s_waitcnt lgkmcnt(0)
	v_mfma_f32_16x16x32_bf16 v[174:177], v[78:81], v[158:161], 0
	v_mfma_f32_16x16x32_bf16 v[174:177], v[90:93], v[162:165], v[174:177]
	v_mfma_f32_16x16x32_bf16 v[170:173], v[114:117], v[162:165], 0
	v_mfma_f32_16x16x32_bf16 v[170:173], v[102:105], v[158:161], v[170:173]
	v_mfma_f32_16x16x32_bf16 v[150:153], v[126:129], v[158:161], 0
	v_mfma_f32_16x16x32_bf16 v[150:153], v[134:137], v[162:165], v[150:153]
	v_mfma_f32_16x16x32_bf16 v[146:149], v[154:157], v[162:165], 0
	v_mfma_f32_16x16x32_bf16 v[146:149], v[142:145], v[158:161], v[146:149]
	v_mfma_f32_16x16x32_bf16 v[118:121], v[142:145], v[166:169], 0
	v_mfma_f32_16x16x32_bf16 v[118:121], v[154:157], v[178:181], v[118:121]
	v_mfma_f32_16x16x32_bf16 v[122:125], v[134:137], v[178:181], 0
	v_mfma_f32_16x16x32_bf16 v[122:125], v[126:129], v[166:169], v[122:125]
	v_mfma_f32_16x16x32_bf16 v[130:133], v[102:105], v[166:169], 0
	v_mfma_f32_16x16x32_bf16 v[130:133], v[114:117], v[178:181], v[130:133]
	v_mfma_f32_16x16x32_bf16 v[138:141], v[90:93], v[178:181], 0
	v_mfma_f32_16x16x32_bf16 v[138:141], v[78:81], v[166:169], v[138:141]
	v_mfma_f32_16x16x32_bf16 v[110:113], v[78:81], v[182:185], 0
	v_mfma_f32_16x16x32_bf16 v[110:113], v[90:93], v[186:189], v[110:113]
	v_mfma_f32_16x16x32_bf16 v[106:109], v[114:117], v[186:189], 0
	v_mfma_f32_16x16x32_bf16 v[106:109], v[102:105], v[182:185], v[106:109]
	v_mfma_f32_16x16x32_bf16 v[98:101], v[126:129], v[182:185], 0
	v_mfma_f32_16x16x32_bf16 v[98:101], v[134:137], v[186:189], v[98:101]
	v_mfma_f32_16x16x32_bf16 v[94:97], v[154:157], v[186:189], 0
	v_mfma_f32_16x16x32_bf16 v[94:97], v[142:145], v[182:185], v[94:97]
	v_mfma_f32_16x16x32_bf16 v[66:69], v[142:145], v[190:193], 0
	v_mfma_f32_16x16x32_bf16 v[66:69], v[154:157], v[214:217], v[66:69]
	v_mfma_f32_16x16x32_bf16 v[74:77], v[134:137], v[214:217], 0
	v_mfma_f32_16x16x32_bf16 v[74:77], v[126:129], v[190:193], v[74:77]
	v_mfma_f32_16x16x32_bf16 v[82:85], v[102:105], v[190:193], 0
	v_mfma_f32_16x16x32_bf16 v[82:85], v[114:117], v[214:217], v[82:85]
	v_mfma_f32_16x16x32_bf16 v[86:89], v[90:93], v[214:217], 0
	v_mfma_f32_16x16x32_bf16 v[86:89], v[78:81], v[190:193], v[86:89]
	s_setprio 1
	s_barrier
	s_add_i32 s0, s0, s28
	s_mov_b32 m0, s0
	ds_read_b128 v[158:161], v237 offset:16384
	ds_read_b128 v[162:165], v237 offset:17408
	ds_read_b128 v[166:169], v237 offset:18432
	ds_read_b128 v[178:181], v237 offset:19456
	ds_read_b128 v[182:185], v237 offset:20480
	ds_read_b128 v[186:189], v237 offset:21504
	ds_read_b128 v[190:193], v237 offset:22528
	ds_read_b128 v[214:217], v237 offset:23552
	global_load_lds_dwordx4 v194, s[70:71]
	s_add_i32 m0, s0, 0x2000
	s_add_u32 s0, s70, 0x80000
	s_addc_u32 s1, s71, 0
	s_add_i32 s18, s18, s28
	global_load_lds_dwordx4 v204, s[70:71]
	s_mov_b32 m0, s18
	s_nop 0
	global_load_lds_dwordx4 v194, s[0:1]
	s_add_i32 m0, s18, 0x2000
	s_nop 0
	global_load_lds_dwordx4 v204, s[0:1]
	s_mov_b32 m0, s29
	s_nop 0
	global_load_lds_dwordx4 v194, vcc
	s_mov_b32 m0, s31
	s_nop 0
	global_load_lds_dwordx4 v204, vcc
	s_waitcnt vmcnt(8)
	s_waitcnt lgkmcnt(0)
	s_barrier
	s_setprio 0
	s_waitcnt lgkmcnt(0)
	v_mfma_f32_16x16x32_bf16 v[62:65], v[78:81], v[158:161], 0
	v_mfma_f32_16x16x32_bf16 v[62:65], v[90:93], v[162:165], v[62:65]
	v_mfma_f32_16x16x32_bf16 v[58:61], v[114:117], v[162:165], 0
	v_mfma_f32_16x16x32_bf16 v[58:61], v[102:105], v[158:161], v[58:61]
	v_mfma_f32_16x16x32_bf16 v[54:57], v[126:129], v[158:161], 0
	v_mfma_f32_16x16x32_bf16 v[54:57], v[134:137], v[162:165], v[54:57]
	v_mfma_f32_16x16x32_bf16 v[50:53], v[154:157], v[162:165], 0
	v_mfma_f32_16x16x32_bf16 v[50:53], v[142:145], v[158:161], v[50:53]
	v_mfma_f32_16x16x32_bf16 v[34:37], v[142:145], v[166:169], 0
	v_mfma_f32_16x16x32_bf16 v[34:37], v[154:157], v[178:181], v[34:37]
	v_mfma_f32_16x16x32_bf16 v[38:41], v[134:137], v[178:181], 0
	v_mfma_f32_16x16x32_bf16 v[38:41], v[126:129], v[166:169], v[38:41]
	v_mfma_f32_16x16x32_bf16 v[42:45], v[102:105], v[166:169], 0
	v_mfma_f32_16x16x32_bf16 v[42:45], v[114:117], v[178:181], v[42:45]
	v_mfma_f32_16x16x32_bf16 v[46:49], v[90:93], v[178:181], 0
	v_mfma_f32_16x16x32_bf16 v[46:49], v[78:81], v[166:169], v[46:49]
	v_mfma_f32_16x16x32_bf16 v[30:33], v[78:81], v[182:185], 0
	v_mfma_f32_16x16x32_bf16 v[30:33], v[90:93], v[186:189], v[30:33]
	v_mfma_f32_16x16x32_bf16 v[26:29], v[114:117], v[186:189], 0
	v_mfma_f32_16x16x32_bf16 v[26:29], v[102:105], v[182:185], v[26:29]
	v_mfma_f32_16x16x32_bf16 v[22:25], v[126:129], v[182:185], 0
	v_mfma_f32_16x16x32_bf16 v[22:25], v[134:137], v[186:189], v[22:25]
	v_mfma_f32_16x16x32_bf16 v[18:21], v[154:157], v[186:189], 0
	v_mfma_f32_16x16x32_bf16 v[18:21], v[142:145], v[182:185], v[18:21]
	v_mfma_f32_16x16x32_bf16 v[2:5], v[142:145], v[190:193], 0
	v_mfma_f32_16x16x32_bf16 v[2:5], v[154:157], v[214:217], v[2:5]
	v_mfma_f32_16x16x32_bf16 v[6:9], v[134:137], v[214:217], 0
	v_mfma_f32_16x16x32_bf16 v[6:9], v[126:129], v[190:193], v[6:9]
	v_mfma_f32_16x16x32_bf16 v[10:13], v[102:105], v[190:193], 0
	v_mfma_f32_16x16x32_bf16 v[10:13], v[114:117], v[214:217], v[10:13]
	v_mfma_f32_16x16x32_bf16 v[14:17], v[90:93], v[214:217], 0
	v_mfma_f32_16x16x32_bf16 v[14:17], v[78:81], v[190:193], v[14:17]
	s_setprio 1
	s_barrier
	s_add_i32 s18, 0, 0x18000
	s_add_i32 s19, 0, 0x1c000
	v_add_u32_e32 v114, s18, v1
	v_add_u32_e32 v154, s19, v1
	ds_read_b128 v[78:81], v114
	ds_read_b128 v[90:93], v114 offset:1024
	ds_read_b128 v[102:105], v114 offset:2048
	ds_read_b128 v[114:117], v114 offset:3072
	ds_read_b128 v[126:129], v154
	ds_read_b128 v[134:137], v154 offset:1024
	ds_read_b128 v[142:145], v154 offset:2048
	ds_read_b128 v[154:157], v154 offset:3072
	s_add_u32 s0, vcc_lo, 0x80000
	s_addc_u32 s1, vcc_hi, 0
	s_mov_b32 m0, s33
	ds_read_b128 v[158:161], v237 offset:32768
	ds_read_b128 v[162:165], v237 offset:33792
	ds_read_b128 v[166:169], v237 offset:34816
	ds_read_b128 v[178:181], v237 offset:35840
	ds_read_b128 v[182:185], v237 offset:36864
	ds_read_b128 v[186:189], v237 offset:37888
	ds_read_b128 v[190:193], v237 offset:38912
	ds_read_b128 v[214:217], v237 offset:39936
	global_load_lds_dwordx4 v194, s[0:1]
	s_mov_b32 m0, s43
	s_nop 0
	global_load_lds_dwordx4 v204, s[0:1]
	s_waitcnt vmcnt(8)
	s_waitcnt lgkmcnt(0)
	s_barrier
	s_setprio 0
	s_waitcnt lgkmcnt(0)
	v_mfma_f32_16x16x32_bf16 v[174:177], v[78:81], v[158:161], v[174:177]
	v_mfma_f32_16x16x32_bf16 v[174:177], v[90:93], v[162:165], v[174:177]
	v_mfma_f32_16x16x32_bf16 v[170:173], v[114:117], v[162:165], v[170:173]
	v_mfma_f32_16x16x32_bf16 v[170:173], v[102:105], v[158:161], v[170:173]
	v_mfma_f32_16x16x32_bf16 v[150:153], v[126:129], v[158:161], v[150:153]
	v_mfma_f32_16x16x32_bf16 v[150:153], v[134:137], v[162:165], v[150:153]
	v_mfma_f32_16x16x32_bf16 v[146:149], v[154:157], v[162:165], v[146:149]
	v_mfma_f32_16x16x32_bf16 v[146:149], v[142:145], v[158:161], v[146:149]
	v_mfma_f32_16x16x32_bf16 v[118:121], v[142:145], v[166:169], v[118:121]
	v_mfma_f32_16x16x32_bf16 v[118:121], v[154:157], v[178:181], v[118:121]
	v_mfma_f32_16x16x32_bf16 v[122:125], v[134:137], v[178:181], v[122:125]
	v_mfma_f32_16x16x32_bf16 v[122:125], v[126:129], v[166:169], v[122:125]
	v_mfma_f32_16x16x32_bf16 v[130:133], v[102:105], v[166:169], v[130:133]
	v_mfma_f32_16x16x32_bf16 v[130:133], v[114:117], v[178:181], v[130:133]
	v_mfma_f32_16x16x32_bf16 v[138:141], v[90:93], v[178:181], v[138:141]
	v_mfma_f32_16x16x32_bf16 v[138:141], v[78:81], v[166:169], v[138:141]
	v_mfma_f32_16x16x32_bf16 v[110:113], v[78:81], v[182:185], v[110:113]
	v_mfma_f32_16x16x32_bf16 v[110:113], v[90:93], v[186:189], v[110:113]
	v_mfma_f32_16x16x32_bf16 v[106:109], v[114:117], v[186:189], v[106:109]
	v_mfma_f32_16x16x32_bf16 v[106:109], v[102:105], v[182:185], v[106:109]
	v_mfma_f32_16x16x32_bf16 v[98:101], v[126:129], v[182:185], v[98:101]
	v_mfma_f32_16x16x32_bf16 v[98:101], v[134:137], v[186:189], v[98:101]
	v_mfma_f32_16x16x32_bf16 v[94:97], v[154:157], v[186:189], v[94:97]
	v_mfma_f32_16x16x32_bf16 v[94:97], v[142:145], v[182:185], v[94:97]
	v_mfma_f32_16x16x32_bf16 v[66:69], v[142:145], v[190:193], v[66:69]
	v_mfma_f32_16x16x32_bf16 v[66:69], v[154:157], v[214:217], v[66:69]
	v_mfma_f32_16x16x32_bf16 v[74:77], v[134:137], v[214:217], v[74:77]
	v_mfma_f32_16x16x32_bf16 v[74:77], v[126:129], v[190:193], v[74:77]
	v_mfma_f32_16x16x32_bf16 v[82:85], v[102:105], v[190:193], v[82:85]
	v_mfma_f32_16x16x32_bf16 v[82:85], v[114:117], v[214:217], v[82:85]
	v_mfma_f32_16x16x32_bf16 v[86:89], v[90:93], v[214:217], v[86:89]
	v_mfma_f32_16x16x32_bf16 v[86:89], v[78:81], v[190:193], v[86:89]
	s_setprio 1
	s_barrier
	s_add_u32 s98, s70, 0x80
	s_addc_u32 s99, s71, 0
	s_add_u32 s100, vcc_lo, 0x80
	s_addc_u32 s101, vcc_hi, 0
	s_add_i32 s0, s18, s28
	s_mov_b32 m0, s0
	ds_read_b128 v[158:161], v237 offset:49152
	ds_read_b128 v[162:165], v237 offset:50176
	ds_read_b128 v[166:169], v237 offset:51200
	ds_read_b128 v[178:181], v237 offset:52224
	ds_read_b128 v[182:185], v237 offset:53248
	ds_read_b128 v[186:189], v237 offset:54272
	ds_read_b128 v[190:193], v237 offset:55296
	ds_read_b128 v[214:217], v237 offset:56320
	global_load_lds_dwordx4 v194, s[98:99]
	s_add_i32 m0, s0, 0x2000
	s_add_u32 s0, s70, 0x80080
	s_addc_u32 s1, s71, 0
	s_add_i32 s18, s19, s28
	global_load_lds_dwordx4 v204, s[98:99]
	s_mov_b32 m0, s18
	s_nop 0
	global_load_lds_dwordx4 v194, s[0:1]
	s_add_i32 m0, s18, 0x2000
	s_nop 0
	global_load_lds_dwordx4 v204, s[0:1]
	s_mov_b32 m0, s68
	s_nop 0
	global_load_lds_dwordx4 v194, s[100:101]
	s_mov_b32 m0, s79
	s_nop 0
	global_load_lds_dwordx4 v204, s[100:101]
	s_waitcnt vmcnt(8)
	s_waitcnt lgkmcnt(0)
	s_barrier
	s_setprio 0
	s_waitcnt lgkmcnt(0)
	v_mfma_f32_16x16x32_bf16 v[62:65], v[78:81], v[158:161], v[62:65]
	v_mfma_f32_16x16x32_bf16 v[62:65], v[90:93], v[162:165], v[62:65]
	v_mfma_f32_16x16x32_bf16 v[58:61], v[114:117], v[162:165], v[58:61]
	v_mfma_f32_16x16x32_bf16 v[58:61], v[102:105], v[158:161], v[58:61]
	v_mfma_f32_16x16x32_bf16 v[54:57], v[126:129], v[158:161], v[54:57]
	v_mfma_f32_16x16x32_bf16 v[54:57], v[134:137], v[162:165], v[54:57]
	v_mfma_f32_16x16x32_bf16 v[50:53], v[154:157], v[162:165], v[50:53]
	v_mfma_f32_16x16x32_bf16 v[50:53], v[142:145], v[158:161], v[50:53]
	v_mfma_f32_16x16x32_bf16 v[34:37], v[142:145], v[166:169], v[34:37]
	v_mfma_f32_16x16x32_bf16 v[34:37], v[154:157], v[178:181], v[34:37]
	v_mfma_f32_16x16x32_bf16 v[38:41], v[134:137], v[178:181], v[38:41]
	v_mfma_f32_16x16x32_bf16 v[38:41], v[126:129], v[166:169], v[38:41]
	v_mfma_f32_16x16x32_bf16 v[42:45], v[102:105], v[166:169], v[42:45]
	v_mfma_f32_16x16x32_bf16 v[42:45], v[114:117], v[178:181], v[42:45]
	v_mfma_f32_16x16x32_bf16 v[46:49], v[90:93], v[178:181], v[46:49]
	v_mfma_f32_16x16x32_bf16 v[46:49], v[78:81], v[166:169], v[46:49]
	v_mfma_f32_16x16x32_bf16 v[30:33], v[78:81], v[182:185], v[30:33]
	v_mfma_f32_16x16x32_bf16 v[30:33], v[90:93], v[186:189], v[30:33]
	v_mfma_f32_16x16x32_bf16 v[26:29], v[114:117], v[186:189], v[26:29]
	v_mfma_f32_16x16x32_bf16 v[26:29], v[102:105], v[182:185], v[26:29]
	v_mfma_f32_16x16x32_bf16 v[22:25], v[126:129], v[182:185], v[22:25]
	v_mfma_f32_16x16x32_bf16 v[22:25], v[134:137], v[186:189], v[22:25]
	v_mfma_f32_16x16x32_bf16 v[18:21], v[154:157], v[186:189], v[18:21]
	v_mfma_f32_16x16x32_bf16 v[18:21], v[142:145], v[182:185], v[18:21]
	v_mfma_f32_16x16x32_bf16 v[2:5], v[142:145], v[190:193], v[2:5]
	v_mfma_f32_16x16x32_bf16 v[2:5], v[154:157], v[214:217], v[2:5]
	v_mfma_f32_16x16x32_bf16 v[6:9], v[134:137], v[214:217], v[6:9]
	v_mfma_f32_16x16x32_bf16 v[6:9], v[126:129], v[190:193], v[6:9]
	v_mfma_f32_16x16x32_bf16 v[10:13], v[102:105], v[190:193], v[10:13]
	v_mfma_f32_16x16x32_bf16 v[10:13], v[114:117], v[214:217], v[10:13]
	v_mfma_f32_16x16x32_bf16 v[14:17], v[90:93], v[214:217], v[14:17]
	v_mfma_f32_16x16x32_bf16 v[14:17], v[78:81], v[190:193], v[14:17]
	s_setprio 1
	s_barrier
	s_add_i32 s57, s57, 2
	s_add_u32 s51, s51, 0x100
	s_addc_u32 s53, s53, 0
	s_cmp_gt_u32 s57, 29
	s_mov_b64 s[76:77], s[90:91]
	s_cbranch_scc1 .LBB0_512
	s_branch .LBB0_510

.LBB0_581:
	s_add_u32 s18, s62, 0xfff80080
	s_addc_u32 s19, s63, -1
	s_and_b64 s[0:1], s[64:65], exec
	s_cselect_b32 s71, s22, s19
	s_cselect_b32 s70, s23, s18
	s_cselect_b32 s65, s39, s58
	s_cselect_b32 s64, s47, s53
	s_add_i32 s0, 0, 0x10000
	v_add_u32_e32 v153, s0, v1
	s_add_i32 s18, 0, 0x14000
	ds_read_b128 v[144:147], v153
	ds_read_b128 v[148:151], v153 offset:1024
	ds_read_b128 v[154:157], v153 offset:2048
	ds_read_b128 v[158:161], v153 offset:3072
	v_add_u32_e32 v153, s18, v1
	ds_read_b128 v[162:165], v153
	ds_read_b128 v[166:169], v153 offset:1024
	ds_read_b128 v[170:173], v153 offset:2048
	ds_read_b128 v[174:177], v153 offset:3072
	s_add_i32 m0, s29, 0xc000
	ds_read_b128 v[178:181], v152
	ds_read_b128 v[182:185], v152 offset:1024
	ds_read_b128 v[186:189], v152 offset:2048
	ds_read_b128 v[190:193], v152 offset:3072
	ds_read_b128 v[204:207], v152 offset:4096
	ds_read_b128 v[208:211], v152 offset:5120
	ds_read_b128 v[212:215], v152 offset:6144
	ds_read_b128 v[216:219], v152 offset:7168
	global_load_lds_dwordx4 v136, s[62:63]
	s_add_i32 m0, s29, 0xe000
	s_nop 0
	global_load_lds_dwordx4 v138, s[62:63]
	s_waitcnt vmcnt(8)
	s_waitcnt lgkmcnt(0)
	s_barrier
	s_setprio 0
	s_waitcnt lgkmcnt(0)
	v_mfma_f32_16x16x32_bf16 v[126:129], v[144:147], v[178:181], v[126:129]
	v_mfma_f32_16x16x32_bf16 v[126:129], v[148:151], v[182:185], v[126:129]
	v_mfma_f32_16x16x32_bf16 v[122:125], v[158:161], v[182:185], v[122:125]
	v_mfma_f32_16x16x32_bf16 v[122:125], v[154:157], v[178:181], v[122:125]
	v_mfma_f32_16x16x32_bf16 v[118:121], v[162:165], v[178:181], v[118:121]
	v_mfma_f32_16x16x32_bf16 v[118:121], v[166:169], v[182:185], v[118:121]
	v_mfma_f32_16x16x32_bf16 v[114:117], v[174:177], v[182:185], v[114:117]
	v_mfma_f32_16x16x32_bf16 v[114:117], v[170:173], v[178:181], v[114:117]
	v_mfma_f32_16x16x32_bf16 v[98:101], v[170:173], v[186:189], v[98:101]
	v_mfma_f32_16x16x32_bf16 v[98:101], v[174:177], v[190:193], v[98:101]
	v_mfma_f32_16x16x32_bf16 v[102:105], v[166:169], v[190:193], v[102:105]
	v_mfma_f32_16x16x32_bf16 v[102:105], v[162:165], v[186:189], v[102:105]
	v_mfma_f32_16x16x32_bf16 v[106:109], v[154:157], v[186:189], v[106:109]
	v_mfma_f32_16x16x32_bf16 v[106:109], v[158:161], v[190:193], v[106:109]
	v_mfma_f32_16x16x32_bf16 v[110:113], v[148:151], v[190:193], v[110:113]
	v_mfma_f32_16x16x32_bf16 v[110:113], v[144:147], v[186:189], v[110:113]
	v_mfma_f32_16x16x32_bf16 v[94:97], v[144:147], v[204:207], v[94:97]
	v_mfma_f32_16x16x32_bf16 v[94:97], v[148:151], v[208:211], v[94:97]
	v_mfma_f32_16x16x32_bf16 v[90:93], v[158:161], v[208:211], v[90:93]
	v_mfma_f32_16x16x32_bf16 v[90:93], v[154:157], v[204:207], v[90:93]
	v_mfma_f32_16x16x32_bf16 v[86:89], v[162:165], v[204:207], v[86:89]
	v_mfma_f32_16x16x32_bf16 v[86:89], v[166:169], v[208:211], v[86:89]
	v_mfma_f32_16x16x32_bf16 v[82:85], v[174:177], v[208:211], v[82:85]
	v_mfma_f32_16x16x32_bf16 v[82:85], v[170:173], v[204:207], v[82:85]
	v_mfma_f32_16x16x32_bf16 v[66:69], v[170:173], v[212:215], v[66:69]
	v_mfma_f32_16x16x32_bf16 v[66:69], v[174:177], v[216:219], v[66:69]
	v_mfma_f32_16x16x32_bf16 v[70:73], v[166:169], v[216:219], v[70:73]
	v_mfma_f32_16x16x32_bf16 v[70:73], v[162:165], v[212:215], v[70:73]
	v_mfma_f32_16x16x32_bf16 v[74:77], v[154:157], v[212:215], v[74:77]
	v_mfma_f32_16x16x32_bf16 v[74:77], v[158:161], v[216:219], v[74:77]
	v_mfma_f32_16x16x32_bf16 v[78:81], v[148:151], v[216:219], v[78:81]
	v_mfma_f32_16x16x32_bf16 v[78:81], v[144:147], v[212:215], v[78:81]
	s_setprio 1
	s_barrier
	s_add_i32 s0, s0, s28
	s_mov_b32 m0, s0
	ds_read_b128 v[178:181], v152 offset:16384
	ds_read_b128 v[182:185], v152 offset:17408
	ds_read_b128 v[186:189], v152 offset:18432
	ds_read_b128 v[190:193], v152 offset:19456
	ds_read_b128 v[204:207], v152 offset:20480
	ds_read_b128 v[208:211], v152 offset:21504
	ds_read_b128 v[212:215], v152 offset:22528
	ds_read_b128 v[216:219], v152 offset:23552
	global_load_lds_dwordx4 v194, s[64:65]
	s_add_i32 m0, s0, 0x2000
	s_add_u32 s0, s64, 0x80000
	s_addc_u32 s1, s65, 0
	s_add_i32 s18, s18, s28
	global_load_lds_dwordx4 v130, s[64:65]
	s_mov_b32 m0, s18
	s_nop 0
	global_load_lds_dwordx4 v194, s[0:1]
	s_add_i32 m0, s18, 0x2000
	s_nop 0
	global_load_lds_dwordx4 v130, s[0:1]
	s_mov_b32 m0, s29
	s_nop 0
	global_load_lds_dwordx4 v194, s[70:71]
	s_mov_b32 m0, s31
	s_nop 0
	global_load_lds_dwordx4 v130, s[70:71]
	s_waitcnt vmcnt(8)
	s_waitcnt lgkmcnt(0)
	s_barrier
	s_setprio 0
	s_waitcnt lgkmcnt(0)
	v_mfma_f32_16x16x32_bf16 v[62:65], v[144:147], v[178:181], v[62:65]
	v_mfma_f32_16x16x32_bf16 v[62:65], v[148:151], v[182:185], v[62:65]
	v_mfma_f32_16x16x32_bf16 v[58:61], v[158:161], v[182:185], v[58:61]
	v_mfma_f32_16x16x32_bf16 v[58:61], v[154:157], v[178:181], v[58:61]
	v_mfma_f32_16x16x32_bf16 v[54:57], v[162:165], v[178:181], v[54:57]
	v_mfma_f32_16x16x32_bf16 v[54:57], v[166:169], v[182:185], v[54:57]
	v_mfma_f32_16x16x32_bf16 v[50:53], v[174:177], v[182:185], v[50:53]
	v_mfma_f32_16x16x32_bf16 v[50:53], v[170:173], v[178:181], v[50:53]
	v_mfma_f32_16x16x32_bf16 v[34:37], v[170:173], v[186:189], v[34:37]
	v_mfma_f32_16x16x32_bf16 v[34:37], v[174:177], v[190:193], v[34:37]
	v_mfma_f32_16x16x32_bf16 v[38:41], v[166:169], v[190:193], v[38:41]
	v_mfma_f32_16x16x32_bf16 v[38:41], v[162:165], v[186:189], v[38:41]
	v_mfma_f32_16x16x32_bf16 v[42:45], v[154:157], v[186:189], v[42:45]
	v_mfma_f32_16x16x32_bf16 v[42:45], v[158:161], v[190:193], v[42:45]
	v_mfma_f32_16x16x32_bf16 v[46:49], v[148:151], v[190:193], v[46:49]
	v_mfma_f32_16x16x32_bf16 v[46:49], v[144:147], v[186:189], v[46:49]
	v_mfma_f32_16x16x32_bf16 v[30:33], v[144:147], v[204:207], v[30:33]
	v_mfma_f32_16x16x32_bf16 v[30:33], v[148:151], v[208:211], v[30:33]
	v_mfma_f32_16x16x32_bf16 v[26:29], v[158:161], v[208:211], v[26:29]
	v_mfma_f32_16x16x32_bf16 v[26:29], v[154:157], v[204:207], v[26:29]
	v_mfma_f32_16x16x32_bf16 v[22:25], v[162:165], v[204:207], v[22:25]
	v_mfma_f32_16x16x32_bf16 v[22:25], v[166:169], v[208:211], v[22:25]
	v_mfma_f32_16x16x32_bf16 v[18:21], v[174:177], v[208:211], v[18:21]
	v_mfma_f32_16x16x32_bf16 v[18:21], v[170:173], v[204:207], v[18:21]
	v_mfma_f32_16x16x32_bf16 v[2:5], v[170:173], v[212:215], v[2:5]
	v_mfma_f32_16x16x32_bf16 v[2:5], v[174:177], v[216:219], v[2:5]
	v_mfma_f32_16x16x32_bf16 v[6:9], v[166:169], v[216:219], v[6:9]
	v_mfma_f32_16x16x32_bf16 v[6:9], v[162:165], v[212:215], v[6:9]
	v_mfma_f32_16x16x32_bf16 v[10:13], v[154:157], v[212:215], v[10:13]
	v_mfma_f32_16x16x32_bf16 v[10:13], v[158:161], v[216:219], v[10:13]
	v_mfma_f32_16x16x32_bf16 v[14:17], v[148:151], v[216:219], v[14:17]
	v_mfma_f32_16x16x32_bf16 v[14:17], v[144:147], v[212:215], v[14:17]
	s_setprio 1
	s_barrier
	s_add_i32 s18, 0, 0x18000
	v_add_u32_e32 v153, s18, v1
	s_add_i32 s19, 0, 0x1c000
	ds_read_b128 v[144:147], v153
	ds_read_b128 v[148:151], v153 offset:1024
	ds_read_b128 v[154:157], v153 offset:2048
	ds_read_b128 v[158:161], v153 offset:3072
	v_add_u32_e32 v153, s19, v1
	ds_read_b128 v[162:165], v153
	ds_read_b128 v[166:169], v153 offset:1024
	ds_read_b128 v[170:173], v153 offset:2048
	ds_read_b128 v[174:177], v153 offset:3072
	s_add_u32 s0, s70, 0x80000
	s_addc_u32 s1, s71, 0
	s_mov_b32 m0, s33
	ds_read_b128 v[178:181], v152 offset:32768
	ds_read_b128 v[182:185], v152 offset:33792
	ds_read_b128 v[186:189], v152 offset:34816
	ds_read_b128 v[190:193], v152 offset:35840
	ds_read_b128 v[204:207], v152 offset:36864
	ds_read_b128 v[208:211], v152 offset:37888
	ds_read_b128 v[212:215], v152 offset:38912
	ds_read_b128 v[216:219], v152 offset:39936
	global_load_lds_dwordx4 v194, s[0:1]
	s_mov_b32 m0, s40
	s_nop 0
	global_load_lds_dwordx4 v130, s[0:1]
	s_waitcnt vmcnt(8)
	s_waitcnt lgkmcnt(0)
	s_barrier
	s_setprio 0
	s_waitcnt lgkmcnt(0)
	v_mfma_f32_16x16x32_bf16 v[126:129], v[144:147], v[178:181], v[126:129]
	v_mfma_f32_16x16x32_bf16 v[126:129], v[148:151], v[182:185], v[126:129]
	v_mfma_f32_16x16x32_bf16 v[122:125], v[158:161], v[182:185], v[122:125]
	v_mfma_f32_16x16x32_bf16 v[122:125], v[154:157], v[178:181], v[122:125]
	v_mfma_f32_16x16x32_bf16 v[118:121], v[162:165], v[178:181], v[118:121]
	v_mfma_f32_16x16x32_bf16 v[118:121], v[166:169], v[182:185], v[118:121]
	v_mfma_f32_16x16x32_bf16 v[114:117], v[174:177], v[182:185], v[114:117]
	v_mfma_f32_16x16x32_bf16 v[114:117], v[170:173], v[178:181], v[114:117]
	v_mfma_f32_16x16x32_bf16 v[98:101], v[170:173], v[186:189], v[98:101]
	v_mfma_f32_16x16x32_bf16 v[98:101], v[174:177], v[190:193], v[98:101]
	v_mfma_f32_16x16x32_bf16 v[102:105], v[166:169], v[190:193], v[102:105]
	v_mfma_f32_16x16x32_bf16 v[102:105], v[162:165], v[186:189], v[102:105]
	v_mfma_f32_16x16x32_bf16 v[106:109], v[154:157], v[186:189], v[106:109]
	v_mfma_f32_16x16x32_bf16 v[106:109], v[158:161], v[190:193], v[106:109]
	v_mfma_f32_16x16x32_bf16 v[110:113], v[148:151], v[190:193], v[110:113]
	v_mfma_f32_16x16x32_bf16 v[110:113], v[144:147], v[186:189], v[110:113]
	v_mfma_f32_16x16x32_bf16 v[94:97], v[144:147], v[204:207], v[94:97]
	v_mfma_f32_16x16x32_bf16 v[94:97], v[148:151], v[208:211], v[94:97]
	v_mfma_f32_16x16x32_bf16 v[90:93], v[158:161], v[208:211], v[90:93]
	v_mfma_f32_16x16x32_bf16 v[90:93], v[154:157], v[204:207], v[90:93]
	v_mfma_f32_16x16x32_bf16 v[86:89], v[162:165], v[204:207], v[86:89]
	v_mfma_f32_16x16x32_bf16 v[86:89], v[166:169], v[208:211], v[86:89]
	v_mfma_f32_16x16x32_bf16 v[82:85], v[174:177], v[208:211], v[82:85]
	v_mfma_f32_16x16x32_bf16 v[82:85], v[170:173], v[204:207], v[82:85]
	v_mfma_f32_16x16x32_bf16 v[66:69], v[170:173], v[212:215], v[66:69]
	v_mfma_f32_16x16x32_bf16 v[66:69], v[174:177], v[216:219], v[66:69]
	v_mfma_f32_16x16x32_bf16 v[70:73], v[166:169], v[216:219], v[70:73]
	v_mfma_f32_16x16x32_bf16 v[70:73], v[162:165], v[212:215], v[70:73]
	v_mfma_f32_16x16x32_bf16 v[74:77], v[154:157], v[212:215], v[74:77]
	v_mfma_f32_16x16x32_bf16 v[74:77], v[158:161], v[216:219], v[74:77]
	v_mfma_f32_16x16x32_bf16 v[78:81], v[148:151], v[216:219], v[78:81]
	v_mfma_f32_16x16x32_bf16 v[78:81], v[144:147], v[212:215], v[78:81]
	s_setprio 1
	s_barrier
	s_add_u32 s98, s64, 0x80
	s_addc_u32 s99, s65, 0
	s_add_u32 s100, s70, 0x80
	s_addc_u32 s101, s71, 0
	s_add_i32 s0, s18, s28
	s_mov_b32 m0, s0
	ds_read_b128 v[178:181], v152 offset:49152
	ds_read_b128 v[182:185], v152 offset:50176
	ds_read_b128 v[186:189], v152 offset:51200
	ds_read_b128 v[190:193], v152 offset:52224
	ds_read_b128 v[204:207], v152 offset:53248
	ds_read_b128 v[208:211], v152 offset:54272
	ds_read_b128 v[212:215], v152 offset:55296
	ds_read_b128 v[216:219], v152 offset:56320
	global_load_lds_dwordx4 v194, s[98:99]
	s_add_i32 m0, s0, 0x2000
	s_add_u32 s0, s64, 0x80080
	s_addc_u32 s1, s65, 0
	s_add_i32 s18, s19, s28
	global_load_lds_dwordx4 v130, s[98:99]
	s_mov_b32 m0, s18
	s_nop 0
	global_load_lds_dwordx4 v194, s[0:1]
	s_add_i32 m0, s18, 0x2000
	s_nop 0
	global_load_lds_dwordx4 v130, s[0:1]
	s_mov_b32 m0, s54
	s_nop 0
	global_load_lds_dwordx4 v194, s[100:101]
	s_mov_b32 m0, s57
	s_nop 0
	global_load_lds_dwordx4 v130, s[100:101]
	s_waitcnt vmcnt(8)
	s_waitcnt lgkmcnt(0)
	s_barrier
	s_setprio 0
	s_waitcnt lgkmcnt(0)
	v_mfma_f32_16x16x32_bf16 v[62:65], v[144:147], v[178:181], v[62:65]
	v_mfma_f32_16x16x32_bf16 v[62:65], v[148:151], v[182:185], v[62:65]
	v_mfma_f32_16x16x32_bf16 v[58:61], v[158:161], v[182:185], v[58:61]
	v_mfma_f32_16x16x32_bf16 v[58:61], v[154:157], v[178:181], v[58:61]
	v_mfma_f32_16x16x32_bf16 v[54:57], v[162:165], v[178:181], v[54:57]
	v_mfma_f32_16x16x32_bf16 v[54:57], v[166:169], v[182:185], v[54:57]
	v_mfma_f32_16x16x32_bf16 v[50:53], v[174:177], v[182:185], v[50:53]
	v_mfma_f32_16x16x32_bf16 v[50:53], v[170:173], v[178:181], v[50:53]
	v_mfma_f32_16x16x32_bf16 v[34:37], v[170:173], v[186:189], v[34:37]
	v_mfma_f32_16x16x32_bf16 v[34:37], v[174:177], v[190:193], v[34:37]
	v_mfma_f32_16x16x32_bf16 v[38:41], v[166:169], v[190:193], v[38:41]
	v_mfma_f32_16x16x32_bf16 v[38:41], v[162:165], v[186:189], v[38:41]
	v_mfma_f32_16x16x32_bf16 v[42:45], v[154:157], v[186:189], v[42:45]
	v_mfma_f32_16x16x32_bf16 v[42:45], v[158:161], v[190:193], v[42:45]
	v_mfma_f32_16x16x32_bf16 v[46:49], v[148:151], v[190:193], v[46:49]
	v_mfma_f32_16x16x32_bf16 v[46:49], v[144:147], v[186:189], v[46:49]
	v_mfma_f32_16x16x32_bf16 v[30:33], v[144:147], v[204:207], v[30:33]
	v_mfma_f32_16x16x32_bf16 v[30:33], v[148:151], v[208:211], v[30:33]
	v_mfma_f32_16x16x32_bf16 v[26:29], v[158:161], v[208:211], v[26:29]
	v_mfma_f32_16x16x32_bf16 v[26:29], v[154:157], v[204:207], v[26:29]
	v_mfma_f32_16x16x32_bf16 v[22:25], v[162:165], v[204:207], v[22:25]
	v_mfma_f32_16x16x32_bf16 v[22:25], v[166:169], v[208:211], v[22:25]
	v_mfma_f32_16x16x32_bf16 v[18:21], v[174:177], v[208:211], v[18:21]
	v_mfma_f32_16x16x32_bf16 v[18:21], v[170:173], v[204:207], v[18:21]
	v_mfma_f32_16x16x32_bf16 v[2:5], v[170:173], v[212:215], v[2:5]
	v_mfma_f32_16x16x32_bf16 v[2:5], v[174:177], v[216:219], v[2:5]
	v_mfma_f32_16x16x32_bf16 v[6:9], v[166:169], v[216:219], v[6:9]
	v_mfma_f32_16x16x32_bf16 v[6:9], v[162:165], v[212:215], v[6:9]
	v_mfma_f32_16x16x32_bf16 v[10:13], v[154:157], v[212:215], v[10:13]
	v_mfma_f32_16x16x32_bf16 v[10:13], v[158:161], v[216:219], v[10:13]
	v_mfma_f32_16x16x32_bf16 v[14:17], v[148:151], v[216:219], v[14:17]
	v_mfma_f32_16x16x32_bf16 v[14:17], v[144:147], v[212:215], v[14:17]
	s_setprio 1
	s_barrier
	s_add_i32 s76, s76, 2
	s_add_u32 s62, s62, 0x100
	s_addc_u32 s63, s63, 0
	s_add_u32 s53, s53, 0x100
	s_addc_u32 s58, s58, 0
	s_cmp_gt_u32 s76, 29
	s_cbranch_scc1 .LBB0_584

.Lpeel_disp_gu:
	s_cmp_lg_u32 s76, -2
	s_cbranch_scc1 .LBB0_581
	s_add_u32 s18, s62, 0xfff80080
	s_addc_u32 s19, s63, -1
	s_and_b64 s[0:1], s[64:65], exec
	s_cselect_b32 s71, s22, s19
	s_cselect_b32 s70, s23, s18
	s_cselect_b32 s65, s39, s58
	s_cselect_b32 s64, s47, s53
	s_add_i32 s0, 0, 0x10000
	v_add_u32_e32 v153, s0, v1
	s_add_i32 s18, 0, 0x14000
	ds_read_b128 v[144:147], v153
	ds_read_b128 v[148:151], v153 offset:1024
	ds_read_b128 v[154:157], v153 offset:2048
	ds_read_b128 v[158:161], v153 offset:3072
	v_add_u32_e32 v153, s18, v1
	ds_read_b128 v[162:165], v153
	ds_read_b128 v[166:169], v153 offset:1024
	ds_read_b128 v[170:173], v153 offset:2048
	ds_read_b128 v[174:177], v153 offset:3072
	s_add_i32 m0, s29, 0xc000
	ds_read_b128 v[178:181], v152
	ds_read_b128 v[182:185], v152 offset:1024
	ds_read_b128 v[186:189], v152 offset:2048
	ds_read_b128 v[190:193], v152 offset:3072
	ds_read_b128 v[204:207], v152 offset:4096
	ds_read_b128 v[208:211], v152 offset:5120
	ds_read_b128 v[212:215], v152 offset:6144
	ds_read_b128 v[216:219], v152 offset:7168
	global_load_lds_dwordx4 v136, s[62:63]
	s_add_i32 m0, s29, 0xe000
	s_nop 0
	global_load_lds_dwordx4 v138, s[62:63]
	s_waitcnt vmcnt(8)
	s_waitcnt lgkmcnt(0)
	s_barrier
	s_setprio 0
	s_waitcnt lgkmcnt(0)
	v_mfma_f32_16x16x32_bf16 v[126:129], v[144:147], v[178:181], 0
	v_mfma_f32_16x16x32_bf16 v[126:129], v[148:151], v[182:185], v[126:129]
	v_mfma_f32_16x16x32_bf16 v[122:125], v[158:161], v[182:185], 0
	v_mfma_f32_16x16x32_bf16 v[122:125], v[154:157], v[178:181], v[122:125]
	v_mfma_f32_16x16x32_bf16 v[118:121], v[162:165], v[178:181], 0
	v_mfma_f32_16x16x32_bf16 v[118:121], v[166:169], v[182:185], v[118:121]
	v_mfma_f32_16x16x32_bf16 v[114:117], v[174:177], v[182:185], 0
	v_mfma_f32_16x16x32_bf16 v[114:117], v[170:173], v[178:181], v[114:117]
	v_mfma_f32_16x16x32_bf16 v[98:101], v[170:173], v[186:189], 0
	v_mfma_f32_16x16x32_bf16 v[98:101], v[174:177], v[190:193], v[98:101]
	v_mfma_f32_16x16x32_bf16 v[102:105], v[166:169], v[190:193], 0
	v_mfma_f32_16x16x32_bf16 v[102:105], v[162:165], v[186:189], v[102:105]
	v_mfma_f32_16x16x32_bf16 v[106:109], v[154:157], v[186:189], 0
	v_mfma_f32_16x16x32_bf16 v[106:109], v[158:161], v[190:193], v[106:109]
	v_mfma_f32_16x16x32_bf16 v[110:113], v[148:151], v[190:193], 0
	v_mfma_f32_16x16x32_bf16 v[110:113], v[144:147], v[186:189], v[110:113]
	v_mfma_f32_16x16x32_bf16 v[94:97], v[144:147], v[204:207], 0
	v_mfma_f32_16x16x32_bf16 v[94:97], v[148:151], v[208:211], v[94:97]
	v_mfma_f32_16x16x32_bf16 v[90:93], v[158:161], v[208:211], 0
	v_mfma_f32_16x16x32_bf16 v[90:93], v[154:157], v[204:207], v[90:93]
	v_mfma_f32_16x16x32_bf16 v[86:89], v[162:165], v[204:207], 0
	v_mfma_f32_16x16x32_bf16 v[86:89], v[166:169], v[208:211], v[86:89]
	v_mfma_f32_16x16x32_bf16 v[82:85], v[174:177], v[208:211], 0
	v_mfma_f32_16x16x32_bf16 v[82:85], v[170:173], v[204:207], v[82:85]
	v_mfma_f32_16x16x32_bf16 v[66:69], v[170:173], v[212:215], 0
	v_mfma_f32_16x16x32_bf16 v[66:69], v[174:177], v[216:219], v[66:69]
	v_mfma_f32_16x16x32_bf16 v[70:73], v[166:169], v[216:219], 0
	v_mfma_f32_16x16x32_bf16 v[70:73], v[162:165], v[212:215], v[70:73]
	v_mfma_f32_16x16x32_bf16 v[74:77], v[154:157], v[212:215], 0
	v_mfma_f32_16x16x32_bf16 v[74:77], v[158:161], v[216:219], v[74:77]
	v_mfma_f32_16x16x32_bf16 v[78:81], v[148:151], v[216:219], 0
	v_mfma_f32_16x16x32_bf16 v[78:81], v[144:147], v[212:215], v[78:81]
	s_setprio 1
	s_barrier
	s_add_i32 s0, s0, s28
	s_mov_b32 m0, s0
	ds_read_b128 v[178:181], v152 offset:16384
	ds_read_b128 v[182:185], v152 offset:17408
	ds_read_b128 v[186:189], v152 offset:18432
	ds_read_b128 v[190:193], v152 offset:19456
	ds_read_b128 v[204:207], v152 offset:20480
	ds_read_b128 v[208:211], v152 offset:21504
	ds_read_b128 v[212:215], v152 offset:22528
	ds_read_b128 v[216:219], v152 offset:23552
	global_load_lds_dwordx4 v194, s[64:65]
	s_add_i32 m0, s0, 0x2000
	s_add_u32 s0, s64, 0x80000
	s_addc_u32 s1, s65, 0
	s_add_i32 s18, s18, s28
	global_load_lds_dwordx4 v130, s[64:65]
	s_mov_b32 m0, s18
	s_nop 0
	global_load_lds_dwordx4 v194, s[0:1]
	s_add_i32 m0, s18, 0x2000
	s_nop 0
	global_load_lds_dwordx4 v130, s[0:1]
	s_mov_b32 m0, s29
	s_nop 0
	global_load_lds_dwordx4 v194, s[70:71]
	s_mov_b32 m0, s31
	s_nop 0
	global_load_lds_dwordx4 v130, s[70:71]
	s_waitcnt vmcnt(8)
	s_waitcnt lgkmcnt(0)
	s_barrier
	s_setprio 0
	s_waitcnt lgkmcnt(0)
	v_mfma_f32_16x16x32_bf16 v[62:65], v[144:147], v[178:181], 0
	v_mfma_f32_16x16x32_bf16 v[62:65], v[148:151], v[182:185], v[62:65]
	v_mfma_f32_16x16x32_bf16 v[58:61], v[158:161], v[182:185], 0
	v_mfma_f32_16x16x32_bf16 v[58:61], v[154:157], v[178:181], v[58:61]
	v_mfma_f32_16x16x32_bf16 v[54:57], v[162:165], v[178:181], 0
	v_mfma_f32_16x16x32_bf16 v[54:57], v[166:169], v[182:185], v[54:57]
	v_mfma_f32_16x16x32_bf16 v[50:53], v[174:177], v[182:185], 0
	v_mfma_f32_16x16x32_bf16 v[50:53], v[170:173], v[178:181], v[50:53]
	v_mfma_f32_16x16x32_bf16 v[34:37], v[170:173], v[186:189], 0
	v_mfma_f32_16x16x32_bf16 v[34:37], v[174:177], v[190:193], v[34:37]
	v_mfma_f32_16x16x32_bf16 v[38:41], v[166:169], v[190:193], 0
	v_mfma_f32_16x16x32_bf16 v[38:41], v[162:165], v[186:189], v[38:41]
	v_mfma_f32_16x16x32_bf16 v[42:45], v[154:157], v[186:189], 0
	v_mfma_f32_16x16x32_bf16 v[42:45], v[158:161], v[190:193], v[42:45]
	v_mfma_f32_16x16x32_bf16 v[46:49], v[148:151], v[190:193], 0
	v_mfma_f32_16x16x32_bf16 v[46:49], v[144:147], v[186:189], v[46:49]
	v_mfma_f32_16x16x32_bf16 v[30:33], v[144:147], v[204:207], 0
	v_mfma_f32_16x16x32_bf16 v[30:33], v[148:151], v[208:211], v[30:33]
	v_mfma_f32_16x16x32_bf16 v[26:29], v[158:161], v[208:211], 0
	v_mfma_f32_16x16x32_bf16 v[26:29], v[154:157], v[204:207], v[26:29]
	v_mfma_f32_16x16x32_bf16 v[22:25], v[162:165], v[204:207], 0
	v_mfma_f32_16x16x32_bf16 v[22:25], v[166:169], v[208:211], v[22:25]
	v_mfma_f32_16x16x32_bf16 v[18:21], v[174:177], v[208:211], 0
	v_mfma_f32_16x16x32_bf16 v[18:21], v[170:173], v[204:207], v[18:21]
	v_mfma_f32_16x16x32_bf16 v[2:5], v[170:173], v[212:215], 0
	v_mfma_f32_16x16x32_bf16 v[2:5], v[174:177], v[216:219], v[2:5]
	v_mfma_f32_16x16x32_bf16 v[6:9], v[166:169], v[216:219], 0
	v_mfma_f32_16x16x32_bf16 v[6:9], v[162:165], v[212:215], v[6:9]
	v_mfma_f32_16x16x32_bf16 v[10:13], v[154:157], v[212:215], 0
	v_mfma_f32_16x16x32_bf16 v[10:13], v[158:161], v[216:219], v[10:13]
	v_mfma_f32_16x16x32_bf16 v[14:17], v[148:151], v[216:219], 0
	v_mfma_f32_16x16x32_bf16 v[14:17], v[144:147], v[212:215], v[14:17]
	s_setprio 1
	s_barrier
	s_add_i32 s18, 0, 0x18000
	v_add_u32_e32 v153, s18, v1
	s_add_i32 s19, 0, 0x1c000
	ds_read_b128 v[144:147], v153
	ds_read_b128 v[148:151], v153 offset:1024
	ds_read_b128 v[154:157], v153 offset:2048
	ds_read_b128 v[158:161], v153 offset:3072
	v_add_u32_e32 v153, s19, v1
	ds_read_b128 v[162:165], v153
	ds_read_b128 v[166:169], v153 offset:1024
	ds_read_b128 v[170:173], v153 offset:2048
	ds_read_b128 v[174:177], v153 offset:3072
	s_add_u32 s0, s70, 0x80000
	s_addc_u32 s1, s71, 0
	s_mov_b32 m0, s33
	ds_read_b128 v[178:181], v152 offset:32768
	ds_read_b128 v[182:185], v152 offset:33792
	ds_read_b128 v[186:189], v152 offset:34816
	ds_read_b128 v[190:193], v152 offset:35840
	ds_read_b128 v[204:207], v152 offset:36864
	ds_read_b128 v[208:211], v152 offset:37888
	ds_read_b128 v[212:215], v152 offset:38912
	ds_read_b128 v[216:219], v152 offset:39936
	global_load_lds_dwordx4 v194, s[0:1]
	s_mov_b32 m0, s40
	s_nop 0
	global_load_lds_dwordx4 v130, s[0:1]
	s_waitcnt vmcnt(8)
	s_waitcnt lgkmcnt(0)
	s_barrier
	s_setprio 0
	s_waitcnt lgkmcnt(0)
	v_mfma_f32_16x16x32_bf16 v[126:129], v[144:147], v[178:181], v[126:129]
	v_mfma_f32_16x16x32_bf16 v[126:129], v[148:151], v[182:185], v[126:129]
	v_mfma_f32_16x16x32_bf16 v[122:125], v[158:161], v[182:185], v[122:125]
	v_mfma_f32_16x16x32_bf16 v[122:125], v[154:157], v[178:181], v[122:125]
	v_mfma_f32_16x16x32_bf16 v[118:121], v[162:165], v[178:181], v[118:121]
	v_mfma_f32_16x16x32_bf16 v[118:121], v[166:169], v[182:185], v[118:121]
	v_mfma_f32_16x16x32_bf16 v[114:117], v[174:177], v[182:185], v[114:117]
	v_mfma_f32_16x16x32_bf16 v[114:117], v[170:173], v[178:181], v[114:117]
	v_mfma_f32_16x16x32_bf16 v[98:101], v[170:173], v[186:189], v[98:101]
	v_mfma_f32_16x16x32_bf16 v[98:101], v[174:177], v[190:193], v[98:101]
	v_mfma_f32_16x16x32_bf16 v[102:105], v[166:169], v[190:193], v[102:105]
	v_mfma_f32_16x16x32_bf16 v[102:105], v[162:165], v[186:189], v[102:105]
	v_mfma_f32_16x16x32_bf16 v[106:109], v[154:157], v[186:189], v[106:109]
	v_mfma_f32_16x16x32_bf16 v[106:109], v[158:161], v[190:193], v[106:109]
	v_mfma_f32_16x16x32_bf16 v[110:113], v[148:151], v[190:193], v[110:113]
	v_mfma_f32_16x16x32_bf16 v[110:113], v[144:147], v[186:189], v[110:113]
	v_mfma_f32_16x16x32_bf16 v[94:97], v[144:147], v[204:207], v[94:97]
	v_mfma_f32_16x16x32_bf16 v[94:97], v[148:151], v[208:211], v[94:97]
	v_mfma_f32_16x16x32_bf16 v[90:93], v[158:161], v[208:211], v[90:93]
	v_mfma_f32_16x16x32_bf16 v[90:93], v[154:157], v[204:207], v[90:93]
	v_mfma_f32_16x16x32_bf16 v[86:89], v[162:165], v[204:207], v[86:89]
	v_mfma_f32_16x16x32_bf16 v[86:89], v[166:169], v[208:211], v[86:89]
	v_mfma_f32_16x16x32_bf16 v[82:85], v[174:177], v[208:211], v[82:85]
	v_mfma_f32_16x16x32_bf16 v[82:85], v[170:173], v[204:207], v[82:85]
	v_mfma_f32_16x16x32_bf16 v[66:69], v[170:173], v[212:215], v[66:69]
	v_mfma_f32_16x16x32_bf16 v[66:69], v[174:177], v[216:219], v[66:69]
	v_mfma_f32_16x16x32_bf16 v[70:73], v[166:169], v[216:219], v[70:73]
	v_mfma_f32_16x16x32_bf16 v[70:73], v[162:165], v[212:215], v[70:73]
	v_mfma_f32_16x16x32_bf16 v[74:77], v[154:157], v[212:215], v[74:77]
	v_mfma_f32_16x16x32_bf16 v[74:77], v[158:161], v[216:219], v[74:77]
	v_mfma_f32_16x16x32_bf16 v[78:81], v[148:151], v[216:219], v[78:81]
	v_mfma_f32_16x16x32_bf16 v[78:81], v[144:147], v[212:215], v[78:81]
	s_setprio 1
	s_barrier
	s_add_u32 s98, s64, 0x80
	s_addc_u32 s99, s65, 0
	s_add_u32 s100, s70, 0x80
	s_addc_u32 s101, s71, 0
	s_add_i32 s0, s18, s28
	s_mov_b32 m0, s0
	ds_read_b128 v[178:181], v152 offset:49152
	ds_read_b128 v[182:185], v152 offset:50176
	ds_read_b128 v[186:189], v152 offset:51200
	ds_read_b128 v[190:193], v152 offset:52224
	ds_read_b128 v[204:207], v152 offset:53248
	ds_read_b128 v[208:211], v152 offset:54272
	ds_read_b128 v[212:215], v152 offset:55296
	ds_read_b128 v[216:219], v152 offset:56320
	global_load_lds_dwordx4 v194, s[98:99]
	s_add_i32 m0, s0, 0x2000
	s_add_u32 s0, s64, 0x80080
	s_addc_u32 s1, s65, 0
	s_add_i32 s18, s19, s28
	global_load_lds_dwordx4 v130, s[98:99]
	s_mov_b32 m0, s18
	s_nop 0
	global_load_lds_dwordx4 v194, s[0:1]
	s_add_i32 m0, s18, 0x2000
	s_nop 0
	global_load_lds_dwordx4 v130, s[0:1]
	s_mov_b32 m0, s54
	s_nop 0
	global_load_lds_dwordx4 v194, s[100:101]
	s_mov_b32 m0, s57
	s_nop 0
	global_load_lds_dwordx4 v130, s[100:101]
	s_waitcnt vmcnt(8)
	s_waitcnt lgkmcnt(0)
	s_barrier
	s_setprio 0
	s_waitcnt lgkmcnt(0)
	v_mfma_f32_16x16x32_bf16 v[62:65], v[144:147], v[178:181], v[62:65]
	v_mfma_f32_16x16x32_bf16 v[62:65], v[148:151], v[182:185], v[62:65]
	v_mfma_f32_16x16x32_bf16 v[58:61], v[158:161], v[182:185], v[58:61]
	v_mfma_f32_16x16x32_bf16 v[58:61], v[154:157], v[178:181], v[58:61]
	v_mfma_f32_16x16x32_bf16 v[54:57], v[162:165], v[178:181], v[54:57]
	v_mfma_f32_16x16x32_bf16 v[54:57], v[166:169], v[182:185], v[54:57]
	v_mfma_f32_16x16x32_bf16 v[50:53], v[174:177], v[182:185], v[50:53]
	v_mfma_f32_16x16x32_bf16 v[50:53], v[170:173], v[178:181], v[50:53]
	v_mfma_f32_16x16x32_bf16 v[34:37], v[170:173], v[186:189], v[34:37]
	v_mfma_f32_16x16x32_bf16 v[34:37], v[174:177], v[190:193], v[34:37]
	v_mfma_f32_16x16x32_bf16 v[38:41], v[166:169], v[190:193], v[38:41]
	v_mfma_f32_16x16x32_bf16 v[38:41], v[162:165], v[186:189], v[38:41]
	v_mfma_f32_16x16x32_bf16 v[42:45], v[154:157], v[186:189], v[42:45]
	v_mfma_f32_16x16x32_bf16 v[42:45], v[158:161], v[190:193], v[42:45]
	v_mfma_f32_16x16x32_bf16 v[46:49], v[148:151], v[190:193], v[46:49]
	v_mfma_f32_16x16x32_bf16 v[46:49], v[144:147], v[186:189], v[46:49]
	v_mfma_f32_16x16x32_bf16 v[30:33], v[144:147], v[204:207], v[30:33]
	v_mfma_f32_16x16x32_bf16 v[30:33], v[148:151], v[208:211], v[30:33]
	v_mfma_f32_16x16x32_bf16 v[26:29], v[158:161], v[208:211], v[26:29]
	v_mfma_f32_16x16x32_bf16 v[26:29], v[154:157], v[204:207], v[26:29]
	v_mfma_f32_16x16x32_bf16 v[22:25], v[162:165], v[204:207], v[22:25]
	v_mfma_f32_16x16x32_bf16 v[22:25], v[166:169], v[208:211], v[22:25]
	v_mfma_f32_16x16x32_bf16 v[18:21], v[174:177], v[208:211], v[18:21]
	v_mfma_f32_16x16x32_bf16 v[18:21], v[170:173], v[204:207], v[18:21]
	v_mfma_f32_16x16x32_bf16 v[2:5], v[170:173], v[212:215], v[2:5]
	v_mfma_f32_16x16x32_bf16 v[2:5], v[174:177], v[216:219], v[2:5]
	v_mfma_f32_16x16x32_bf16 v[6:9], v[166:169], v[216:219], v[6:9]
	v_mfma_f32_16x16x32_bf16 v[6:9], v[162:165], v[212:215], v[6:9]
	v_mfma_f32_16x16x32_bf16 v[10:13], v[154:157], v[212:215], v[10:13]
	v_mfma_f32_16x16x32_bf16 v[10:13], v[158:161], v[216:219], v[10:13]
	v_mfma_f32_16x16x32_bf16 v[14:17], v[148:151], v[216:219], v[14:17]
	v_mfma_f32_16x16x32_bf16 v[14:17], v[144:147], v[212:215], v[14:17]
	s_setprio 1
	s_barrier
	s_add_i32 s76, s76, 2
	s_add_u32 s62, s62, 0x100
	s_addc_u32 s63, s63, 0
	s_add_u32 s53, s53, 0x100
	s_addc_u32 s58, s58, 0
	s_cmp_gt_u32 s76, 29
	s_cbranch_scc1 .LBB0_584
	s_branch .LBB0_582

.LBB0_645:
	s_add_u32 s64, s8, 0x100
	s_addc_u32 s65, s9, 0
	s_and_b64 s[0:1], s[70:71], exec
	s_cselect_b32 s77, s63, s65
	s_cselect_b32 s76, s62, s64
	s_cselect_b32 s71, s85, s23
	s_cselect_b32 s70, s84, s7
	s_add_i32 s0, 0, 0x10000
	s_add_i32 s18, 0, 0x14000
	v_add_u32_e32 v106, s0, v1
	v_add_u32_e32 v154, s18, v1
	ds_read_b128 v[70:73], v106
	ds_read_b128 v[82:85], v106 offset:1024
	ds_read_b128 v[94:97], v106 offset:2048
	ds_read_b128 v[106:109], v106 offset:3072
	ds_read_b128 v[118:121], v154
	ds_read_b128 v[130:133], v154 offset:1024
	ds_read_b128 v[142:145], v154 offset:2048
	ds_read_b128 v[154:157], v154 offset:3072
	s_add_i32 m0, s29, 0xc000
	ds_read_b128 v[158:161], v237
	ds_read_b128 v[170:173], v237 offset:1024
	ds_read_b128 v[174:177], v237 offset:2048
	ds_read_b128 v[178:181], v237 offset:3072
	ds_read_b128 v[182:185], v237 offset:4096
	ds_read_b128 v[186:189], v237 offset:5120
	ds_read_b128 v[210:213], v237 offset:6144
	ds_read_b128 v[214:217], v237 offset:7168
	global_load_lds_dwordx4 v206, s[8:9]
	s_add_i32 m0, s29, 0xe000
	s_nop 0
	global_load_lds_dwordx4 v208, s[8:9]
	s_waitcnt vmcnt(8)
	s_waitcnt lgkmcnt(0)
	s_barrier
	s_setprio 0
	s_waitcnt lgkmcnt(0)
	v_mfma_f32_16x16x32_bf16 v[166:169], v[70:73], v[158:161], v[166:169]
	v_mfma_f32_16x16x32_bf16 v[166:169], v[82:85], v[170:173], v[166:169]
	v_mfma_f32_16x16x32_bf16 v[162:165], v[106:109], v[170:173], v[162:165]
	v_mfma_f32_16x16x32_bf16 v[162:165], v[94:97], v[158:161], v[162:165]
	v_mfma_f32_16x16x32_bf16 v[150:153], v[118:121], v[158:161], v[150:153]
	v_mfma_f32_16x16x32_bf16 v[150:153], v[130:133], v[170:173], v[150:153]
	v_mfma_f32_16x16x32_bf16 v[146:149], v[154:157], v[170:173], v[146:149]
	v_mfma_f32_16x16x32_bf16 v[146:149], v[142:145], v[158:161], v[146:149]
	v_mfma_f32_16x16x32_bf16 v[122:125], v[142:145], v[174:177], v[122:125]
	v_mfma_f32_16x16x32_bf16 v[122:125], v[154:157], v[178:181], v[122:125]
	v_mfma_f32_16x16x32_bf16 v[126:129], v[130:133], v[178:181], v[126:129]
	v_mfma_f32_16x16x32_bf16 v[126:129], v[118:121], v[174:177], v[126:129]
	v_mfma_f32_16x16x32_bf16 v[134:137], v[94:97], v[174:177], v[134:137]
	v_mfma_f32_16x16x32_bf16 v[134:137], v[106:109], v[178:181], v[134:137]
	v_mfma_f32_16x16x32_bf16 v[138:141], v[82:85], v[178:181], v[138:141]
	v_mfma_f32_16x16x32_bf16 v[138:141], v[70:73], v[174:177], v[138:141]
	v_mfma_f32_16x16x32_bf16 v[114:117], v[70:73], v[182:185], v[114:117]
	v_mfma_f32_16x16x32_bf16 v[114:117], v[82:85], v[186:189], v[114:117]
	v_mfma_f32_16x16x32_bf16 v[110:113], v[106:109], v[186:189], v[110:113]
	v_mfma_f32_16x16x32_bf16 v[110:113], v[94:97], v[182:185], v[110:113]
	v_mfma_f32_16x16x32_bf16 v[102:105], v[118:121], v[182:185], v[102:105]
	v_mfma_f32_16x16x32_bf16 v[102:105], v[130:133], v[186:189], v[102:105]
	v_mfma_f32_16x16x32_bf16 v[98:101], v[154:157], v[186:189], v[98:101]
	v_mfma_f32_16x16x32_bf16 v[98:101], v[142:145], v[182:185], v[98:101]
	v_mfma_f32_16x16x32_bf16 v[74:77], v[142:145], v[210:213], v[74:77]
	v_mfma_f32_16x16x32_bf16 v[74:77], v[154:157], v[214:217], v[74:77]
	v_mfma_f32_16x16x32_bf16 v[78:81], v[130:133], v[214:217], v[78:81]
	v_mfma_f32_16x16x32_bf16 v[78:81], v[118:121], v[210:213], v[78:81]
	v_mfma_f32_16x16x32_bf16 v[86:89], v[94:97], v[210:213], v[86:89]
	v_mfma_f32_16x16x32_bf16 v[86:89], v[106:109], v[214:217], v[86:89]
	v_mfma_f32_16x16x32_bf16 v[90:93], v[82:85], v[214:217], v[90:93]
	v_mfma_f32_16x16x32_bf16 v[90:93], v[70:73], v[210:213], v[90:93]
	s_setprio 1
	s_barrier
	s_add_i32 s0, s0, s28
	s_mov_b32 m0, s0
	ds_read_b128 v[158:161], v237 offset:16384
	ds_read_b128 v[170:173], v237 offset:17408
	ds_read_b128 v[174:177], v237 offset:18432
	ds_read_b128 v[178:181], v237 offset:19456
	ds_read_b128 v[182:185], v237 offset:20480
	ds_read_b128 v[186:189], v237 offset:21504
	ds_read_b128 v[210:213], v237 offset:22528
	ds_read_b128 v[214:217], v237 offset:23552
	global_load_lds_dwordx4 v192, s[70:71]
	s_add_i32 m0, s0, 0x2000
	s_add_u32 s0, s70, 0x160000
	s_addc_u32 s1, s71, 0
	s_add_i32 s8, s18, s28
	global_load_lds_dwordx4 v190, s[70:71]
	s_mov_b32 m0, s8
	s_nop 0
	global_load_lds_dwordx4 v192, s[0:1]
	s_add_i32 m0, s8, 0x2000
	s_nop 0
	global_load_lds_dwordx4 v190, s[0:1]
	s_mov_b32 m0, s29
	s_nop 0
	global_load_lds_dwordx4 v192, s[76:77]
	s_mov_b32 m0, s31
	s_nop 0
	global_load_lds_dwordx4 v190, s[76:77]
	s_waitcnt vmcnt(8)
	s_waitcnt lgkmcnt(0)
	s_barrier
	s_setprio 0
	s_waitcnt lgkmcnt(0)
	v_mfma_f32_16x16x32_bf16 v[62:65], v[70:73], v[158:161], v[62:65]
	v_mfma_f32_16x16x32_bf16 v[62:65], v[82:85], v[170:173], v[62:65]
	v_mfma_f32_16x16x32_bf16 v[58:61], v[106:109], v[170:173], v[58:61]
	v_mfma_f32_16x16x32_bf16 v[58:61], v[94:97], v[158:161], v[58:61]
	v_mfma_f32_16x16x32_bf16 v[54:57], v[118:121], v[158:161], v[54:57]
	v_mfma_f32_16x16x32_bf16 v[54:57], v[130:133], v[170:173], v[54:57]
	v_mfma_f32_16x16x32_bf16 v[50:53], v[154:157], v[170:173], v[50:53]
	v_mfma_f32_16x16x32_bf16 v[50:53], v[142:145], v[158:161], v[50:53]
	v_mfma_f32_16x16x32_bf16 v[34:37], v[142:145], v[174:177], v[34:37]
	v_mfma_f32_16x16x32_bf16 v[34:37], v[154:157], v[178:181], v[34:37]
	v_mfma_f32_16x16x32_bf16 v[38:41], v[130:133], v[178:181], v[38:41]
	v_mfma_f32_16x16x32_bf16 v[38:41], v[118:121], v[174:177], v[38:41]
	v_mfma_f32_16x16x32_bf16 v[42:45], v[94:97], v[174:177], v[42:45]
	v_mfma_f32_16x16x32_bf16 v[42:45], v[106:109], v[178:181], v[42:45]
	v_mfma_f32_16x16x32_bf16 v[46:49], v[82:85], v[178:181], v[46:49]
	v_mfma_f32_16x16x32_bf16 v[46:49], v[70:73], v[174:177], v[46:49]
	v_mfma_f32_16x16x32_bf16 v[30:33], v[70:73], v[182:185], v[30:33]
	v_mfma_f32_16x16x32_bf16 v[30:33], v[82:85], v[186:189], v[30:33]
	v_mfma_f32_16x16x32_bf16 v[26:29], v[106:109], v[186:189], v[26:29]
	v_mfma_f32_16x16x32_bf16 v[26:29], v[94:97], v[182:185], v[26:29]
	v_mfma_f32_16x16x32_bf16 v[22:25], v[118:121], v[182:185], v[22:25]
	v_mfma_f32_16x16x32_bf16 v[22:25], v[130:133], v[186:189], v[22:25]
	v_mfma_f32_16x16x32_bf16 v[18:21], v[154:157], v[186:189], v[18:21]
	v_mfma_f32_16x16x32_bf16 v[18:21], v[142:145], v[182:185], v[18:21]
	v_mfma_f32_16x16x32_bf16 v[2:5], v[142:145], v[210:213], v[2:5]
	v_mfma_f32_16x16x32_bf16 v[2:5], v[154:157], v[214:217], v[2:5]
	v_mfma_f32_16x16x32_bf16 v[6:9], v[130:133], v[214:217], v[6:9]
	v_mfma_f32_16x16x32_bf16 v[6:9], v[118:121], v[210:213], v[6:9]
	v_mfma_f32_16x16x32_bf16 v[10:13], v[94:97], v[210:213], v[10:13]
	v_mfma_f32_16x16x32_bf16 v[10:13], v[106:109], v[214:217], v[10:13]
	v_mfma_f32_16x16x32_bf16 v[14:17], v[82:85], v[214:217], v[14:17]
	v_mfma_f32_16x16x32_bf16 v[14:17], v[70:73], v[210:213], v[14:17]
	s_setprio 1
	s_barrier
	s_add_i32 s8, 0, 0x18000
	s_add_i32 s9, 0, 0x1c000
	v_add_u32_e32 v106, s8, v1
	v_add_u32_e32 v154, s9, v1
	ds_read_b128 v[70:73], v106
	ds_read_b128 v[82:85], v106 offset:1024
	ds_read_b128 v[94:97], v106 offset:2048
	ds_read_b128 v[106:109], v106 offset:3072
	ds_read_b128 v[118:121], v154
	ds_read_b128 v[130:133], v154 offset:1024
	ds_read_b128 v[142:145], v154 offset:2048
	ds_read_b128 v[154:157], v154 offset:3072
	s_add_u32 s0, s76, 0x160000
	s_addc_u32 s1, s77, 0
	s_mov_b32 m0, s33
	ds_read_b128 v[158:161], v237 offset:32768
	ds_read_b128 v[170:173], v237 offset:33792
	ds_read_b128 v[174:177], v237 offset:34816
	ds_read_b128 v[178:181], v237 offset:35840
	ds_read_b128 v[182:185], v237 offset:36864
	ds_read_b128 v[186:189], v237 offset:37888
	ds_read_b128 v[210:213], v237 offset:38912
	ds_read_b128 v[214:217], v237 offset:39936
	global_load_lds_dwordx4 v192, s[0:1]
	s_mov_b32 m0, s43
	s_nop 0
	global_load_lds_dwordx4 v190, s[0:1]
	s_waitcnt vmcnt(8)
	s_waitcnt lgkmcnt(0)
	s_barrier
	s_setprio 0
	s_waitcnt lgkmcnt(0)
	v_mfma_f32_16x16x32_bf16 v[166:169], v[70:73], v[158:161], v[166:169]
	v_mfma_f32_16x16x32_bf16 v[166:169], v[82:85], v[170:173], v[166:169]
	v_mfma_f32_16x16x32_bf16 v[162:165], v[106:109], v[170:173], v[162:165]
	v_mfma_f32_16x16x32_bf16 v[162:165], v[94:97], v[158:161], v[162:165]
	v_mfma_f32_16x16x32_bf16 v[150:153], v[118:121], v[158:161], v[150:153]
	v_mfma_f32_16x16x32_bf16 v[150:153], v[130:133], v[170:173], v[150:153]
	v_mfma_f32_16x16x32_bf16 v[146:149], v[154:157], v[170:173], v[146:149]
	v_mfma_f32_16x16x32_bf16 v[146:149], v[142:145], v[158:161], v[146:149]
	v_mfma_f32_16x16x32_bf16 v[122:125], v[142:145], v[174:177], v[122:125]
	v_mfma_f32_16x16x32_bf16 v[122:125], v[154:157], v[178:181], v[122:125]
	v_mfma_f32_16x16x32_bf16 v[126:129], v[130:133], v[178:181], v[126:129]
	v_mfma_f32_16x16x32_bf16 v[126:129], v[118:121], v[174:177], v[126:129]
	v_mfma_f32_16x16x32_bf16 v[134:137], v[94:97], v[174:177], v[134:137]
	v_mfma_f32_16x16x32_bf16 v[134:137], v[106:109], v[178:181], v[134:137]
	v_mfma_f32_16x16x32_bf16 v[138:141], v[82:85], v[178:181], v[138:141]
	v_mfma_f32_16x16x32_bf16 v[138:141], v[70:73], v[174:177], v[138:141]
	v_mfma_f32_16x16x32_bf16 v[114:117], v[70:73], v[182:185], v[114:117]
	v_mfma_f32_16x16x32_bf16 v[114:117], v[82:85], v[186:189], v[114:117]
	v_mfma_f32_16x16x32_bf16 v[110:113], v[106:109], v[186:189], v[110:113]
	v_mfma_f32_16x16x32_bf16 v[110:113], v[94:97], v[182:185], v[110:113]
	v_mfma_f32_16x16x32_bf16 v[102:105], v[118:121], v[182:185], v[102:105]
	v_mfma_f32_16x16x32_bf16 v[102:105], v[130:133], v[186:189], v[102:105]
	v_mfma_f32_16x16x32_bf16 v[98:101], v[154:157], v[186:189], v[98:101]
	v_mfma_f32_16x16x32_bf16 v[98:101], v[142:145], v[182:185], v[98:101]
	v_mfma_f32_16x16x32_bf16 v[74:77], v[142:145], v[210:213], v[74:77]
	v_mfma_f32_16x16x32_bf16 v[74:77], v[154:157], v[214:217], v[74:77]
	v_mfma_f32_16x16x32_bf16 v[78:81], v[130:133], v[214:217], v[78:81]
	v_mfma_f32_16x16x32_bf16 v[78:81], v[118:121], v[210:213], v[78:81]
	v_mfma_f32_16x16x32_bf16 v[86:89], v[94:97], v[210:213], v[86:89]
	v_mfma_f32_16x16x32_bf16 v[86:89], v[106:109], v[214:217], v[86:89]
	v_mfma_f32_16x16x32_bf16 v[90:93], v[82:85], v[214:217], v[90:93]
	v_mfma_f32_16x16x32_bf16 v[90:93], v[70:73], v[210:213], v[90:93]
	s_setprio 1
	s_barrier
	s_add_u32 s98, s70, 0x80
	s_addc_u32 s99, s71, 0
	s_add_u32 s100, s76, 0x80
	s_addc_u32 s101, s77, 0
	s_add_i32 s0, s8, s28
	s_mov_b32 m0, s0
	ds_read_b128 v[158:161], v237 offset:49152
	ds_read_b128 v[170:173], v237 offset:50176
	ds_read_b128 v[174:177], v237 offset:51200
	ds_read_b128 v[178:181], v237 offset:52224
	ds_read_b128 v[182:185], v237 offset:53248
	ds_read_b128 v[186:189], v237 offset:54272
	ds_read_b128 v[210:213], v237 offset:55296
	ds_read_b128 v[214:217], v237 offset:56320
	global_load_lds_dwordx4 v192, s[98:99]
	s_add_i32 m0, s0, 0x2000
	s_add_u32 s0, s70, 0x160080
	s_addc_u32 s1, s71, 0
	s_add_i32 s8, s9, s28
	global_load_lds_dwordx4 v190, s[98:99]
	s_mov_b32 m0, s8
	s_nop 0
	global_load_lds_dwordx4 v192, s[0:1]
	s_add_i32 m0, s8, 0x2000
	s_nop 0
	global_load_lds_dwordx4 v190, s[0:1]
	s_mov_b32 m0, s68
	s_nop 0
	global_load_lds_dwordx4 v192, s[100:101]
	s_mov_b32 m0, s79
	s_nop 0
	global_load_lds_dwordx4 v190, s[100:101]
	s_waitcnt vmcnt(8)
	s_waitcnt lgkmcnt(0)
	s_barrier
	s_setprio 0
	s_waitcnt lgkmcnt(0)
	v_mfma_f32_16x16x32_bf16 v[62:65], v[70:73], v[158:161], v[62:65]
	v_mfma_f32_16x16x32_bf16 v[62:65], v[82:85], v[170:173], v[62:65]
	v_mfma_f32_16x16x32_bf16 v[58:61], v[106:109], v[170:173], v[58:61]
	v_mfma_f32_16x16x32_bf16 v[58:61], v[94:97], v[158:161], v[58:61]
	v_mfma_f32_16x16x32_bf16 v[54:57], v[118:121], v[158:161], v[54:57]
	v_mfma_f32_16x16x32_bf16 v[54:57], v[130:133], v[170:173], v[54:57]
	v_mfma_f32_16x16x32_bf16 v[50:53], v[154:157], v[170:173], v[50:53]
	v_mfma_f32_16x16x32_bf16 v[50:53], v[142:145], v[158:161], v[50:53]
	v_mfma_f32_16x16x32_bf16 v[34:37], v[142:145], v[174:177], v[34:37]
	v_mfma_f32_16x16x32_bf16 v[34:37], v[154:157], v[178:181], v[34:37]
	v_mfma_f32_16x16x32_bf16 v[38:41], v[130:133], v[178:181], v[38:41]
	v_mfma_f32_16x16x32_bf16 v[38:41], v[118:121], v[174:177], v[38:41]
	v_mfma_f32_16x16x32_bf16 v[42:45], v[94:97], v[174:177], v[42:45]
	v_mfma_f32_16x16x32_bf16 v[42:45], v[106:109], v[178:181], v[42:45]
	v_mfma_f32_16x16x32_bf16 v[46:49], v[82:85], v[178:181], v[46:49]
	v_mfma_f32_16x16x32_bf16 v[46:49], v[70:73], v[174:177], v[46:49]
	v_mfma_f32_16x16x32_bf16 v[30:33], v[70:73], v[182:185], v[30:33]
	v_mfma_f32_16x16x32_bf16 v[30:33], v[82:85], v[186:189], v[30:33]
	v_mfma_f32_16x16x32_bf16 v[26:29], v[106:109], v[186:189], v[26:29]
	v_mfma_f32_16x16x32_bf16 v[26:29], v[94:97], v[182:185], v[26:29]
	v_mfma_f32_16x16x32_bf16 v[22:25], v[118:121], v[182:185], v[22:25]
	v_mfma_f32_16x16x32_bf16 v[22:25], v[130:133], v[186:189], v[22:25]
	v_mfma_f32_16x16x32_bf16 v[18:21], v[154:157], v[186:189], v[18:21]
	v_mfma_f32_16x16x32_bf16 v[18:21], v[142:145], v[182:185], v[18:21]
	v_mfma_f32_16x16x32_bf16 v[2:5], v[142:145], v[210:213], v[2:5]
	v_mfma_f32_16x16x32_bf16 v[2:5], v[154:157], v[214:217], v[2:5]
	v_mfma_f32_16x16x32_bf16 v[6:9], v[130:133], v[214:217], v[6:9]
	v_mfma_f32_16x16x32_bf16 v[6:9], v[118:121], v[210:213], v[6:9]
	v_mfma_f32_16x16x32_bf16 v[10:13], v[94:97], v[210:213], v[10:13]
	v_mfma_f32_16x16x32_bf16 v[10:13], v[106:109], v[214:217], v[10:13]
	v_mfma_f32_16x16x32_bf16 v[14:17], v[82:85], v[214:217], v[14:17]
	v_mfma_f32_16x16x32_bf16 v[14:17], v[70:73], v[210:213], v[14:17]
	s_setprio 1
	s_barrier
	s_add_i32 s41, s41, 2
	s_add_u32 s7, s7, 0x100
	s_addc_u32 s23, s23, 0
	s_cmpk_gt_u32 s41, 0x55
	s_mov_b64 s[8:9], s[64:65]
	s_cbranch_scc1 .LBB0_648

.Lpeel_disp_down:
	s_cmp_lg_u32 s41, -2
	s_cbranch_scc1 .LBB0_645
	s_add_u32 s64, s8, 0x100
	s_addc_u32 s65, s9, 0
	s_and_b64 s[0:1], s[70:71], exec
	s_cselect_b32 s77, s63, s65
	s_cselect_b32 s76, s62, s64
	s_cselect_b32 s71, s85, s23
	s_cselect_b32 s70, s84, s7
	s_add_i32 s0, 0, 0x10000
	s_add_i32 s18, 0, 0x14000
	v_add_u32_e32 v106, s0, v1
	v_add_u32_e32 v154, s18, v1
	ds_read_b128 v[70:73], v106
	ds_read_b128 v[82:85], v106 offset:1024
	ds_read_b128 v[94:97], v106 offset:2048
	ds_read_b128 v[106:109], v106 offset:3072
	ds_read_b128 v[118:121], v154
	ds_read_b128 v[130:133], v154 offset:1024
	ds_read_b128 v[142:145], v154 offset:2048
	ds_read_b128 v[154:157], v154 offset:3072
	s_add_i32 m0, s29, 0xc000
	ds_read_b128 v[158:161], v237
	ds_read_b128 v[170:173], v237 offset:1024
	ds_read_b128 v[174:177], v237 offset:2048
	ds_read_b128 v[178:181], v237 offset:3072
	ds_read_b128 v[182:185], v237 offset:4096
	ds_read_b128 v[186:189], v237 offset:5120
	ds_read_b128 v[210:213], v237 offset:6144
	ds_read_b128 v[214:217], v237 offset:7168
	global_load_lds_dwordx4 v206, s[8:9]
	s_add_i32 m0, s29, 0xe000
	s_nop 0
	global_load_lds_dwordx4 v208, s[8:9]
	s_waitcnt vmcnt(8)
	s_waitcnt lgkmcnt(0)
	s_barrier
	s_setprio 0
	s_waitcnt lgkmcnt(0)
	v_mfma_f32_16x16x32_bf16 v[166:169], v[70:73], v[158:161], 0
	v_mfma_f32_16x16x32_bf16 v[166:169], v[82:85], v[170:173], v[166:169]
	v_mfma_f32_16x16x32_bf16 v[162:165], v[106:109], v[170:173], 0
	v_mfma_f32_16x16x32_bf16 v[162:165], v[94:97], v[158:161], v[162:165]
	v_mfma_f32_16x16x32_bf16 v[150:153], v[118:121], v[158:161], 0
	v_mfma_f32_16x16x32_bf16 v[150:153], v[130:133], v[170:173], v[150:153]
	v_mfma_f32_16x16x32_bf16 v[146:149], v[154:157], v[170:173], 0
	v_mfma_f32_16x16x32_bf16 v[146:149], v[142:145], v[158:161], v[146:149]
	v_mfma_f32_16x16x32_bf16 v[122:125], v[142:145], v[174:177], 0
	v_mfma_f32_16x16x32_bf16 v[122:125], v[154:157], v[178:181], v[122:125]
	v_mfma_f32_16x16x32_bf16 v[126:129], v[130:133], v[178:181], 0
	v_mfma_f32_16x16x32_bf16 v[126:129], v[118:121], v[174:177], v[126:129]
	v_mfma_f32_16x16x32_bf16 v[134:137], v[94:97], v[174:177], 0
	v_mfma_f32_16x16x32_bf16 v[134:137], v[106:109], v[178:181], v[134:137]
	v_mfma_f32_16x16x32_bf16 v[138:141], v[82:85], v[178:181], 0
	v_mfma_f32_16x16x32_bf16 v[138:141], v[70:73], v[174:177], v[138:141]
	v_mfma_f32_16x16x32_bf16 v[114:117], v[70:73], v[182:185], 0
	v_mfma_f32_16x16x32_bf16 v[114:117], v[82:85], v[186:189], v[114:117]
	v_mfma_f32_16x16x32_bf16 v[110:113], v[106:109], v[186:189], 0
	v_mfma_f32_16x16x32_bf16 v[110:113], v[94:97], v[182:185], v[110:113]
	v_mfma_f32_16x16x32_bf16 v[102:105], v[118:121], v[182:185], 0
	v_mfma_f32_16x16x32_bf16 v[102:105], v[130:133], v[186:189], v[102:105]
	v_mfma_f32_16x16x32_bf16 v[98:101], v[154:157], v[186:189], 0
	v_mfma_f32_16x16x32_bf16 v[98:101], v[142:145], v[182:185], v[98:101]
	v_mfma_f32_16x16x32_bf16 v[74:77], v[142:145], v[210:213], 0
	v_mfma_f32_16x16x32_bf16 v[74:77], v[154:157], v[214:217], v[74:77]
	v_mfma_f32_16x16x32_bf16 v[78:81], v[130:133], v[214:217], 0
	v_mfma_f32_16x16x32_bf16 v[78:81], v[118:121], v[210:213], v[78:81]
	v_mfma_f32_16x16x32_bf16 v[86:89], v[94:97], v[210:213], 0
	v_mfma_f32_16x16x32_bf16 v[86:89], v[106:109], v[214:217], v[86:89]
	v_mfma_f32_16x16x32_bf16 v[90:93], v[82:85], v[214:217], 0
	v_mfma_f32_16x16x32_bf16 v[90:93], v[70:73], v[210:213], v[90:93]
	s_setprio 1
	s_barrier
	s_add_i32 s0, s0, s28
	s_mov_b32 m0, s0
	ds_read_b128 v[158:161], v237 offset:16384
	ds_read_b128 v[170:173], v237 offset:17408
	ds_read_b128 v[174:177], v237 offset:18432
	ds_read_b128 v[178:181], v237 offset:19456
	ds_read_b128 v[182:185], v237 offset:20480
	ds_read_b128 v[186:189], v237 offset:21504
	ds_read_b128 v[210:213], v237 offset:22528
	ds_read_b128 v[214:217], v237 offset:23552
	global_load_lds_dwordx4 v192, s[70:71]
	s_add_i32 m0, s0, 0x2000
	s_add_u32 s0, s70, 0x160000
	s_addc_u32 s1, s71, 0
	s_add_i32 s8, s18, s28
	global_load_lds_dwordx4 v190, s[70:71]
	s_mov_b32 m0, s8
	s_nop 0
	global_load_lds_dwordx4 v192, s[0:1]
	s_add_i32 m0, s8, 0x2000
	s_nop 0
	global_load_lds_dwordx4 v190, s[0:1]
	s_mov_b32 m0, s29
	s_nop 0
	global_load_lds_dwordx4 v192, s[76:77]
	s_mov_b32 m0, s31
	s_nop 0
	global_load_lds_dwordx4 v190, s[76:77]
	s_waitcnt vmcnt(8)
	s_waitcnt lgkmcnt(0)
	s_barrier
	s_setprio 0
	s_waitcnt lgkmcnt(0)
	v_mfma_f32_16x16x32_bf16 v[62:65], v[70:73], v[158:161], 0
	v_mfma_f32_16x16x32_bf16 v[62:65], v[82:85], v[170:173], v[62:65]
	v_mfma_f32_16x16x32_bf16 v[58:61], v[106:109], v[170:173], 0
	v_mfma_f32_16x16x32_bf16 v[58:61], v[94:97], v[158:161], v[58:61]
	v_mfma_f32_16x16x32_bf16 v[54:57], v[118:121], v[158:161], 0
	v_mfma_f32_16x16x32_bf16 v[54:57], v[130:133], v[170:173], v[54:57]
	v_mfma_f32_16x16x32_bf16 v[50:53], v[154:157], v[170:173], 0
	v_mfma_f32_16x16x32_bf16 v[50:53], v[142:145], v[158:161], v[50:53]
	v_mfma_f32_16x16x32_bf16 v[34:37], v[142:145], v[174:177], 0
	v_mfma_f32_16x16x32_bf16 v[34:37], v[154:157], v[178:181], v[34:37]
	v_mfma_f32_16x16x32_bf16 v[38:41], v[130:133], v[178:181], 0
	v_mfma_f32_16x16x32_bf16 v[38:41], v[118:121], v[174:177], v[38:41]
	v_mfma_f32_16x16x32_bf16 v[42:45], v[94:97], v[174:177], 0
	v_mfma_f32_16x16x32_bf16 v[42:45], v[106:109], v[178:181], v[42:45]
	v_mfma_f32_16x16x32_bf16 v[46:49], v[82:85], v[178:181], 0
	v_mfma_f32_16x16x32_bf16 v[46:49], v[70:73], v[174:177], v[46:49]
	v_mfma_f32_16x16x32_bf16 v[30:33], v[70:73], v[182:185], 0
	v_mfma_f32_16x16x32_bf16 v[30:33], v[82:85], v[186:189], v[30:33]
	v_mfma_f32_16x16x32_bf16 v[26:29], v[106:109], v[186:189], 0
	v_mfma_f32_16x16x32_bf16 v[26:29], v[94:97], v[182:185], v[26:29]
	v_mfma_f32_16x16x32_bf16 v[22:25], v[118:121], v[182:185], 0
	v_mfma_f32_16x16x32_bf16 v[22:25], v[130:133], v[186:189], v[22:25]
	v_mfma_f32_16x16x32_bf16 v[18:21], v[154:157], v[186:189], 0
	v_mfma_f32_16x16x32_bf16 v[18:21], v[142:145], v[182:185], v[18:21]
	v_mfma_f32_16x16x32_bf16 v[2:5], v[142:145], v[210:213], 0
	v_mfma_f32_16x16x32_bf16 v[2:5], v[154:157], v[214:217], v[2:5]
	v_mfma_f32_16x16x32_bf16 v[6:9], v[130:133], v[214:217], 0
	v_mfma_f32_16x16x32_bf16 v[6:9], v[118:121], v[210:213], v[6:9]
	v_mfma_f32_16x16x32_bf16 v[10:13], v[94:97], v[210:213], 0
	v_mfma_f32_16x16x32_bf16 v[10:13], v[106:109], v[214:217], v[10:13]
	v_mfma_f32_16x16x32_bf16 v[14:17], v[82:85], v[214:217], 0
	v_mfma_f32_16x16x32_bf16 v[14:17], v[70:73], v[210:213], v[14:17]
	s_setprio 1
	s_barrier
	s_add_i32 s8, 0, 0x18000
	s_add_i32 s9, 0, 0x1c000
	v_add_u32_e32 v106, s8, v1
	v_add_u32_e32 v154, s9, v1
	ds_read_b128 v[70:73], v106
	ds_read_b128 v[82:85], v106 offset:1024
	ds_read_b128 v[94:97], v106 offset:2048
	ds_read_b128 v[106:109], v106 offset:3072
	ds_read_b128 v[118:121], v154
	ds_read_b128 v[130:133], v154 offset:1024
	ds_read_b128 v[142:145], v154 offset:2048
	ds_read_b128 v[154:157], v154 offset:3072
	s_add_u32 s0, s76, 0x160000
	s_addc_u32 s1, s77, 0
	s_mov_b32 m0, s33
	ds_read_b128 v[158:161], v237 offset:32768
	ds_read_b128 v[170:173], v237 offset:33792
	ds_read_b128 v[174:177], v237 offset:34816
	ds_read_b128 v[178:181], v237 offset:35840
	ds_read_b128 v[182:185], v237 offset:36864
	ds_read_b128 v[186:189], v237 offset:37888
	ds_read_b128 v[210:213], v237 offset:38912
	ds_read_b128 v[214:217], v237 offset:39936
	global_load_lds_dwordx4 v192, s[0:1]
	s_mov_b32 m0, s43
	s_nop 0
	global_load_lds_dwordx4 v190, s[0:1]
	s_waitcnt vmcnt(8)
	s_waitcnt lgkmcnt(0)
	s_barrier
	s_setprio 0
	s_waitcnt lgkmcnt(0)
	v_mfma_f32_16x16x32_bf16 v[166:169], v[70:73], v[158:161], v[166:169]
	v_mfma_f32_16x16x32_bf16 v[166:169], v[82:85], v[170:173], v[166:169]
	v_mfma_f32_16x16x32_bf16 v[162:165], v[106:109], v[170:173], v[162:165]
	v_mfma_f32_16x16x32_bf16 v[162:165], v[94:97], v[158:161], v[162:165]
	v_mfma_f32_16x16x32_bf16 v[150:153], v[118:121], v[158:161], v[150:153]
	v_mfma_f32_16x16x32_bf16 v[150:153], v[130:133], v[170:173], v[150:153]
	v_mfma_f32_16x16x32_bf16 v[146:149], v[154:157], v[170:173], v[146:149]
	v_mfma_f32_16x16x32_bf16 v[146:149], v[142:145], v[158:161], v[146:149]
	v_mfma_f32_16x16x32_bf16 v[122:125], v[142:145], v[174:177], v[122:125]
	v_mfma_f32_16x16x32_bf16 v[122:125], v[154:157], v[178:181], v[122:125]
	v_mfma_f32_16x16x32_bf16 v[126:129], v[130:133], v[178:181], v[126:129]
	v_mfma_f32_16x16x32_bf16 v[126:129], v[118:121], v[174:177], v[126:129]
	v_mfma_f32_16x16x32_bf16 v[134:137], v[94:97], v[174:177], v[134:137]
	v_mfma_f32_16x16x32_bf16 v[134:137], v[106:109], v[178:181], v[134:137]
	v_mfma_f32_16x16x32_bf16 v[138:141], v[82:85], v[178:181], v[138:141]
	v_mfma_f32_16x16x32_bf16 v[138:141], v[70:73], v[174:177], v[138:141]
	v_mfma_f32_16x16x32_bf16 v[114:117], v[70:73], v[182:185], v[114:117]
	v_mfma_f32_16x16x32_bf16 v[114:117], v[82:85], v[186:189], v[114:117]
	v_mfma_f32_16x16x32_bf16 v[110:113], v[106:109], v[186:189], v[110:113]
	v_mfma_f32_16x16x32_bf16 v[110:113], v[94:97], v[182:185], v[110:113]
	v_mfma_f32_16x16x32_bf16 v[102:105], v[118:121], v[182:185], v[102:105]
	v_mfma_f32_16x16x32_bf16 v[102:105], v[130:133], v[186:189], v[102:105]
	v_mfma_f32_16x16x32_bf16 v[98:101], v[154:157], v[186:189], v[98:101]
	v_mfma_f32_16x16x32_bf16 v[98:101], v[142:145], v[182:185], v[98:101]
	v_mfma_f32_16x16x32_bf16 v[74:77], v[142:145], v[210:213], v[74:77]
	v_mfma_f32_16x16x32_bf16 v[74:77], v[154:157], v[214:217], v[74:77]
	v_mfma_f32_16x16x32_bf16 v[78:81], v[130:133], v[214:217], v[78:81]
	v_mfma_f32_16x16x32_bf16 v[78:81], v[118:121], v[210:213], v[78:81]
	v_mfma_f32_16x16x32_bf16 v[86:89], v[94:97], v[210:213], v[86:89]
	v_mfma_f32_16x16x32_bf16 v[86:89], v[106:109], v[214:217], v[86:89]
	v_mfma_f32_16x16x32_bf16 v[90:93], v[82:85], v[214:217], v[90:93]
	v_mfma_f32_16x16x32_bf16 v[90:93], v[70:73], v[210:213], v[90:93]
	s_setprio 1
	s_barrier
	s_add_u32 s98, s70, 0x80
	s_addc_u32 s99, s71, 0
	s_add_u32 s100, s76, 0x80
	s_addc_u32 s101, s77, 0
	s_add_i32 s0, s8, s28
	s_mov_b32 m0, s0
	ds_read_b128 v[158:161], v237 offset:49152
	ds_read_b128 v[170:173], v237 offset:50176
	ds_read_b128 v[174:177], v237 offset:51200
	ds_read_b128 v[178:181], v237 offset:52224
	ds_read_b128 v[182:185], v237 offset:53248
	ds_read_b128 v[186:189], v237 offset:54272
	ds_read_b128 v[210:213], v237 offset:55296
	ds_read_b128 v[214:217], v237 offset:56320
	global_load_lds_dwordx4 v192, s[98:99]
	s_add_i32 m0, s0, 0x2000
	s_add_u32 s0, s70, 0x160080
	s_addc_u32 s1, s71, 0
	s_add_i32 s8, s9, s28
	global_load_lds_dwordx4 v190, s[98:99]
	s_mov_b32 m0, s8
	s_nop 0
	global_load_lds_dwordx4 v192, s[0:1]
	s_add_i32 m0, s8, 0x2000
	s_nop 0
	global_load_lds_dwordx4 v190, s[0:1]
	s_mov_b32 m0, s68
	s_nop 0
	global_load_lds_dwordx4 v192, s[100:101]
	s_mov_b32 m0, s79
	s_nop 0
	global_load_lds_dwordx4 v190, s[100:101]
	s_waitcnt vmcnt(8)
	s_waitcnt lgkmcnt(0)
	s_barrier
	s_setprio 0
	s_waitcnt lgkmcnt(0)
	v_mfma_f32_16x16x32_bf16 v[62:65], v[70:73], v[158:161], v[62:65]
	v_mfma_f32_16x16x32_bf16 v[62:65], v[82:85], v[170:173], v[62:65]
	v_mfma_f32_16x16x32_bf16 v[58:61], v[106:109], v[170:173], v[58:61]
	v_mfma_f32_16x16x32_bf16 v[58:61], v[94:97], v[158:161], v[58:61]
	v_mfma_f32_16x16x32_bf16 v[54:57], v[118:121], v[158:161], v[54:57]
	v_mfma_f32_16x16x32_bf16 v[54:57], v[130:133], v[170:173], v[54:57]
	v_mfma_f32_16x16x32_bf16 v[50:53], v[154:157], v[170:173], v[50:53]
	v_mfma_f32_16x16x32_bf16 v[50:53], v[142:145], v[158:161], v[50:53]
	v_mfma_f32_16x16x32_bf16 v[34:37], v[142:145], v[174:177], v[34:37]
	v_mfma_f32_16x16x32_bf16 v[34:37], v[154:157], v[178:181], v[34:37]
	v_mfma_f32_16x16x32_bf16 v[38:41], v[130:133], v[178:181], v[38:41]
	v_mfma_f32_16x16x32_bf16 v[38:41], v[118:121], v[174:177], v[38:41]
	v_mfma_f32_16x16x32_bf16 v[42:45], v[94:97], v[174:177], v[42:45]
	v_mfma_f32_16x16x32_bf16 v[42:45], v[106:109], v[178:181], v[42:45]
	v_mfma_f32_16x16x32_bf16 v[46:49], v[82:85], v[178:181], v[46:49]
	v_mfma_f32_16x16x32_bf16 v[46:49], v[70:73], v[174:177], v[46:49]
	v_mfma_f32_16x16x32_bf16 v[30:33], v[70:73], v[182:185], v[30:33]
	v_mfma_f32_16x16x32_bf16 v[30:33], v[82:85], v[186:189], v[30:33]
	v_mfma_f32_16x16x32_bf16 v[26:29], v[106:109], v[186:189], v[26:29]
	v_mfma_f32_16x16x32_bf16 v[26:29], v[94:97], v[182:185], v[26:29]
	v_mfma_f32_16x16x32_bf16 v[22:25], v[118:121], v[182:185], v[22:25]
	v_mfma_f32_16x16x32_bf16 v[22:25], v[130:133], v[186:189], v[22:25]
	v_mfma_f32_16x16x32_bf16 v[18:21], v[154:157], v[186:189], v[18:21]
	v_mfma_f32_16x16x32_bf16 v[18:21], v[142:145], v[182:185], v[18:21]
	v_mfma_f32_16x16x32_bf16 v[2:5], v[142:145], v[210:213], v[2:5]
	v_mfma_f32_16x16x32_bf16 v[2:5], v[154:157], v[214:217], v[2:5]
	v_mfma_f32_16x16x32_bf16 v[6:9], v[130:133], v[214:217], v[6:9]
	v_mfma_f32_16x16x32_bf16 v[6:9], v[118:121], v[210:213], v[6:9]
	v_mfma_f32_16x16x32_bf16 v[10:13], v[94:97], v[210:213], v[10:13]
	v_mfma_f32_16x16x32_bf16 v[10:13], v[106:109], v[214:217], v[10:13]
	v_mfma_f32_16x16x32_bf16 v[14:17], v[82:85], v[214:217], v[14:17]
	v_mfma_f32_16x16x32_bf16 v[14:17], v[70:73], v[210:213], v[14:17]
	s_setprio 1
	s_barrier
	s_add_i32 s41, s41, 2
	s_add_u32 s7, s7, 0x100
	s_addc_u32 s23, s23, 0
	s_cmpk_gt_u32 s41, 0x55
	s_mov_b64 s[8:9], s[64:65]
	s_cbranch_scc1 .LBB0_648
	s_branch .LBB0_646
